# peeled last K-iteration without redundant clamped loads in all five pipelined GEMM loops
# speedup vs baseline: 1.0485x; 1.0106x over previous
; #define GLOAD(ra, rb, koff)                                                        \
;   {                                                                                \
;     _Pragma("unroll") for (int j = 0; j < 4; j++) ra[j] = *(const u32x4*)(pa + j * sa32 + (koff));   \
;     _Pragma("unroll") for (int j = 0; j < NB_; j++) rb[j] = *(const u32x4*)(pbv[j] + (koff));         \
;   }
; template <int NT, bool PRE> ...
;     ...
;   if (!PRE) {
;     GLOAD(ra0, rb0, 0);
;     GLOAD(ra1, rb1, 64);
;   }
;   __syncthreads();
;   for (int k0 = 0; k0 < K; k0 += 128) {
;     LSTORE(ra0, rb0, 0);
;     __syncthreads();
;     GLOAD(ra0, rb0, min(k0 + 128, K - 128));
;     __builtin_amdgcn_sched_barrier(0);
;     COMPUTE(0);
.LBB0_231:
	s_add_i32 s4, s1, 0x100
	s_min_u32 s4, s4, 0x380
	s_lshl_b32 s54, s4, 1
	ds_read_b128 v[164:167], v160
	ds_read_b128 v[210:213], v161 offset:16384
	ds_read_b128 v[214:217], v161 offset:18432
	ds_read_b128 v[218:221], v161 offset:20480
	ds_read_b128 v[222:225], v161 offset:22528
	ds_read_b128 v[198:201], v160 offset:2048
	ds_read_b128 v[202:205], v160 offset:4096
	ds_read_b128 v[206:209], v160 offset:6144
	ds_read_b128 v[226:229], v162
	ds_read_b128 v[230:233], v162 offset:2048
	ds_read_b128 v[234:237], v162 offset:4096
	ds_read_b128 v[238:241], v162 offset:6144
	ds_read_b128 v[242:245], v163 offset:16384
	v_lshl_add_u64 v[112:113], v[152:153], 0, s[54:55]
	v_add_co_u32_e32 v114, vcc, s33, v112
	v_lshl_add_u64 v[64:65], v[144:145], 0, s[54:55]
	s_nop 0
	v_addc_co_u32_e32 v115, vcc, 0, v113, vcc
	v_add_co_u32_e32 v116, vcc, s56, v112
	v_lshl_add_u64 v[66:67], v[146:147], 0, s[54:55]
	s_nop 0
	v_addc_co_u32_e32 v117, vcc, 0, v113, vcc
	v_add_co_u32_e32 v118, vcc, s57, v112
	v_lshl_add_u64 v[68:69], v[148:149], 0, s[54:55]
	v_lshl_add_u64 v[70:71], v[150:151], 0, s[54:55]
	v_addc_co_u32_e32 v119, vcc, 0, v113, vcc
	s_addk_i32 s1, 0x80
	s_setprio 1
	s_waitcnt lgkmcnt(11)
	v_mfma_f32_16x16x32_bf16 v[60:63], v[210:213], v[164:167], v[60:63]
	s_waitcnt lgkmcnt(10)
	v_mfma_f32_16x16x32_bf16 v[44:47], v[214:217], v[164:167], v[44:47]
	s_waitcnt lgkmcnt(9)
	v_mfma_f32_16x16x32_bf16 v[28:31], v[218:221], v[164:167], v[28:31]
	s_waitcnt lgkmcnt(8)
	v_mfma_f32_16x16x32_bf16 v[12:15], v[222:225], v[164:167], v[12:15]
	ds_read_b128 v[164:167], v163 offset:18432
	global_load_dwordx4 v[104:107], v[64:65], off
	s_nop 0
	global_load_dwordx4 v[84:87], v[66:67], off
	s_waitcnt lgkmcnt(8)
	v_mfma_f32_16x16x32_bf16 v[56:59], v[210:213], v[198:201], v[56:59]
	v_mfma_f32_16x16x32_bf16 v[40:43], v[214:217], v[198:201], v[40:43]
	v_mfma_f32_16x16x32_bf16 v[24:27], v[218:221], v[198:201], v[24:27]
	v_mfma_f32_16x16x32_bf16 v[8:11], v[222:225], v[198:201], v[8:11]
	ds_read_b128 v[198:201], v163 offset:20480
	global_load_dwordx4 v[64:67], v[68:69], off
	s_nop 0
	global_load_dwordx4 v[68:71], v[70:71], off
	s_waitcnt lgkmcnt(8)
	v_mfma_f32_16x16x32_bf16 v[52:55], v[210:213], v[202:205], v[52:55]
	v_mfma_f32_16x16x32_bf16 v[36:39], v[214:217], v[202:205], v[36:39]
	v_mfma_f32_16x16x32_bf16 v[20:23], v[218:221], v[202:205], v[20:23]
	v_mfma_f32_16x16x32_bf16 v[4:7], v[222:225], v[202:205], v[4:7]
	ds_read_b128 v[202:205], v163 offset:22528
	global_load_dwordx4 v[124:127], v[112:113], off
	s_nop 0
	global_load_dwordx4 v[120:123], v[114:115], off
	s_waitcnt lgkmcnt(8)
	v_mfma_f32_16x16x32_bf16 v[48:51], v[210:213], v[206:209], v[48:51]
	v_mfma_f32_16x16x32_bf16 v[32:35], v[214:217], v[206:209], v[32:35]
	v_mfma_f32_16x16x32_bf16 v[16:19], v[218:221], v[206:209], v[16:19]
	v_mfma_f32_16x16x32_bf16 v[0:3], v[222:225], v[206:209], v[0:3]
	global_load_dwordx4 v[112:115], v[116:117], off
	s_nop 0
	global_load_dwordx4 v[116:119], v[118:119], off
	s_waitcnt lgkmcnt(3)
	v_mfma_f32_16x16x32_bf16 v[60:63], v[242:245], v[226:229], v[60:63]
	v_mfma_f32_16x16x32_bf16 v[56:59], v[242:245], v[230:233], v[56:59]
	v_mfma_f32_16x16x32_bf16 v[52:55], v[242:245], v[234:237], v[52:55]
	v_mfma_f32_16x16x32_bf16 v[48:51], v[242:245], v[238:241], v[48:51]
	s_waitcnt vmcnt(14)
	ds_write_b128 v130, v[76:79] offset:49152
	ds_write_b128 v130, v[80:83] offset:53248
	s_waitcnt lgkmcnt(4)
	v_mfma_f32_16x16x32_bf16 v[44:47], v[164:167], v[226:229], v[44:47]
	v_mfma_f32_16x16x32_bf16 v[40:43], v[164:167], v[230:233], v[40:43]
	v_mfma_f32_16x16x32_bf16 v[36:39], v[164:167], v[234:237], v[36:39]
	v_mfma_f32_16x16x32_bf16 v[32:35], v[164:167], v[238:241], v[32:35]
	s_waitcnt vmcnt(11)
	ds_write_b128 v130, v[88:91] offset:57344
	ds_write_b128 v130, v[72:75] offset:32768
	s_waitcnt lgkmcnt(5)
	v_mfma_f32_16x16x32_bf16 v[28:31], v[198:201], v[226:229], v[28:31]
	v_mfma_f32_16x16x32_bf16 v[24:27], v[198:201], v[230:233], v[24:27]
	v_mfma_f32_16x16x32_bf16 v[20:23], v[198:201], v[234:237], v[20:23]
	v_mfma_f32_16x16x32_bf16 v[16:19], v[198:201], v[238:241], v[16:19]
	s_waitcnt vmcnt(9)
	ds_write_b128 v130, v[96:99] offset:36864
	ds_write_b128 v130, v[100:103] offset:40960
	s_waitcnt lgkmcnt(6)
	v_mfma_f32_16x16x32_bf16 v[12:15], v[202:205], v[226:229], v[12:15]
	v_mfma_f32_16x16x32_bf16 v[8:11], v[202:205], v[230:233], v[8:11]
	v_mfma_f32_16x16x32_bf16 v[4:7], v[202:205], v[234:237], v[4:7]
	v_mfma_f32_16x16x32_bf16 v[0:3], v[202:205], v[238:241], v[0:3]
	s_waitcnt vmcnt(8)
	ds_write_b128 v130, v[108:111] offset:45056
	ds_write_b128 v130, v[92:95] offset:61440
	s_setprio 0
	s_waitcnt lgkmcnt(0)
	s_barrier
; #define GLOAD(ra, rb, koff)                                                        \
;   {                                                                                \
;     _Pragma("unroll") for (int j = 0; j < 4; j++) ra[j] = *(const u32x4*)(pa + j * sa32 + (koff));   \
;     _Pragma("unroll") for (int j = 0; j < NB_; j++) rb[j] = *(const u32x4*)(pbv[j] + (koff));         \
;   }
; template <int NT, bool PRE> ...
;     ...
;   if (!PRE) {
;     GLOAD(ra0, rb0, 0);
;     GLOAD(ra1, rb1, 64);
;   }
;   __syncthreads();
;   for (int k0 = 0; k0 < K; k0 += 128) {
;     LSTORE(ra0, rb0, 0);
;     __syncthreads();
;     GLOAD(ra0, rb0, min(k0 + 128, K - 128));
;     __builtin_amdgcn_sched_barrier(0);
;     COMPUTE(0);
;     LSTORE(ra1, rb1, 1);
;     __syncthreads();
;     GLOAD(ra1, rb1, min(k0 + 192, K - 64));
;     __builtin_amdgcn_sched_barrier(0);
;     COMPUTE(1);
	s_min_u32 s4, s1, 0x300
	s_lshl_b32 s54, s4, 1
	ds_read_b128 v[164:167], v160 offset:32768
	ds_read_b128 v[210:213], v161 offset:49152
	ds_read_b128 v[214:217], v161 offset:51200
	ds_read_b128 v[218:221], v161 offset:53248
	ds_read_b128 v[222:225], v161 offset:55296
	ds_read_b128 v[198:201], v160 offset:34816
	ds_read_b128 v[202:205], v160 offset:36864
	ds_read_b128 v[206:209], v160 offset:38912
	ds_read_b128 v[226:229], v162 offset:32768
	ds_read_b128 v[230:233], v162 offset:34816
	ds_read_b128 v[234:237], v162 offset:36864
	ds_read_b128 v[238:241], v162 offset:38912
	ds_read_b128 v[242:245], v163 offset:49152
	v_lshl_add_u64 v[72:73], v[152:153], 0, s[54:55]
	v_add_co_u32_e32 v96, vcc, s33, v72
	v_lshl_add_u64 v[74:75], v[144:145], 0, s[54:55]
	s_nop 0
	v_addc_co_u32_e32 v97, vcc, 0, v73, vcc
	v_add_co_u32_e32 v100, vcc, s56, v72
	v_lshl_add_u64 v[80:81], v[146:147], 0, s[54:55]
	s_nop 0
	v_addc_co_u32_e32 v101, vcc, 0, v73, vcc
	v_add_co_u32_e32 v108, vcc, s57, v72
	v_lshl_add_u64 v[88:89], v[148:149], 0, s[54:55]
	v_lshl_add_u64 v[92:93], v[150:151], 0, s[54:55]
	v_addc_co_u32_e32 v109, vcc, 0, v73, vcc
	s_setprio 1
	s_waitcnt lgkmcnt(11)
	v_mfma_f32_16x16x32_bf16 v[60:63], v[210:213], v[164:167], v[60:63]
	s_waitcnt lgkmcnt(10)
	v_mfma_f32_16x16x32_bf16 v[44:47], v[214:217], v[164:167], v[44:47]
	s_waitcnt lgkmcnt(9)
	v_mfma_f32_16x16x32_bf16 v[28:31], v[218:221], v[164:167], v[28:31]
	s_waitcnt lgkmcnt(8)
	v_mfma_f32_16x16x32_bf16 v[12:15], v[222:225], v[164:167], v[12:15]
	ds_read_b128 v[164:167], v163 offset:51200
	global_load_dwordx4 v[76:79], v[74:75], off offset:384
	s_nop 0
	global_load_dwordx4 v[80:83], v[80:81], off offset:384
	s_waitcnt lgkmcnt(8)
	v_mfma_f32_16x16x32_bf16 v[56:59], v[210:213], v[198:201], v[56:59]
	v_mfma_f32_16x16x32_bf16 v[40:43], v[214:217], v[198:201], v[40:43]
	v_mfma_f32_16x16x32_bf16 v[24:27], v[218:221], v[198:201], v[24:27]
	v_mfma_f32_16x16x32_bf16 v[8:11], v[222:225], v[198:201], v[8:11]
	ds_read_b128 v[198:201], v163 offset:53248
	global_load_dwordx4 v[88:91], v[88:89], off offset:384
	s_nop 0
	global_load_dwordx4 v[92:95], v[92:93], off offset:384
	s_waitcnt lgkmcnt(8)
	v_mfma_f32_16x16x32_bf16 v[52:55], v[210:213], v[202:205], v[52:55]
	v_mfma_f32_16x16x32_bf16 v[36:39], v[214:217], v[202:205], v[36:39]
	v_mfma_f32_16x16x32_bf16 v[20:23], v[218:221], v[202:205], v[20:23]
	v_mfma_f32_16x16x32_bf16 v[4:7], v[222:225], v[202:205], v[4:7]
	ds_read_b128 v[202:205], v163 offset:55296
	global_load_dwordx4 v[72:75], v[72:73], off offset:384
	s_nop 0
	global_load_dwordx4 v[96:99], v[96:97], off offset:384
	s_waitcnt lgkmcnt(8)
	v_mfma_f32_16x16x32_bf16 v[48:51], v[210:213], v[206:209], v[48:51]
	v_mfma_f32_16x16x32_bf16 v[32:35], v[214:217], v[206:209], v[32:35]
	v_mfma_f32_16x16x32_bf16 v[16:19], v[218:221], v[206:209], v[16:19]
	v_mfma_f32_16x16x32_bf16 v[0:3], v[222:225], v[206:209], v[0:3]
	global_load_dwordx4 v[100:103], v[100:101], off offset:384
	s_nop 0
	global_load_dwordx4 v[108:111], v[108:109], off offset:384
	s_waitcnt lgkmcnt(3)
	v_mfma_f32_16x16x32_bf16 v[60:63], v[242:245], v[226:229], v[60:63]
	v_mfma_f32_16x16x32_bf16 v[56:59], v[242:245], v[230:233], v[56:59]
	v_mfma_f32_16x16x32_bf16 v[52:55], v[242:245], v[234:237], v[52:55]
	v_mfma_f32_16x16x32_bf16 v[48:51], v[242:245], v[238:241], v[48:51]
	s_waitcnt vmcnt(14)
	ds_write_b128 v130, v[104:107] offset:16384
	ds_write_b128 v130, v[84:87] offset:20480
	s_waitcnt lgkmcnt(4)
	v_mfma_f32_16x16x32_bf16 v[44:47], v[164:167], v[226:229], v[44:47]
	v_mfma_f32_16x16x32_bf16 v[40:43], v[164:167], v[230:233], v[40:43]
	v_mfma_f32_16x16x32_bf16 v[36:39], v[164:167], v[234:237], v[36:39]
	v_mfma_f32_16x16x32_bf16 v[32:35], v[164:167], v[238:241], v[32:35]
	s_waitcnt vmcnt(12)
	ds_write_b128 v130, v[64:67] offset:24576
	ds_write_b128 v130, v[68:71] offset:28672
	s_waitcnt lgkmcnt(5)
	v_mfma_f32_16x16x32_bf16 v[28:31], v[198:201], v[226:229], v[28:31]
	v_mfma_f32_16x16x32_bf16 v[24:27], v[198:201], v[230:233], v[24:27]
	v_mfma_f32_16x16x32_bf16 v[20:23], v[198:201], v[234:237], v[20:23]
	v_mfma_f32_16x16x32_bf16 v[16:19], v[198:201], v[238:241], v[16:19]
	s_waitcnt vmcnt(10)
	ds_write_b128 v130, v[124:127]
	ds_write_b128 v130, v[120:123] offset:4096
	s_waitcnt lgkmcnt(6)
	v_mfma_f32_16x16x32_bf16 v[12:15], v[202:205], v[226:229], v[12:15]
	v_mfma_f32_16x16x32_bf16 v[8:11], v[202:205], v[230:233], v[8:11]
	v_mfma_f32_16x16x32_bf16 v[4:7], v[202:205], v[234:237], v[4:7]
	v_mfma_f32_16x16x32_bf16 v[0:3], v[202:205], v[238:241], v[0:3]
	s_waitcnt vmcnt(8)
	ds_write_b128 v130, v[112:115] offset:8192
	ds_write_b128 v130, v[116:119] offset:12288
	s_setprio 0
	s_waitcnt lgkmcnt(0)
	s_barrier
	s_cmpk_lt_u32 s1, 0x300
	s_cbranch_scc1 .LBB0_231
; #define GLOAD(ra, rb, koff)                                                        \
;   {                                                                                \
;     _Pragma("unroll") for (int j = 0; j < 4; j++) ra[j] = *(const u32x4*)(pa + j * sa32 + (koff));   \
;     _Pragma("unroll") for (int j = 0; j < NB_; j++) rb[j] = *(const u32x4*)(pbv[j] + (koff));         \
;   }
; template <int NT, bool PRE> ...
;     ...
;   if (!PRE) {
;     GLOAD(ra0, rb0, 0);
;     GLOAD(ra1, rb1, 64);
;   }
;   __syncthreads();
;   for (int k0 = 0; k0 < K; k0 += 128) {
;     LSTORE(ra0, rb0, 0);
;     __syncthreads();
;     GLOAD(ra0, rb0, min(k0 + 128, K - 128));
;     __builtin_amdgcn_sched_barrier(0);
;     COMPUTE(0);
;     LSTORE(ra1, rb1, 1);
	ds_read_b128 v[164:167], v160
	ds_read_b128 v[210:213], v161 offset:16384
	ds_read_b128 v[214:217], v161 offset:18432
	ds_read_b128 v[218:221], v161 offset:20480
	ds_read_b128 v[222:225], v161 offset:22528
	ds_read_b128 v[198:201], v160 offset:2048
	ds_read_b128 v[202:205], v160 offset:4096
	ds_read_b128 v[206:209], v160 offset:6144
	ds_read_b128 v[226:229], v162
	ds_read_b128 v[230:233], v162 offset:2048
	ds_read_b128 v[234:237], v162 offset:4096
	ds_read_b128 v[238:241], v162 offset:6144
	ds_read_b128 v[242:245], v163 offset:16384
	s_addk_i32 s1, 0x80
	s_setprio 1
	s_waitcnt lgkmcnt(11)
	v_mfma_f32_16x16x32_bf16 v[60:63], v[210:213], v[164:167], v[60:63]
	s_waitcnt lgkmcnt(10)
	v_mfma_f32_16x16x32_bf16 v[44:47], v[214:217], v[164:167], v[44:47]
	s_waitcnt lgkmcnt(9)
	v_mfma_f32_16x16x32_bf16 v[28:31], v[218:221], v[164:167], v[28:31]
	s_waitcnt lgkmcnt(8)
	v_mfma_f32_16x16x32_bf16 v[12:15], v[222:225], v[164:167], v[12:15]
	ds_read_b128 v[164:167], v163 offset:18432
	s_waitcnt lgkmcnt(8)
	v_mfma_f32_16x16x32_bf16 v[56:59], v[210:213], v[198:201], v[56:59]
	v_mfma_f32_16x16x32_bf16 v[40:43], v[214:217], v[198:201], v[40:43]
	v_mfma_f32_16x16x32_bf16 v[24:27], v[218:221], v[198:201], v[24:27]
	v_mfma_f32_16x16x32_bf16 v[8:11], v[222:225], v[198:201], v[8:11]
	ds_read_b128 v[198:201], v163 offset:20480
	s_waitcnt lgkmcnt(8)
	v_mfma_f32_16x16x32_bf16 v[52:55], v[210:213], v[202:205], v[52:55]
	v_mfma_f32_16x16x32_bf16 v[36:39], v[214:217], v[202:205], v[36:39]
	v_mfma_f32_16x16x32_bf16 v[20:23], v[218:221], v[202:205], v[20:23]
	v_mfma_f32_16x16x32_bf16 v[4:7], v[222:225], v[202:205], v[4:7]
	ds_read_b128 v[202:205], v163 offset:22528
	s_waitcnt lgkmcnt(8)
	v_mfma_f32_16x16x32_bf16 v[48:51], v[210:213], v[206:209], v[48:51]
	v_mfma_f32_16x16x32_bf16 v[32:35], v[214:217], v[206:209], v[32:35]
	v_mfma_f32_16x16x32_bf16 v[16:19], v[218:221], v[206:209], v[16:19]
	v_mfma_f32_16x16x32_bf16 v[0:3], v[222:225], v[206:209], v[0:3]
	s_waitcnt lgkmcnt(3)
	v_mfma_f32_16x16x32_bf16 v[60:63], v[242:245], v[226:229], v[60:63]
	v_mfma_f32_16x16x32_bf16 v[56:59], v[242:245], v[230:233], v[56:59]
	v_mfma_f32_16x16x32_bf16 v[52:55], v[242:245], v[234:237], v[52:55]
	v_mfma_f32_16x16x32_bf16 v[48:51], v[242:245], v[238:241], v[48:51]
	s_waitcnt vmcnt(6)
	ds_write_b128 v130, v[76:79] offset:49152
	ds_write_b128 v130, v[80:83] offset:53248
	s_waitcnt lgkmcnt(4)
	v_mfma_f32_16x16x32_bf16 v[44:47], v[164:167], v[226:229], v[44:47]
	v_mfma_f32_16x16x32_bf16 v[40:43], v[164:167], v[230:233], v[40:43]
	v_mfma_f32_16x16x32_bf16 v[36:39], v[164:167], v[234:237], v[36:39]
	v_mfma_f32_16x16x32_bf16 v[32:35], v[164:167], v[238:241], v[32:35]
	s_waitcnt vmcnt(3)
	ds_write_b128 v130, v[88:91] offset:57344
	ds_write_b128 v130, v[72:75] offset:32768
	s_waitcnt lgkmcnt(5)
	v_mfma_f32_16x16x32_bf16 v[28:31], v[198:201], v[226:229], v[28:31]
	v_mfma_f32_16x16x32_bf16 v[24:27], v[198:201], v[230:233], v[24:27]
	v_mfma_f32_16x16x32_bf16 v[20:23], v[198:201], v[234:237], v[20:23]
	v_mfma_f32_16x16x32_bf16 v[16:19], v[198:201], v[238:241], v[16:19]
	s_waitcnt vmcnt(1)
	ds_write_b128 v130, v[96:99] offset:36864
	ds_write_b128 v130, v[100:103] offset:40960
	s_waitcnt lgkmcnt(6)
	v_mfma_f32_16x16x32_bf16 v[12:15], v[202:205], v[226:229], v[12:15]
	v_mfma_f32_16x16x32_bf16 v[8:11], v[202:205], v[230:233], v[8:11]
	v_mfma_f32_16x16x32_bf16 v[4:7], v[202:205], v[234:237], v[4:7]
	v_mfma_f32_16x16x32_bf16 v[0:3], v[202:205], v[238:241], v[0:3]
	s_waitcnt vmcnt(0)
	ds_write_b128 v130, v[108:111] offset:45056
	ds_write_b128 v130, v[92:95] offset:61440
	s_setprio 0
	s_waitcnt lgkmcnt(0)
	s_barrier
; template <int NT>
; __device__ __forceinline__ void zgemm_tile(char* ws, int m0, int n0, u16* sA, u16* sB, int tq) {
;     ...
; #pragma unroll
;     for (int ni = 0; ni < NT; ni++) {
;       int col = GEMM_COL(ni, NT * 32);
;       int cb = col & ~15;
; #pragma unroll
;       for (int mi = 0; mi < 4; mi++) {
;         int row = GEMM_ROW(mi);
;         int b = row >= NPB ? 1 : 0;
;         int n = row - b * NPB;
;         f32x4 v = acc[mi][ni];
;         if (cb < 2480) *(uint2*)(Z + (size_t)row * ZLD + col) = pack4(v);
	ds_read_b128 v[164:167], v160 offset:32768
	ds_read_b128 v[210:213], v161 offset:49152
	ds_read_b128 v[214:217], v161 offset:51200
	ds_read_b128 v[218:221], v161 offset:53248
	ds_read_b128 v[222:225], v161 offset:55296
	ds_read_b128 v[198:201], v160 offset:34816
	ds_read_b128 v[202:205], v160 offset:36864
	ds_read_b128 v[206:209], v160 offset:38912
	ds_read_b128 v[226:229], v162 offset:32768
	ds_read_b128 v[230:233], v162 offset:34816
	ds_read_b128 v[234:237], v162 offset:36864
	ds_read_b128 v[238:241], v162 offset:38912
	ds_read_b128 v[242:245], v163 offset:49152
	s_setprio 1
	s_waitcnt lgkmcnt(11)
	v_mfma_f32_16x16x32_bf16 v[60:63], v[210:213], v[164:167], v[60:63]
	s_waitcnt lgkmcnt(10)
	v_mfma_f32_16x16x32_bf16 v[44:47], v[214:217], v[164:167], v[44:47]
	s_waitcnt lgkmcnt(9)
	v_mfma_f32_16x16x32_bf16 v[28:31], v[218:221], v[164:167], v[28:31]
	s_waitcnt lgkmcnt(8)
	v_mfma_f32_16x16x32_bf16 v[12:15], v[222:225], v[164:167], v[12:15]
	ds_read_b128 v[164:167], v163 offset:51200
	s_waitcnt lgkmcnt(8)
	v_mfma_f32_16x16x32_bf16 v[56:59], v[210:213], v[198:201], v[56:59]
	v_mfma_f32_16x16x32_bf16 v[40:43], v[214:217], v[198:201], v[40:43]
	v_mfma_f32_16x16x32_bf16 v[24:27], v[218:221], v[198:201], v[24:27]
	v_mfma_f32_16x16x32_bf16 v[8:11], v[222:225], v[198:201], v[8:11]
	ds_read_b128 v[198:201], v163 offset:53248
	s_waitcnt lgkmcnt(8)
	v_mfma_f32_16x16x32_bf16 v[52:55], v[210:213], v[202:205], v[52:55]
	v_mfma_f32_16x16x32_bf16 v[36:39], v[214:217], v[202:205], v[36:39]
	v_mfma_f32_16x16x32_bf16 v[20:23], v[218:221], v[202:205], v[20:23]
	v_mfma_f32_16x16x32_bf16 v[4:7], v[222:225], v[202:205], v[4:7]
	ds_read_b128 v[202:205], v163 offset:55296
	s_waitcnt lgkmcnt(8)
	v_mfma_f32_16x16x32_bf16 v[48:51], v[210:213], v[206:209], v[48:51]
	v_mfma_f32_16x16x32_bf16 v[32:35], v[214:217], v[206:209], v[32:35]
	v_mfma_f32_16x16x32_bf16 v[16:19], v[218:221], v[206:209], v[16:19]
	v_mfma_f32_16x16x32_bf16 v[0:3], v[222:225], v[206:209], v[0:3]
	s_waitcnt lgkmcnt(3)
	v_mfma_f32_16x16x32_bf16 v[60:63], v[242:245], v[226:229], v[60:63]
	v_mfma_f32_16x16x32_bf16 v[56:59], v[242:245], v[230:233], v[56:59]
	v_mfma_f32_16x16x32_bf16 v[52:55], v[242:245], v[234:237], v[52:55]
	v_mfma_f32_16x16x32_bf16 v[48:51], v[242:245], v[238:241], v[48:51]
	s_waitcnt lgkmcnt(2)
	v_mfma_f32_16x16x32_bf16 v[44:47], v[164:167], v[226:229], v[44:47]
	v_mfma_f32_16x16x32_bf16 v[40:43], v[164:167], v[230:233], v[40:43]
	v_mfma_f32_16x16x32_bf16 v[36:39], v[164:167], v[234:237], v[36:39]
	v_mfma_f32_16x16x32_bf16 v[32:35], v[164:167], v[238:241], v[32:35]
	s_waitcnt lgkmcnt(1)
	v_mfma_f32_16x16x32_bf16 v[28:31], v[198:201], v[226:229], v[28:31]
	v_mfma_f32_16x16x32_bf16 v[24:27], v[198:201], v[230:233], v[24:27]
	v_mfma_f32_16x16x32_bf16 v[20:23], v[198:201], v[234:237], v[20:23]
	v_mfma_f32_16x16x32_bf16 v[16:19], v[198:201], v[238:241], v[16:19]
	s_waitcnt lgkmcnt(0)
	v_mfma_f32_16x16x32_bf16 v[12:15], v[202:205], v[226:229], v[12:15]
	v_mfma_f32_16x16x32_bf16 v[8:11], v[202:205], v[230:233], v[8:11]
	v_mfma_f32_16x16x32_bf16 v[4:7], v[202:205], v[234:237], v[4:7]
	v_mfma_f32_16x16x32_bf16 v[0:3], v[202:205], v[238:241], v[0:3]
	s_setprio 0
	s_waitcnt lgkmcnt(0)
	s_waitcnt vmcnt(13)
	v_or_b32_e32 v65, s0, v159
	v_or_b32_e32 v130, v65, v156
	v_or_b32_e32 v64, s3, v154
	s_movk_i32 s0, 0x9b0
	v_ashrrev_i32_e32 v67, 31, v130
	v_mov_b32_e32 v66, v130
	v_add_u32_e32 v64, v64, v158
	v_cmp_gt_i32_e64 s[50:51], s0, v65
	s_waitcnt vmcnt(12)
	v_lshl_add_u64 v[70:71], v[66:67], 1, s[18:19]
	s_and_saveexec_b64 s[0:1], s[50:51]
	s_cbranch_execz .LBB0_234
	v_cvt_pk_bf16_f32 v66, v60, v61
	v_cvt_pk_bf16_f32 v67, v62, v63
	v_mad_i64_i32 v[68:69], s[4:5], v64, s91, v[70:71]
	global_store_dwordx2 v[68:69], v[66:67], off

; #define GLOAD(ra, rb, koff)                                                        \
;   {                                                                                \
;     _Pragma("unroll") for (int j = 0; j < 4; j++) ra[j] = *(const u32x4*)(pa + j * sa32 + (koff));   \
;     _Pragma("unroll") for (int j = 0; j < NB_; j++) rb[j] = *(const u32x4*)(pbv[j] + (koff));         \
;   }
; template <int NT, bool PRE> ...
;     ...
;   const int wsw = ((tid & 7) ^ ((tid >> 4) & 7)) * 8;
;   const int rsw = (lane & 15) >> 1;
;     ...
;   if (!PRE) {
;     GLOAD(ra0, rb0, 0);
;     GLOAD(ra1, rb1, 64);
;   }
;   __syncthreads();
;   for (int k0 = 0; k0 < K; k0 += 128) {
;     LSTORE(ra0, rb0, 0);
;     __syncthreads();
;     GLOAD(ra0, rb0, min(k0 + 128, K - 128));
;     __builtin_amdgcn_sched_barrier(0);
;     COMPUTE(0);
;     LSTORE(ra1, rb1, 1);
;     __syncthreads();
;     GLOAD(ra1, rb1, min(k0 + 192, K - 64));
;     __builtin_amdgcn_sched_barrier(0);
;     COMPUTE(1);
;   }
.LBB0_1989:
	s_add_i32 s22, s21, 0x100
	s_min_u32 s22, s22, 0x380
	s_lshl_b32 s54, s22, 1
	ds_read_b128 v[158:161], v153
	ds_read_b128 v[206:209], v154 offset:16384
	ds_read_b128 v[210:213], v154 offset:18432
	ds_read_b128 v[214:217], v154 offset:20480
	ds_read_b128 v[218:221], v154 offset:22528
	ds_read_b128 v[162:165], v153 offset:2048
	ds_read_b128 v[198:201], v153 offset:4096
	ds_read_b128 v[202:205], v153 offset:6144
	ds_read_b128 v[222:225], v155
	ds_read_b128 v[226:229], v155 offset:2048
	ds_read_b128 v[230:233], v155 offset:4096
	ds_read_b128 v[234:237], v155 offset:6144
	ds_read_b128 v[238:241], v156 offset:16384
	ds_read_b128 v[242:245], v156 offset:18432
	v_lshl_add_u64 v[108:109], v[144:145], 0, s[54:55]
	v_add_co_u32_e32 v112, vcc, s33, v108
	v_lshl_add_u64 v[72:73], v[136:137], 0, s[54:55]
	s_nop 0
	v_addc_co_u32_e32 v113, vcc, 0, v109, vcc
	v_add_co_u32_e32 v114, vcc, s56, v108
	v_lshl_add_u64 v[74:75], v[138:139], 0, s[54:55]
	s_nop 0
	v_addc_co_u32_e32 v115, vcc, 0, v109, vcc
	v_add_co_u32_e32 v116, vcc, s57, v108
	v_lshl_add_u64 v[92:93], v[140:141], 0, s[54:55]
	v_lshl_add_u64 v[94:95], v[142:143], 0, s[54:55]
	v_addc_co_u32_e32 v117, vcc, 0, v109, vcc
	s_addk_i32 s21, 0x80
	s_setprio 1
	s_waitcnt lgkmcnt(12)
	v_mfma_f32_16x16x32_bf16 v[124:127], v[206:209], v[158:161], v[124:127]
	s_waitcnt lgkmcnt(11)
	v_mfma_f32_16x16x32_bf16 v[56:59], v[210:213], v[158:161], v[56:59]
	s_waitcnt lgkmcnt(10)
	v_mfma_f32_16x16x32_bf16 v[52:55], v[214:217], v[158:161], v[52:55]
	s_waitcnt lgkmcnt(9)
	v_mfma_f32_16x16x32_bf16 v[48:51], v[218:221], v[158:161], v[48:51]
	ds_read_b128 v[158:161], v156 offset:20480
	global_load_dwordx4 v[100:103], v[72:73], off
	s_nop 0
	global_load_dwordx4 v[84:87], v[74:75], off
	s_waitcnt lgkmcnt(9)
	v_mfma_f32_16x16x32_bf16 v[44:47], v[206:209], v[162:165], v[44:47]
	v_mfma_f32_16x16x32_bf16 v[40:43], v[210:213], v[162:165], v[40:43]
	v_mfma_f32_16x16x32_bf16 v[36:39], v[214:217], v[162:165], v[36:39]
	v_mfma_f32_16x16x32_bf16 v[32:35], v[218:221], v[162:165], v[32:35]
	ds_read_b128 v[162:165], v156 offset:22528
	global_load_dwordx4 v[72:75], v[92:93], off
	s_nop 0
	global_load_dwordx4 v[92:95], v[94:95], off
	s_waitcnt lgkmcnt(9)
	v_mfma_f32_16x16x32_bf16 v[28:31], v[206:209], v[198:201], v[28:31]
	v_mfma_f32_16x16x32_bf16 v[24:27], v[210:213], v[198:201], v[24:27]
	v_mfma_f32_16x16x32_bf16 v[20:23], v[214:217], v[198:201], v[20:23]
	v_mfma_f32_16x16x32_bf16 v[16:19], v[218:221], v[198:201], v[16:19]
	global_load_dwordx4 v[108:111], v[108:109], off
	s_nop 0
	global_load_dwordx4 v[120:123], v[112:113], off
	s_waitcnt lgkmcnt(8)
	v_mfma_f32_16x16x32_bf16 v[12:15], v[206:209], v[202:205], v[12:15]
	v_mfma_f32_16x16x32_bf16 v[8:11], v[210:213], v[202:205], v[8:11]
	v_mfma_f32_16x16x32_bf16 v[4:7], v[214:217], v[202:205], v[4:7]
	v_mfma_f32_16x16x32_bf16 v[0:3], v[218:221], v[202:205], v[0:3]
	global_load_dwordx4 v[112:115], v[114:115], off
	s_nop 0
	global_load_dwordx4 v[116:119], v[116:117], off
	s_waitcnt lgkmcnt(3)
	v_mfma_f32_16x16x32_bf16 v[124:127], v[238:241], v[222:225], v[124:127]
	v_mfma_f32_16x16x32_bf16 v[44:47], v[238:241], v[226:229], v[44:47]
	v_mfma_f32_16x16x32_bf16 v[28:31], v[238:241], v[230:233], v[28:31]
	v_mfma_f32_16x16x32_bf16 v[12:15], v[238:241], v[234:237], v[12:15]
	s_waitcnt vmcnt(14)
	ds_write_b128 v148, v[64:67] offset:49152
	ds_write_b128 v148, v[68:71] offset:53248
	s_waitcnt lgkmcnt(4)
	v_mfma_f32_16x16x32_bf16 v[56:59], v[242:245], v[222:225], v[56:59]
	v_mfma_f32_16x16x32_bf16 v[40:43], v[242:245], v[226:229], v[40:43]
	v_mfma_f32_16x16x32_bf16 v[24:27], v[242:245], v[230:233], v[24:27]
	v_mfma_f32_16x16x32_bf16 v[8:11], v[242:245], v[234:237], v[8:11]
	s_waitcnt vmcnt(11)
	ds_write_b128 v148, v[76:79] offset:57344
	ds_write_b128 v148, v[60:63] offset:32768
	s_waitcnt lgkmcnt(5)
	v_mfma_f32_16x16x32_bf16 v[52:55], v[158:161], v[222:225], v[52:55]
	v_mfma_f32_16x16x32_bf16 v[36:39], v[158:161], v[226:229], v[36:39]
	v_mfma_f32_16x16x32_bf16 v[20:23], v[158:161], v[230:233], v[20:23]
	v_mfma_f32_16x16x32_bf16 v[4:7], v[158:161], v[234:237], v[4:7]
	s_waitcnt vmcnt(9)
	ds_write_b128 v148, v[80:83] offset:36864
	ds_write_b128 v148, v[96:99] offset:40960
	s_waitcnt lgkmcnt(6)
	v_mfma_f32_16x16x32_bf16 v[48:51], v[162:165], v[222:225], v[48:51]
	v_mfma_f32_16x16x32_bf16 v[32:35], v[162:165], v[226:229], v[32:35]
	v_mfma_f32_16x16x32_bf16 v[16:19], v[162:165], v[230:233], v[16:19]
	v_mfma_f32_16x16x32_bf16 v[0:3], v[162:165], v[234:237], v[0:3]
	s_waitcnt vmcnt(8)
	ds_write_b128 v148, v[104:107] offset:45056
	ds_write_b128 v148, v[88:91] offset:61440
	s_setprio 0
	s_waitcnt lgkmcnt(0)
	s_barrier
; #define GLOAD(ra, rb, koff)                                                        \
;   {                                                                                \
;     _Pragma("unroll") for (int j = 0; j < 4; j++) ra[j] = *(const u32x4*)(pa + j * sa32 + (koff));   \
;     _Pragma("unroll") for (int j = 0; j < NB_; j++) rb[j] = *(const u32x4*)(pbv[j] + (koff));         \
;   }
; template <int NT, bool PRE> ...
;     ...
;   const int wsw = ((tid & 7) ^ ((tid >> 4) & 7)) * 8;
;   const int rsw = (lane & 15) >> 1;
;     ...
;   if (!PRE) {
;     GLOAD(ra0, rb0, 0);
;     GLOAD(ra1, rb1, 64);
;   }
;   __syncthreads();
;   for (int k0 = 0; k0 < K; k0 += 128) {
;     LSTORE(ra0, rb0, 0);
;     __syncthreads();
;     GLOAD(ra0, rb0, min(k0 + 128, K - 128));
;     __builtin_amdgcn_sched_barrier(0);
;     COMPUTE(0);
;     LSTORE(ra1, rb1, 1);
;     __syncthreads();
;     GLOAD(ra1, rb1, min(k0 + 192, K - 64));
;     __builtin_amdgcn_sched_barrier(0);
;     COMPUTE(1);
;   }
	s_min_u32 s22, s21, 0x300
	s_lshl_b32 s54, s22, 1
	ds_read_b128 v[158:161], v153 offset:32768
	ds_read_b128 v[206:209], v154 offset:49152
	ds_read_b128 v[210:213], v154 offset:51200
	ds_read_b128 v[214:217], v154 offset:53248
	ds_read_b128 v[218:221], v154 offset:55296
	ds_read_b128 v[162:165], v153 offset:34816
	ds_read_b128 v[198:201], v153 offset:36864
	ds_read_b128 v[202:205], v153 offset:38912
	ds_read_b128 v[222:225], v155 offset:32768
	ds_read_b128 v[226:229], v155 offset:34816
	ds_read_b128 v[230:233], v155 offset:36864
	ds_read_b128 v[234:237], v155 offset:38912
	ds_read_b128 v[238:241], v156 offset:49152
	ds_read_b128 v[242:245], v156 offset:51200
	v_lshl_add_u64 v[60:61], v[144:145], 0, s[54:55]
	v_add_co_u32_e32 v82, vcc, s33, v60
	v_lshl_add_u64 v[62:63], v[136:137], 0, s[54:55]
	s_nop 0
	v_addc_co_u32_e32 v83, vcc, 0, v61, vcc
	v_add_co_u32_e32 v96, vcc, s56, v60
	v_lshl_add_u64 v[68:69], v[138:139], 0, s[54:55]
	s_nop 0
	v_addc_co_u32_e32 v97, vcc, 0, v61, vcc
	v_add_co_u32_e32 v104, vcc, s57, v60
	v_lshl_add_u64 v[76:77], v[140:141], 0, s[54:55]
	v_lshl_add_u64 v[80:81], v[142:143], 0, s[54:55]
	v_addc_co_u32_e32 v105, vcc, 0, v61, vcc
	s_setprio 1
	s_waitcnt lgkmcnt(12)
	v_mfma_f32_16x16x32_bf16 v[124:127], v[206:209], v[158:161], v[124:127]
	s_waitcnt lgkmcnt(11)
	v_mfma_f32_16x16x32_bf16 v[56:59], v[210:213], v[158:161], v[56:59]
	s_waitcnt lgkmcnt(10)
	v_mfma_f32_16x16x32_bf16 v[52:55], v[214:217], v[158:161], v[52:55]
	s_waitcnt lgkmcnt(9)
	v_mfma_f32_16x16x32_bf16 v[48:51], v[218:221], v[158:161], v[48:51]
	ds_read_b128 v[158:161], v156 offset:53248
	global_load_dwordx4 v[64:67], v[62:63], off offset:384
	s_nop 0
	global_load_dwordx4 v[68:71], v[68:69], off offset:384
	s_waitcnt lgkmcnt(9)
	v_mfma_f32_16x16x32_bf16 v[44:47], v[206:209], v[162:165], v[44:47]
	v_mfma_f32_16x16x32_bf16 v[40:43], v[210:213], v[162:165], v[40:43]
	v_mfma_f32_16x16x32_bf16 v[36:39], v[214:217], v[162:165], v[36:39]
	v_mfma_f32_16x16x32_bf16 v[32:35], v[218:221], v[162:165], v[32:35]
	ds_read_b128 v[162:165], v156 offset:55296
	global_load_dwordx4 v[76:79], v[76:77], off offset:384
	s_nop 0
	global_load_dwordx4 v[88:91], v[80:81], off offset:384
	s_waitcnt lgkmcnt(9)
	v_mfma_f32_16x16x32_bf16 v[28:31], v[206:209], v[198:201], v[28:31]
	v_mfma_f32_16x16x32_bf16 v[24:27], v[210:213], v[198:201], v[24:27]
	v_mfma_f32_16x16x32_bf16 v[20:23], v[214:217], v[198:201], v[20:23]
	v_mfma_f32_16x16x32_bf16 v[16:19], v[218:221], v[198:201], v[16:19]
	global_load_dwordx4 v[60:63], v[60:61], off offset:384
	s_nop 0
	global_load_dwordx4 v[80:83], v[82:83], off offset:384
	s_waitcnt lgkmcnt(8)
	v_mfma_f32_16x16x32_bf16 v[12:15], v[206:209], v[202:205], v[12:15]
	v_mfma_f32_16x16x32_bf16 v[8:11], v[210:213], v[202:205], v[8:11]
	v_mfma_f32_16x16x32_bf16 v[4:7], v[214:217], v[202:205], v[4:7]
	v_mfma_f32_16x16x32_bf16 v[0:3], v[218:221], v[202:205], v[0:3]
	global_load_dwordx4 v[96:99], v[96:97], off offset:384
	s_nop 0
	global_load_dwordx4 v[104:107], v[104:105], off offset:384
	s_waitcnt lgkmcnt(3)
	v_mfma_f32_16x16x32_bf16 v[124:127], v[238:241], v[222:225], v[124:127]
	v_mfma_f32_16x16x32_bf16 v[44:47], v[238:241], v[226:229], v[44:47]
	v_mfma_f32_16x16x32_bf16 v[28:31], v[238:241], v[230:233], v[28:31]
	v_mfma_f32_16x16x32_bf16 v[12:15], v[238:241], v[234:237], v[12:15]
	s_waitcnt vmcnt(14)
	ds_write_b128 v148, v[100:103] offset:16384
	ds_write_b128 v148, v[84:87] offset:20480
	s_waitcnt lgkmcnt(4)
	v_mfma_f32_16x16x32_bf16 v[56:59], v[242:245], v[222:225], v[56:59]
	v_mfma_f32_16x16x32_bf16 v[40:43], v[242:245], v[226:229], v[40:43]
	v_mfma_f32_16x16x32_bf16 v[24:27], v[242:245], v[230:233], v[24:27]
	v_mfma_f32_16x16x32_bf16 v[8:11], v[242:245], v[234:237], v[8:11]
	s_waitcnt vmcnt(12)
	ds_write_b128 v148, v[72:75] offset:24576
	ds_write_b128 v148, v[92:95] offset:28672
	s_waitcnt lgkmcnt(5)
	v_mfma_f32_16x16x32_bf16 v[52:55], v[158:161], v[222:225], v[52:55]
	v_mfma_f32_16x16x32_bf16 v[36:39], v[158:161], v[226:229], v[36:39]
	v_mfma_f32_16x16x32_bf16 v[20:23], v[158:161], v[230:233], v[20:23]
	v_mfma_f32_16x16x32_bf16 v[4:7], v[158:161], v[234:237], v[4:7]
	s_waitcnt vmcnt(10)
	ds_write_b128 v148, v[108:111]
	ds_write_b128 v148, v[120:123] offset:4096
	s_waitcnt lgkmcnt(6)
	v_mfma_f32_16x16x32_bf16 v[48:51], v[162:165], v[222:225], v[48:51]
	v_mfma_f32_16x16x32_bf16 v[32:35], v[162:165], v[226:229], v[32:35]
	v_mfma_f32_16x16x32_bf16 v[16:19], v[162:165], v[230:233], v[16:19]
	v_mfma_f32_16x16x32_bf16 v[0:3], v[162:165], v[234:237], v[0:3]
	s_waitcnt vmcnt(8)
	ds_write_b128 v148, v[112:115] offset:8192
	ds_write_b128 v148, v[116:119] offset:12288
	s_setprio 0
	s_waitcnt lgkmcnt(0)
	s_barrier
	s_cmpk_lt_u32 s21, 0x300
	s_cbranch_scc1 .LBB0_1989
; #define GLOAD(ra, rb, koff)                                                        \
;   {                                                                                \
;     _Pragma("unroll") for (int j = 0; j < 4; j++) ra[j] = *(const u32x4*)(pa + j * sa32 + (koff));   \
;     _Pragma("unroll") for (int j = 0; j < NB_; j++) rb[j] = *(const u32x4*)(pbv[j] + (koff));         \
;   }
; template <int NT, bool PRE> ...
;     ...
;   if (!PRE) {
;     GLOAD(ra0, rb0, 0);
;     GLOAD(ra1, rb1, 64);
;   }
;   __syncthreads();
;   for (int k0 = 0; k0 < K; k0 += 128) {
;     LSTORE(ra0, rb0, 0);
;     __syncthreads();
;     GLOAD(ra0, rb0, min(k0 + 128, K - 128));
;     __builtin_amdgcn_sched_barrier(0);
;     COMPUTE(0);
;     LSTORE(ra1, rb1, 1);
;     __syncthreads();
;     GLOAD(ra1, rb1, min(k0 + 192, K - 64));
;     __builtin_amdgcn_sched_barrier(0);
;     COMPUTE(1);
;   }
	ds_read_b128 v[158:161], v153
	ds_read_b128 v[206:209], v154 offset:16384
	ds_read_b128 v[210:213], v154 offset:18432
	ds_read_b128 v[214:217], v154 offset:20480
	ds_read_b128 v[218:221], v154 offset:22528
	ds_read_b128 v[162:165], v153 offset:2048
	ds_read_b128 v[198:201], v153 offset:4096
	ds_read_b128 v[202:205], v153 offset:6144
	ds_read_b128 v[222:225], v155
	ds_read_b128 v[226:229], v155 offset:2048
	ds_read_b128 v[230:233], v155 offset:4096
	ds_read_b128 v[234:237], v155 offset:6144
	ds_read_b128 v[238:241], v156 offset:16384
	ds_read_b128 v[242:245], v156 offset:18432
	s_addk_i32 s21, 0x80
	s_setprio 1
	s_waitcnt lgkmcnt(12)
	v_mfma_f32_16x16x32_bf16 v[124:127], v[206:209], v[158:161], v[124:127]
	s_waitcnt lgkmcnt(11)
	v_mfma_f32_16x16x32_bf16 v[56:59], v[210:213], v[158:161], v[56:59]
	s_waitcnt lgkmcnt(10)
	v_mfma_f32_16x16x32_bf16 v[52:55], v[214:217], v[158:161], v[52:55]
	s_waitcnt lgkmcnt(9)
	v_mfma_f32_16x16x32_bf16 v[48:51], v[218:221], v[158:161], v[48:51]
	ds_read_b128 v[158:161], v156 offset:20480
	s_waitcnt lgkmcnt(9)
	v_mfma_f32_16x16x32_bf16 v[44:47], v[206:209], v[162:165], v[44:47]
	v_mfma_f32_16x16x32_bf16 v[40:43], v[210:213], v[162:165], v[40:43]
	v_mfma_f32_16x16x32_bf16 v[36:39], v[214:217], v[162:165], v[36:39]
	v_mfma_f32_16x16x32_bf16 v[32:35], v[218:221], v[162:165], v[32:35]
	ds_read_b128 v[162:165], v156 offset:22528
	s_waitcnt lgkmcnt(9)
	v_mfma_f32_16x16x32_bf16 v[28:31], v[206:209], v[198:201], v[28:31]
	v_mfma_f32_16x16x32_bf16 v[24:27], v[210:213], v[198:201], v[24:27]
	v_mfma_f32_16x16x32_bf16 v[20:23], v[214:217], v[198:201], v[20:23]
	v_mfma_f32_16x16x32_bf16 v[16:19], v[218:221], v[198:201], v[16:19]
	s_waitcnt lgkmcnt(8)
	v_mfma_f32_16x16x32_bf16 v[12:15], v[206:209], v[202:205], v[12:15]
	v_mfma_f32_16x16x32_bf16 v[8:11], v[210:213], v[202:205], v[8:11]
	v_mfma_f32_16x16x32_bf16 v[4:7], v[214:217], v[202:205], v[4:7]
	v_mfma_f32_16x16x32_bf16 v[0:3], v[218:221], v[202:205], v[0:3]
	s_waitcnt lgkmcnt(3)
	v_mfma_f32_16x16x32_bf16 v[124:127], v[238:241], v[222:225], v[124:127]
	v_mfma_f32_16x16x32_bf16 v[44:47], v[238:241], v[226:229], v[44:47]
	v_mfma_f32_16x16x32_bf16 v[28:31], v[238:241], v[230:233], v[28:31]
	v_mfma_f32_16x16x32_bf16 v[12:15], v[238:241], v[234:237], v[12:15]
	s_waitcnt vmcnt(6)
	ds_write_b128 v148, v[64:67] offset:49152
	ds_write_b128 v148, v[68:71] offset:53248
	s_waitcnt lgkmcnt(4)
	v_mfma_f32_16x16x32_bf16 v[56:59], v[242:245], v[222:225], v[56:59]
	v_mfma_f32_16x16x32_bf16 v[40:43], v[242:245], v[226:229], v[40:43]
	v_mfma_f32_16x16x32_bf16 v[24:27], v[242:245], v[230:233], v[24:27]
	v_mfma_f32_16x16x32_bf16 v[8:11], v[242:245], v[234:237], v[8:11]
	s_waitcnt vmcnt(3)
	ds_write_b128 v148, v[76:79] offset:57344
	ds_write_b128 v148, v[60:63] offset:32768
	s_waitcnt lgkmcnt(5)
	v_mfma_f32_16x16x32_bf16 v[52:55], v[158:161], v[222:225], v[52:55]
	v_mfma_f32_16x16x32_bf16 v[36:39], v[158:161], v[226:229], v[36:39]
	v_mfma_f32_16x16x32_bf16 v[20:23], v[158:161], v[230:233], v[20:23]
	v_mfma_f32_16x16x32_bf16 v[4:7], v[158:161], v[234:237], v[4:7]
	s_waitcnt vmcnt(1)
	ds_write_b128 v148, v[80:83] offset:36864
	ds_write_b128 v148, v[96:99] offset:40960
	s_waitcnt lgkmcnt(6)
	v_mfma_f32_16x16x32_bf16 v[48:51], v[162:165], v[222:225], v[48:51]
	v_mfma_f32_16x16x32_bf16 v[32:35], v[162:165], v[226:229], v[32:35]
	v_mfma_f32_16x16x32_bf16 v[16:19], v[162:165], v[230:233], v[16:19]
	v_mfma_f32_16x16x32_bf16 v[0:3], v[162:165], v[234:237], v[0:3]
	s_waitcnt vmcnt(0)
	ds_write_b128 v148, v[104:107] offset:45056
	ds_write_b128 v148, v[88:91] offset:61440
	s_setprio 0
	s_waitcnt lgkmcnt(0)
	s_barrier
	ds_read_b128 v[158:161], v153 offset:32768
	ds_read_b128 v[206:209], v154 offset:49152
	ds_read_b128 v[210:213], v154 offset:51200
	ds_read_b128 v[214:217], v154 offset:53248
	ds_read_b128 v[218:221], v154 offset:55296
	ds_read_b128 v[162:165], v153 offset:34816
	ds_read_b128 v[198:201], v153 offset:36864
	ds_read_b128 v[202:205], v153 offset:38912
	ds_read_b128 v[222:225], v155 offset:32768
	ds_read_b128 v[226:229], v155 offset:34816
	ds_read_b128 v[230:233], v155 offset:36864
	ds_read_b128 v[234:237], v155 offset:38912
	ds_read_b128 v[238:241], v156 offset:49152
	ds_read_b128 v[242:245], v156 offset:51200
	s_setprio 1
	s_waitcnt lgkmcnt(12)
	v_mfma_f32_16x16x32_bf16 v[124:127], v[206:209], v[158:161], v[124:127]
	s_waitcnt lgkmcnt(11)
	v_mfma_f32_16x16x32_bf16 v[56:59], v[210:213], v[158:161], v[56:59]
	s_waitcnt lgkmcnt(10)
	v_mfma_f32_16x16x32_bf16 v[52:55], v[214:217], v[158:161], v[52:55]
	s_waitcnt lgkmcnt(9)
	v_mfma_f32_16x16x32_bf16 v[48:51], v[218:221], v[158:161], v[48:51]
	ds_read_b128 v[158:161], v156 offset:53248
	s_waitcnt lgkmcnt(9)
	v_mfma_f32_16x16x32_bf16 v[44:47], v[206:209], v[162:165], v[44:47]
	v_mfma_f32_16x16x32_bf16 v[40:43], v[210:213], v[162:165], v[40:43]
	v_mfma_f32_16x16x32_bf16 v[36:39], v[214:217], v[162:165], v[36:39]
	v_mfma_f32_16x16x32_bf16 v[32:35], v[218:221], v[162:165], v[32:35]
	ds_read_b128 v[162:165], v156 offset:55296
	s_waitcnt lgkmcnt(9)
	v_mfma_f32_16x16x32_bf16 v[28:31], v[206:209], v[198:201], v[28:31]
	v_mfma_f32_16x16x32_bf16 v[24:27], v[210:213], v[198:201], v[24:27]
	v_mfma_f32_16x16x32_bf16 v[20:23], v[214:217], v[198:201], v[20:23]
	v_mfma_f32_16x16x32_bf16 v[16:19], v[218:221], v[198:201], v[16:19]
	s_waitcnt lgkmcnt(8)
	v_mfma_f32_16x16x32_bf16 v[12:15], v[206:209], v[202:205], v[12:15]
	v_mfma_f32_16x16x32_bf16 v[8:11], v[210:213], v[202:205], v[8:11]
	v_mfma_f32_16x16x32_bf16 v[4:7], v[214:217], v[202:205], v[4:7]
	v_mfma_f32_16x16x32_bf16 v[0:3], v[218:221], v[202:205], v[0:3]
	s_waitcnt lgkmcnt(3)
; __device__ __forceinline__ float sigmoidf_(float x) { return 1.f / (1.f + __expf(-x)); }
; __device__ __forceinline__ void phase_merge(const Params& P, u16* sA, u16* sB) {
;     ...
; #pragma unroll
;       for (int mi = 0; mi < 4; mi++)
; #pragma unroll
;         for (int ni = 0; ni < 4; ni++) {
;           f32x4 g = ag[mi][ni];
;           gp[mi][ni] = u32x2{pk2bf(sigmoidf_(g[0]), sigmoidf_(g[1])), pk2bf(sigmoidf_(g[2]), sigmoidf_(g[3]))};
;         }
	v_mfma_f32_16x16x32_bf16 v[124:127], v[238:241], v[222:225], v[124:127]
	v_mfma_f32_16x16x32_bf16 v[44:47], v[238:241], v[226:229], v[44:47]
	v_mfma_f32_16x16x32_bf16 v[28:31], v[238:241], v[230:233], v[28:31]
	v_mfma_f32_16x16x32_bf16 v[12:15], v[238:241], v[234:237], v[12:15]
	s_waitcnt lgkmcnt(2)
	v_mfma_f32_16x16x32_bf16 v[56:59], v[242:245], v[222:225], v[56:59]
	v_mfma_f32_16x16x32_bf16 v[40:43], v[242:245], v[226:229], v[40:43]
	v_mfma_f32_16x16x32_bf16 v[24:27], v[242:245], v[230:233], v[24:27]
	v_mfma_f32_16x16x32_bf16 v[8:11], v[242:245], v[234:237], v[8:11]
	s_waitcnt lgkmcnt(1)
	v_mfma_f32_16x16x32_bf16 v[52:55], v[158:161], v[222:225], v[52:55]
	v_mfma_f32_16x16x32_bf16 v[36:39], v[158:161], v[226:229], v[36:39]
	v_mfma_f32_16x16x32_bf16 v[20:23], v[158:161], v[230:233], v[20:23]
	v_mfma_f32_16x16x32_bf16 v[4:7], v[158:161], v[234:237], v[4:7]
	s_waitcnt lgkmcnt(0)
	v_mfma_f32_16x16x32_bf16 v[48:51], v[162:165], v[222:225], v[48:51]
	v_mfma_f32_16x16x32_bf16 v[32:35], v[162:165], v[226:229], v[32:35]
	v_mfma_f32_16x16x32_bf16 v[16:19], v[162:165], v[230:233], v[16:19]
	v_mfma_f32_16x16x32_bf16 v[0:3], v[162:165], v[234:237], v[0:3]
	s_setprio 0
	s_waitcnt lgkmcnt(0)
	s_waitcnt vmcnt(3)
	v_mul_f32_e32 v60, 0xbfb8aa3b, v124
	v_mul_f32_e32 v61, 0xbfb8aa3b, v125
	v_exp_f32_e32 v60, v60
	v_exp_f32_e32 v61, v61
	v_mul_f32_e32 v56, 0xbfb8aa3b, v56
	v_mul_f32_e32 v57, 0xbfb8aa3b, v57
	v_exp_f32_e32 v56, v56
	v_pk_add_f32 v[60:61], v[60:61], 1.0 op_sel_hi:[1,0]
	v_exp_f32_e32 v57, v57
	v_div_scale_f32 v62, s[22:23], v61, v61, 1.0
	v_rcp_f32_e32 v63, v62
	v_pk_add_f32 v[56:57], v[56:57], 1.0 op_sel_hi:[1,0]
	v_mul_f32_e32 v52, 0xbfb8aa3b, v52
	v_mul_f32_e32 v53, 0xbfb8aa3b, v53
	v_fma_f32 v64, -v62, v63, 1.0
	v_fmac_f32_e32 v63, v64, v63
	v_div_scale_f32 v64, vcc, 1.0, v61, 1.0
	v_mul_f32_e32 v65, v64, v63
	v_fma_f32 v66, -v62, v65, v64
	v_fmac_f32_e32 v65, v66, v63
	v_fma_f32 v62, -v62, v65, v64
	v_div_fmas_f32 v62, v62, v63, v65
	v_div_fixup_f32 v61, v62, v61, 1.0
	v_div_scale_f32 v62, s[22:23], v60, v60, 1.0
	v_rcp_f32_e32 v63, v62
	v_exp_f32_e32 v52, v52
	v_exp_f32_e32 v53, v53
	v_mul_f32_e32 v48, 0xbfb8aa3b, v48
	v_fma_f32 v64, -v62, v63, 1.0
	v_fmac_f32_e32 v63, v64, v63
	v_div_scale_f32 v64, vcc, 1.0, v60, 1.0
	v_mul_f32_e32 v65, v64, v63
	v_fma_f32 v66, -v62, v65, v64
	v_fmac_f32_e32 v65, v66, v63
	v_fma_f32 v62, -v62, v65, v64
	v_div_fmas_f32 v62, v62, v63, v65
	v_div_fixup_f32 v60, v62, v60, 1.0
	v_cvt_pk_bf16_f32 v60, v60, v61
	v_mul_f32_e32 v61, 0xbfb8aa3b, v126
	v_exp_f32_e32 v62, v61
	v_mul_f32_e32 v61, 0xbfb8aa3b, v127
	v_exp_f32_e32 v63, v61
	v_pk_add_f32 v[52:53], v[52:53], 1.0 op_sel_hi:[1,0]
	v_mul_f32_e32 v49, 0xbfb8aa3b, v49
	v_exp_f32_e32 v48, v48
	v_pk_add_f32 v[62:63], v[62:63], 1.0 op_sel_hi:[1,0]
	v_exp_f32_e32 v49, v49
	v_div_scale_f32 v61, s[22:23], v63, v63, 1.0
	v_rcp_f32_e32 v64, v61
	v_pk_add_f32 v[48:49], v[48:49], 1.0 op_sel_hi:[1,0]
	v_mul_f32_e32 v44, 0xbfb8aa3b, v44
	v_mul_f32_e32 v45, 0xbfb8aa3b, v45
	v_fma_f32 v65, -v61, v64, 1.0
	v_fmac_f32_e32 v64, v65, v64
	v_div_scale_f32 v65, vcc, 1.0, v63, 1.0
	v_mul_f32_e32 v66, v65, v64
	v_fma_f32 v67, -v61, v66, v65
	v_fmac_f32_e32 v66, v67, v64
	v_fma_f32 v61, -v61, v66, v65
	v_div_fmas_f32 v61, v61, v64, v66
	v_div_fixup_f32 v61, v61, v63, 1.0
	v_div_scale_f32 v63, s[22:23], v62, v62, 1.0
	v_rcp_f32_e32 v64, v63
	v_exp_f32_e32 v44, v44
	v_exp_f32_e32 v45, v45
	v_mul_f32_e32 v40, 0xbfb8aa3b, v40
	v_fma_f32 v65, -v63, v64, 1.0
	v_fmac_f32_e32 v64, v65, v64
	v_div_scale_f32 v65, vcc, 1.0, v62, 1.0
	v_mul_f32_e32 v66, v65, v64
	v_fma_f32 v67, -v63, v66, v65
	v_fmac_f32_e32 v66, v67, v64
	v_fma_f32 v63, -v63, v66, v65
	v_div_fmas_f32 v63, v63, v64, v66
	v_div_fixup_f32 v62, v63, v62, 1.0
	v_cvt_pk_bf16_f32 v61, v62, v61
	v_div_scale_f32 v62, s[22:23], v57, v57, 1.0
	v_rcp_f32_e32 v63, v62
	v_pk_add_f32 v[44:45], v[44:45], 1.0 op_sel_hi:[1,0]
	v_mul_f32_e32 v41, 0xbfb8aa3b, v41
	v_exp_f32_e32 v40, v40
	v_fma_f32 v64, -v62, v63, 1.0
	v_fmac_f32_e32 v63, v64, v63
	v_div_scale_f32 v64, vcc, 1.0, v57, 1.0
	v_mul_f32_e32 v65, v64, v63
	v_fma_f32 v66, -v62, v65, v64
	v_fmac_f32_e32 v65, v66, v63
	v_fma_f32 v62, -v62, v65, v64
	v_div_fmas_f32 v62, v62, v63, v65
	v_div_fixup_f32 v57, v62, v57, 1.0
	v_div_scale_f32 v62, s[22:23], v56, v56, 1.0
	v_rcp_f32_e32 v63, v62
	v_exp_f32_e32 v41, v41
	v_mul_f32_e32 v36, 0xbfb8aa3b, v36
	v_mul_f32_e32 v37, 0xbfb8aa3b, v37
	v_fma_f32 v64, -v62, v63, 1.0
	v_fmac_f32_e32 v63, v64, v63
	v_div_scale_f32 v64, vcc, 1.0, v56, 1.0
	v_mul_f32_e32 v65, v64, v63
	v_fma_f32 v66, -v62, v65, v64
	v_fmac_f32_e32 v65, v66, v63
	v_fma_f32 v62, -v62, v65, v64
	v_div_fmas_f32 v62, v62, v63, v65
	v_div_fixup_f32 v56, v62, v56, 1.0
	v_cvt_pk_bf16_f32 v56, v56, v57
	v_mul_f32_e32 v57, 0xbfb8aa3b, v58
	v_exp_f32_e32 v58, v57
	v_mul_f32_e32 v57, 0xbfb8aa3b, v59
	v_exp_f32_e32 v59, v57
	v_pk_add_f32 v[40:41], v[40:41], 1.0 op_sel_hi:[1,0]
	v_exp_f32_e32 v36, v36
	v_exp_f32_e32 v37, v37
	v_pk_add_f32 v[58:59], v[58:59], 1.0 op_sel_hi:[1,0]
	v_mul_f32_e32 v32, 0xbfb8aa3b, v32
	v_div_scale_f32 v57, s[22:23], v59, v59, 1.0
	v_rcp_f32_e32 v62, v57
	v_pk_add_f32 v[36:37], v[36:37], 1.0 op_sel_hi:[1,0]
	v_mul_f32_e32 v33, 0xbfb8aa3b, v33
	v_exp_f32_e32 v32, v32
	v_fma_f32 v63, -v57, v62, 1.0
	v_fmac_f32_e32 v62, v63, v62
	v_div_scale_f32 v63, vcc, 1.0, v59, 1.0
	v_mul_f32_e32 v64, v63, v62
	v_fma_f32 v65, -v57, v64, v63
	v_fmac_f32_e32 v64, v65, v62
	v_fma_f32 v57, -v57, v64, v63
	v_div_fmas_f32 v57, v57, v62, v64
	v_div_fixup_f32 v57, v57, v59, 1.0
	v_div_scale_f32 v59, s[22:23], v58, v58, 1.0
	v_rcp_f32_e32 v62, v59
	v_exp_f32_e32 v33, v33
; __device__ __forceinline__ float sigmoidf_(float x) { return 1.f / (1.f + __expf(-x)); }
; __device__ __forceinline__ void phase_merge(const Params& P, u16* sA, u16* sB) {
;     ...
; #pragma unroll
;       for (int mi = 0; mi < 4; mi++)
; #pragma unroll
;         for (int ni = 0; ni < 4; ni++) {
;           f32x4 g = ag[mi][ni];
;           gp[mi][ni] = u32x2{pk2bf(sigmoidf_(g[0]), sigmoidf_(g[1])), pk2bf(sigmoidf_(g[2]), sigmoidf_(g[3]))};
;         }
	v_mul_f32_e32 v28, 0xbfb8aa3b, v28
	v_mul_f32_e32 v29, 0xbfb8aa3b, v29
	v_fma_f32 v63, -v59, v62, 1.0
	v_fmac_f32_e32 v62, v63, v62
	v_div_scale_f32 v63, vcc, 1.0, v58, 1.0
	v_mul_f32_e32 v64, v63, v62
	v_fma_f32 v65, -v59, v64, v63
	v_fmac_f32_e32 v64, v65, v62
	v_fma_f32 v59, -v59, v64, v63
	v_div_fmas_f32 v59, v59, v62, v64
	v_div_fixup_f32 v58, v59, v58, 1.0
	v_cvt_pk_bf16_f32 v57, v58, v57
	v_div_scale_f32 v58, s[22:23], v53, v53, 1.0
	v_rcp_f32_e32 v59, v58
	v_pk_add_f32 v[32:33], v[32:33], 1.0 op_sel_hi:[1,0]
	v_exp_f32_e32 v28, v28
	v_exp_f32_e32 v29, v29
	v_fma_f32 v62, -v58, v59, 1.0
	v_fmac_f32_e32 v59, v62, v59
	v_div_scale_f32 v62, vcc, 1.0, v53, 1.0
	v_mul_f32_e32 v63, v62, v59
	v_fma_f32 v64, -v58, v63, v62
	v_fmac_f32_e32 v63, v64, v59
	v_fma_f32 v58, -v58, v63, v62
	v_div_fmas_f32 v58, v58, v59, v63
	v_div_fixup_f32 v53, v58, v53, 1.0
	v_div_scale_f32 v58, s[22:23], v52, v52, 1.0
	v_rcp_f32_e32 v59, v58
	v_pk_add_f32 v[28:29], v[28:29], 1.0 op_sel_hi:[1,0]
	v_mul_f32_e32 v24, 0xbfb8aa3b, v24
	v_mul_f32_e32 v25, 0xbfb8aa3b, v25
	v_fma_f32 v62, -v58, v59, 1.0
	v_fmac_f32_e32 v59, v62, v59
	v_div_scale_f32 v62, vcc, 1.0, v52, 1.0
	v_mul_f32_e32 v63, v62, v59
	v_fma_f32 v64, -v58, v63, v62
	v_fmac_f32_e32 v63, v64, v59
	v_fma_f32 v58, -v58, v63, v62
	v_div_fmas_f32 v58, v58, v59, v63
	v_div_fixup_f32 v52, v58, v52, 1.0
	v_cvt_pk_bf16_f32 v52, v52, v53
	v_mul_f32_e32 v53, 0xbfb8aa3b, v54
	v_exp_f32_e32 v54, v53
	v_mul_f32_e32 v53, 0xbfb8aa3b, v55
	v_exp_f32_e32 v55, v53
	v_exp_f32_e32 v24, v24
	v_exp_f32_e32 v25, v25
	v_mul_f32_e32 v20, 0xbfb8aa3b, v20
	v_pk_add_f32 v[54:55], v[54:55], 1.0 op_sel_hi:[1,0]
	v_mul_f32_e32 v21, 0xbfb8aa3b, v21
	v_div_scale_f32 v53, s[22:23], v55, v55, 1.0
	v_rcp_f32_e32 v58, v53
	v_pk_add_f32 v[24:25], v[24:25], 1.0 op_sel_hi:[1,0]
	v_exp_f32_e32 v20, v20
	v_exp_f32_e32 v21, v21
	v_fma_f32 v59, -v53, v58, 1.0
	v_fmac_f32_e32 v58, v59, v58
	v_div_scale_f32 v59, vcc, 1.0, v55, 1.0
	v_mul_f32_e32 v62, v59, v58
	v_fma_f32 v63, -v53, v62, v59
	v_fmac_f32_e32 v62, v63, v58
	v_fma_f32 v53, -v53, v62, v59
	v_div_fmas_f32 v53, v53, v58, v62
	v_div_fixup_f32 v53, v53, v55, 1.0
	v_div_scale_f32 v55, s[22:23], v54, v54, 1.0
	v_rcp_f32_e32 v58, v55
	v_pk_add_f32 v[20:21], v[20:21], 1.0 op_sel_hi:[1,0]
	v_mul_f32_e32 v16, 0xbfb8aa3b, v16
	v_mul_f32_e32 v17, 0xbfb8aa3b, v17
	v_fma_f32 v59, -v55, v58, 1.0
	v_fmac_f32_e32 v58, v59, v58
	v_div_scale_f32 v59, vcc, 1.0, v54, 1.0
	v_mul_f32_e32 v62, v59, v58
	v_fma_f32 v63, -v55, v62, v59
	v_fmac_f32_e32 v62, v63, v58
	v_fma_f32 v55, -v55, v62, v59
	v_div_fmas_f32 v55, v55, v58, v62
	v_div_fixup_f32 v54, v55, v54, 1.0
	v_cvt_pk_bf16_f32 v53, v54, v53
	v_div_scale_f32 v54, s[22:23], v49, v49, 1.0
	v_rcp_f32_e32 v55, v54
	v_exp_f32_e32 v16, v16
	v_exp_f32_e32 v17, v17
	v_mul_f32_e32 v12, 0xbfb8aa3b, v12
	v_fma_f32 v58, -v54, v55, 1.0
	v_fmac_f32_e32 v55, v58, v55
	v_div_scale_f32 v58, vcc, 1.0, v49, 1.0
	v_mul_f32_e32 v59, v58, v55
	v_fma_f32 v62, -v54, v59, v58
	v_fmac_f32_e32 v59, v62, v55
	v_fma_f32 v54, -v54, v59, v58
	v_div_fmas_f32 v54, v54, v55, v59
	v_div_fixup_f32 v49, v54, v49, 1.0
	v_div_scale_f32 v54, s[22:23], v48, v48, 1.0
	v_rcp_f32_e32 v55, v54
	v_pk_add_f32 v[16:17], v[16:17], 1.0 op_sel_hi:[1,0]
	v_mul_f32_e32 v13, 0xbfb8aa3b, v13
	v_exp_f32_e32 v12, v12
	v_fma_f32 v58, -v54, v55, 1.0
	v_fmac_f32_e32 v55, v58, v55
	v_div_scale_f32 v58, vcc, 1.0, v48, 1.0
	v_mul_f32_e32 v59, v58, v55
	v_fma_f32 v62, -v54, v59, v58
	v_fmac_f32_e32 v59, v62, v55
	v_fma_f32 v54, -v54, v59, v58
	v_div_fmas_f32 v54, v54, v55, v59
	v_div_fixup_f32 v48, v54, v48, 1.0
	v_cvt_pk_bf16_f32 v54, v48, v49
	v_mul_f32_e32 v48, 0xbfb8aa3b, v50
	v_mul_f32_e32 v49, 0xbfb8aa3b, v51
	v_exp_f32_e32 v48, v48
	v_exp_f32_e32 v49, v49
	v_exp_f32_e32 v13, v13
	v_mul_f32_e32 v8, 0xbfb8aa3b, v8
	v_mul_f32_e32 v9, 0xbfb8aa3b, v9
	v_pk_add_f32 v[48:49], v[48:49], 1.0 op_sel_hi:[1,0]
	v_pk_add_f32 v[12:13], v[12:13], 1.0 op_sel_hi:[1,0]
	v_div_scale_f32 v50, s[22:23], v49, v49, 1.0
	v_rcp_f32_e32 v51, v50
	v_exp_f32_e32 v8, v8
	v_exp_f32_e32 v9, v9
	v_mul_f32_e32 v4, 0xbfb8aa3b, v4
	v_fma_f32 v55, -v50, v51, 1.0
	v_fmac_f32_e32 v51, v55, v51
	v_div_scale_f32 v55, vcc, 1.0, v49, 1.0
	v_mul_f32_e32 v58, v55, v51
	v_fma_f32 v59, -v50, v58, v55
	v_fmac_f32_e32 v58, v59, v51
	v_fma_f32 v50, -v50, v58, v55
	v_div_fmas_f32 v50, v50, v51, v58
	v_div_fixup_f32 v49, v50, v49, 1.0
	v_div_scale_f32 v50, s[22:23], v48, v48, 1.0
	v_rcp_f32_e32 v51, v50
	v_pk_add_f32 v[8:9], v[8:9], 1.0 op_sel_hi:[1,0]
	v_mul_f32_e32 v5, 0xbfb8aa3b, v5
	v_exp_f32_e32 v4, v4
	v_fma_f32 v55, -v50, v51, 1.0
	v_fmac_f32_e32 v51, v55, v51
	v_div_scale_f32 v55, vcc, 1.0, v48, 1.0
	v_mul_f32_e32 v58, v55, v51
	v_fma_f32 v59, -v50, v58, v55
	v_fmac_f32_e32 v58, v59, v51
	v_fma_f32 v50, -v50, v58, v55
	v_div_fmas_f32 v50, v50, v51, v58
	v_div_fixup_f32 v48, v50, v48, 1.0
	v_cvt_pk_bf16_f32 v50, v48, v49
	v_div_scale_f32 v48, s[22:23], v45, v45, 1.0
	v_rcp_f32_e32 v49, v48
	v_exp_f32_e32 v5, v5
	v_mul_f32_e32 v0, 0xbfb8aa3b, v0
	v_mul_f32_e32 v1, 0xbfb8aa3b, v1
	v_fma_f32 v51, -v48, v49, 1.0
	v_fmac_f32_e32 v49, v51, v49
	v_div_scale_f32 v51, vcc, 1.0, v45, 1.0
	v_mul_f32_e32 v55, v51, v49
	v_fma_f32 v58, -v48, v55, v51
	v_fmac_f32_e32 v55, v58, v49
	v_fma_f32 v48, -v48, v55, v51
	v_div_fmas_f32 v48, v48, v49, v55
	v_div_fixup_f32 v45, v48, v45, 1.0
	v_div_scale_f32 v48, s[22:23], v44, v44, 1.0
	v_rcp_f32_e32 v49, v48
	v_pk_add_f32 v[4:5], v[4:5], 1.0 op_sel_hi:[1,0]
	v_exp_f32_e32 v0, v0
	v_exp_f32_e32 v1, v1
	v_fma_f32 v51, -v48, v49, 1.0
	v_fmac_f32_e32 v49, v51, v49
	v_div_scale_f32 v51, vcc, 1.0, v44, 1.0
	v_mul_f32_e32 v55, v51, v49
	v_fma_f32 v58, -v48, v55, v51
	v_fmac_f32_e32 v55, v58, v49
	v_fma_f32 v48, -v48, v55, v51
	v_div_fmas_f32 v48, v48, v49, v55
	v_div_fixup_f32 v44, v48, v44, 1.0
	v_cvt_pk_bf16_f32 v51, v44, v45
	v_mul_f32_e32 v44, 0xbfb8aa3b, v46
	v_mul_f32_e32 v45, 0xbfb8aa3b, v47
	v_exp_f32_e32 v44, v44
	v_exp_f32_e32 v45, v45
	v_pk_add_f32 v[0:1], v[0:1], 1.0 op_sel_hi:[1,0]
	s_waitcnt vmcnt(2)
; __device__ __forceinline__ float sigmoidf_(float x) { return 1.f / (1.f + __expf(-x)); }
; __device__ __forceinline__ void phase_merge(const Params& P, u16* sA, u16* sB) {
;     ...
; #pragma unroll
;       for (int mi = 0; mi < 4; mi++)
; #pragma unroll
;         for (int ni = 0; ni < 4; ni++) {
;           f32x4 g = ag[mi][ni];
;           gp[mi][ni] = u32x2{pk2bf(sigmoidf_(g[0]), sigmoidf_(g[1])), pk2bf(sigmoidf_(g[2]), sigmoidf_(g[3]))};
;         }
	v_mov_b32_e32 v82, v169
	v_pk_add_f32 v[44:45], v[44:45], 1.0 op_sel_hi:[1,0]
	v_lshlrev_b32_e32 v83, 4, v82
	v_div_scale_f32 v46, s[22:23], v45, v45, 1.0
	v_rcp_f32_e32 v47, v46
	v_and_b32_e32 v130, 0x70, v83
	v_lshrrev_b32_e32 v84, 4, v82
	v_xor_b32_e32 v85, v84, v82
	v_fma_f32 v48, -v46, v47, 1.0
	v_fmac_f32_e32 v47, v48, v47
	v_div_scale_f32 v48, vcc, 1.0, v45, 1.0
	v_mul_f32_e32 v49, v48, v47
	v_fma_f32 v55, -v46, v49, v48
	v_fmac_f32_e32 v49, v55, v47
	v_fma_f32 v46, -v46, v49, v48
	v_div_fmas_f32 v46, v46, v47, v49
	v_div_fixup_f32 v45, v46, v45, 1.0
	v_div_scale_f32 v46, s[22:23], v44, v44, 1.0
	v_rcp_f32_e32 v47, v46
	v_lshlrev_b32_e32 v85, 4, v85
	v_and_b32_e32 v85, 0x70, v85
	v_and_b32_e32 v86, 15, v82
	v_fma_f32 v48, -v46, v47, 1.0
	v_fmac_f32_e32 v47, v48, v47
	v_div_scale_f32 v48, vcc, 1.0, v44, 1.0
	v_mul_f32_e32 v49, v48, v47
	v_fma_f32 v55, -v46, v49, v48
	v_fmac_f32_e32 v49, v55, v47
	v_fma_f32 v46, -v46, v49, v48
	v_div_fmas_f32 v46, v46, v47, v49
	v_div_fixup_f32 v44, v46, v44, 1.0
	v_cvt_pk_bf16_f32 v55, v44, v45
	v_div_scale_f32 v44, s[22:23], v41, v41, 1.0
	v_rcp_f32_e32 v45, v44
	v_bfe_u32 v87, v82, 1, 3
	v_lshlrev_b32_e32 v86, 7, v86
	s_movk_i32 s21, 0x800
	v_fma_f32 v46, -v44, v45, 1.0
	v_fmac_f32_e32 v45, v46, v45
	v_div_scale_f32 v46, vcc, 1.0, v41, 1.0
	v_mul_f32_e32 v47, v46, v45
	v_fma_f32 v48, -v44, v47, v46
	v_fmac_f32_e32 v47, v48, v45
	v_fma_f32 v44, -v44, v47, v46
	v_div_fmas_f32 v44, v44, v45, v47
	v_div_fixup_f32 v41, v44, v41, 1.0
	v_div_scale_f32 v44, s[22:23], v40, v40, 1.0
	v_rcp_f32_e32 v45, v44
	v_bitop3_b32 v84, v84, v87, 3 bitop3:0x6c
	v_lshlrev_b32_e32 v84, 4, v84
	v_fma_f32 v46, -v44, v45, 1.0
	v_fmac_f32_e32 v45, v46, v45
	v_div_scale_f32 v46, vcc, 1.0, v40, 1.0
	v_mul_f32_e32 v47, v46, v45
	v_fma_f32 v48, -v44, v47, v46
	v_fmac_f32_e32 v47, v48, v45
	v_fma_f32 v44, -v44, v47, v46
	v_div_fmas_f32 v44, v44, v45, v47
	v_div_fixup_f32 v40, v44, v40, 1.0
	v_cvt_pk_bf16_f32 v58, v40, v41
	v_mul_f32_e32 v40, 0xbfb8aa3b, v42
	v_mul_f32_e32 v41, 0xbfb8aa3b, v43
	v_exp_f32_e32 v40, v40
	v_exp_f32_e32 v41, v41
	s_nop 0
	v_pk_add_f32 v[40:41], v[40:41], 1.0 op_sel_hi:[1,0]
	s_nop 0
	v_div_scale_f32 v42, s[22:23], v41, v41, 1.0
	v_rcp_f32_e32 v43, v42
	s_nop 0
	v_fma_f32 v44, -v42, v43, 1.0
	v_fmac_f32_e32 v43, v44, v43
	v_div_scale_f32 v44, vcc, 1.0, v41, 1.0
	v_mul_f32_e32 v45, v44, v43
	v_fma_f32 v46, -v42, v45, v44
	v_fmac_f32_e32 v45, v46, v43
	v_fma_f32 v42, -v42, v45, v44
	v_div_fmas_f32 v42, v42, v43, v45
	v_div_fixup_f32 v41, v42, v41, 1.0
	v_div_scale_f32 v42, s[22:23], v40, v40, 1.0
	v_rcp_f32_e32 v43, v42
	s_nop 0
	v_fma_f32 v44, -v42, v43, 1.0
	v_fmac_f32_e32 v43, v44, v43
	v_div_scale_f32 v44, vcc, 1.0, v40, 1.0
	v_mul_f32_e32 v45, v44, v43
	v_fma_f32 v46, -v42, v45, v44
	v_fmac_f32_e32 v45, v46, v43
	v_fma_f32 v42, -v42, v45, v44
	v_div_fmas_f32 v42, v42, v43, v45
	v_div_fixup_f32 v40, v42, v40, 1.0
	v_cvt_pk_bf16_f32 v59, v40, v41
	v_div_scale_f32 v40, s[22:23], v37, v37, 1.0
	v_rcp_f32_e32 v41, v40
	s_nop 0
	v_fma_f32 v42, -v40, v41, 1.0
	v_fmac_f32_e32 v41, v42, v41
	v_div_scale_f32 v42, vcc, 1.0, v37, 1.0
	v_mul_f32_e32 v43, v42, v41
	v_fma_f32 v44, -v40, v43, v42
	v_fmac_f32_e32 v43, v44, v41
	v_fma_f32 v40, -v40, v43, v42
	v_div_fmas_f32 v40, v40, v41, v43
	v_div_fixup_f32 v37, v40, v37, 1.0
	v_div_scale_f32 v40, s[22:23], v36, v36, 1.0
	v_rcp_f32_e32 v41, v40
	s_nop 0
	v_fma_f32 v42, -v40, v41, 1.0
	v_fmac_f32_e32 v41, v42, v41
	v_div_scale_f32 v42, vcc, 1.0, v36, 1.0
	v_mul_f32_e32 v43, v42, v41
	v_fma_f32 v44, -v40, v43, v42
	v_fmac_f32_e32 v43, v44, v41
	v_fma_f32 v40, -v40, v43, v42
	v_div_fmas_f32 v40, v40, v41, v43
	v_div_fixup_f32 v36, v40, v36, 1.0
	v_cvt_pk_bf16_f32 v62, v36, v37
	v_mul_f32_e32 v36, 0xbfb8aa3b, v38
	v_mul_f32_e32 v37, 0xbfb8aa3b, v39
	v_exp_f32_e32 v36, v36
	v_exp_f32_e32 v37, v37
	s_nop 0
	v_pk_add_f32 v[36:37], v[36:37], 1.0 op_sel_hi:[1,0]
	s_nop 0
	v_div_scale_f32 v38, s[22:23], v37, v37, 1.0
	v_rcp_f32_e32 v39, v38
	s_nop 0
	v_fma_f32 v40, -v38, v39, 1.0
	v_fmac_f32_e32 v39, v40, v39
	v_div_scale_f32 v40, vcc, 1.0, v37, 1.0
	v_mul_f32_e32 v41, v40, v39
	v_fma_f32 v42, -v38, v41, v40
	v_fmac_f32_e32 v41, v42, v39
	v_fma_f32 v38, -v38, v41, v40
	v_div_fmas_f32 v38, v38, v39, v41
	v_div_fixup_f32 v37, v38, v37, 1.0
	v_div_scale_f32 v38, s[22:23], v36, v36, 1.0
	v_rcp_f32_e32 v39, v38
	s_nop 0
	v_fma_f32 v40, -v38, v39, 1.0
	v_fmac_f32_e32 v39, v40, v39
	v_div_scale_f32 v40, vcc, 1.0, v36, 1.0
	v_mul_f32_e32 v41, v40, v39
	v_fma_f32 v42, -v38, v41, v40
	v_fmac_f32_e32 v41, v42, v39
	v_fma_f32 v38, -v38, v41, v40
	v_div_fmas_f32 v38, v38, v39, v41
	v_div_fixup_f32 v36, v38, v36, 1.0
	v_cvt_pk_bf16_f32 v63, v36, v37
	v_div_scale_f32 v36, s[22:23], v33, v33, 1.0
	v_rcp_f32_e32 v37, v36
	s_nop 0
	v_fma_f32 v38, -v36, v37, 1.0
	v_fmac_f32_e32 v37, v38, v37
	v_div_scale_f32 v38, vcc, 1.0, v33, 1.0
	v_mul_f32_e32 v39, v38, v37
	v_fma_f32 v40, -v36, v39, v38
	v_fmac_f32_e32 v39, v40, v37
	v_fma_f32 v36, -v36, v39, v38
	v_div_fmas_f32 v36, v36, v37, v39
	v_div_fixup_f32 v33, v36, v33, 1.0
	v_div_scale_f32 v36, s[22:23], v32, v32, 1.0
	v_rcp_f32_e32 v37, v36
	s_nop 0
	v_fma_f32 v38, -v36, v37, 1.0
	v_fmac_f32_e32 v37, v38, v37
	v_div_scale_f32 v38, vcc, 1.0, v32, 1.0
	v_mul_f32_e32 v39, v38, v37
	v_fma_f32 v40, -v36, v39, v38
	v_fmac_f32_e32 v39, v40, v37
	v_fma_f32 v36, -v36, v39, v38
	v_div_fmas_f32 v36, v36, v37, v39
	v_div_fixup_f32 v32, v36, v32, 1.0
	v_cvt_pk_bf16_f32 v64, v32, v33
	v_mul_f32_e32 v32, 0xbfb8aa3b, v34
	v_mul_f32_e32 v33, 0xbfb8aa3b, v35
	v_exp_f32_e32 v32, v32
	v_exp_f32_e32 v33, v33
	s_nop 0
	v_pk_add_f32 v[32:33], v[32:33], 1.0 op_sel_hi:[1,0]
; __device__ __forceinline__ float sigmoidf_(float x) { return 1.f / (1.f + __expf(-x)); }
; __device__ __forceinline__ void phase_merge(const Params& P, u16* sA, u16* sB) {
;     ...
; #pragma unroll
;       for (int mi = 0; mi < 4; mi++)
; #pragma unroll
;         for (int ni = 0; ni < 4; ni++) {
;           f32x4 g = ag[mi][ni];
;           gp[mi][ni] = u32x2{pk2bf(sigmoidf_(g[0]), sigmoidf_(g[1])), pk2bf(sigmoidf_(g[2]), sigmoidf_(g[3]))};
;         }
	s_nop 0
	v_div_scale_f32 v34, s[22:23], v33, v33, 1.0
	v_rcp_f32_e32 v35, v34
	s_nop 0
	v_fma_f32 v36, -v34, v35, 1.0
	v_fmac_f32_e32 v35, v36, v35
	v_div_scale_f32 v36, vcc, 1.0, v33, 1.0
	v_mul_f32_e32 v37, v36, v35
	v_fma_f32 v38, -v34, v37, v36
	v_fmac_f32_e32 v37, v38, v35
	v_fma_f32 v34, -v34, v37, v36
	v_div_fmas_f32 v34, v34, v35, v37
	v_div_fixup_f32 v33, v34, v33, 1.0
	v_div_scale_f32 v34, s[22:23], v32, v32, 1.0
	v_rcp_f32_e32 v35, v34
	s_nop 0
	v_fma_f32 v36, -v34, v35, 1.0
	v_fmac_f32_e32 v35, v36, v35
	v_div_scale_f32 v36, vcc, 1.0, v32, 1.0
	v_mul_f32_e32 v37, v36, v35
	v_fma_f32 v38, -v34, v37, v36
	v_fmac_f32_e32 v37, v38, v35
	v_fma_f32 v34, -v34, v37, v36
	v_div_fmas_f32 v34, v34, v35, v37
	v_div_fixup_f32 v32, v34, v32, 1.0
	v_cvt_pk_bf16_f32 v65, v32, v33
	v_div_scale_f32 v32, s[22:23], v29, v29, 1.0
	v_rcp_f32_e32 v33, v32
	s_nop 0
	v_fma_f32 v34, -v32, v33, 1.0
	v_fmac_f32_e32 v33, v34, v33
	v_div_scale_f32 v34, vcc, 1.0, v29, 1.0
	v_mul_f32_e32 v35, v34, v33
	v_fma_f32 v36, -v32, v35, v34
	v_fmac_f32_e32 v35, v36, v33
	v_fma_f32 v32, -v32, v35, v34
	v_div_fmas_f32 v32, v32, v33, v35
	v_div_fixup_f32 v29, v32, v29, 1.0
	v_div_scale_f32 v32, s[22:23], v28, v28, 1.0
	v_rcp_f32_e32 v33, v32
	s_nop 0
	v_fma_f32 v34, -v32, v33, 1.0
	v_fmac_f32_e32 v33, v34, v33
	v_div_scale_f32 v34, vcc, 1.0, v28, 1.0
	v_mul_f32_e32 v35, v34, v33
	v_fma_f32 v36, -v32, v35, v34
	v_fmac_f32_e32 v35, v36, v33
	v_fma_f32 v32, -v32, v35, v34
	v_div_fmas_f32 v32, v32, v33, v35
	v_div_fixup_f32 v28, v32, v28, 1.0
	v_cvt_pk_bf16_f32 v66, v28, v29
	v_mul_f32_e32 v28, 0xbfb8aa3b, v30
	v_mul_f32_e32 v29, 0xbfb8aa3b, v31
	v_exp_f32_e32 v28, v28
	v_exp_f32_e32 v29, v29
	s_nop 0
	v_pk_add_f32 v[28:29], v[28:29], 1.0 op_sel_hi:[1,0]
	s_nop 0
	v_div_scale_f32 v30, s[22:23], v29, v29, 1.0
	v_rcp_f32_e32 v31, v30
	s_nop 0
	v_fma_f32 v32, -v30, v31, 1.0
	v_fmac_f32_e32 v31, v32, v31
	v_div_scale_f32 v32, vcc, 1.0, v29, 1.0
	v_mul_f32_e32 v33, v32, v31
	v_fma_f32 v34, -v30, v33, v32
	v_fmac_f32_e32 v33, v34, v31
	v_fma_f32 v30, -v30, v33, v32
	v_div_fmas_f32 v30, v30, v31, v33
	v_div_fixup_f32 v29, v30, v29, 1.0
	v_div_scale_f32 v30, s[22:23], v28, v28, 1.0
	v_rcp_f32_e32 v31, v30
	s_nop 0
	v_fma_f32 v32, -v30, v31, 1.0
	v_fmac_f32_e32 v31, v32, v31
	v_div_scale_f32 v32, vcc, 1.0, v28, 1.0
	v_mul_f32_e32 v33, v32, v31
	v_fma_f32 v34, -v30, v33, v32
	v_fmac_f32_e32 v33, v34, v31
	v_fma_f32 v30, -v30, v33, v32
	v_div_fmas_f32 v30, v30, v31, v33
	v_div_fixup_f32 v28, v30, v28, 1.0
	v_cvt_pk_bf16_f32 v67, v28, v29
	v_div_scale_f32 v28, s[22:23], v25, v25, 1.0
	v_rcp_f32_e32 v29, v28
	s_nop 0
	v_fma_f32 v30, -v28, v29, 1.0
	v_fmac_f32_e32 v29, v30, v29
	v_div_scale_f32 v30, vcc, 1.0, v25, 1.0
	v_mul_f32_e32 v31, v30, v29
	v_fma_f32 v32, -v28, v31, v30
	v_fmac_f32_e32 v31, v32, v29
	v_fma_f32 v28, -v28, v31, v30
	v_div_fmas_f32 v28, v28, v29, v31
	v_div_fixup_f32 v25, v28, v25, 1.0
	v_div_scale_f32 v28, s[22:23], v24, v24, 1.0
	v_rcp_f32_e32 v29, v28
	s_nop 0
	v_fma_f32 v30, -v28, v29, 1.0
	v_fmac_f32_e32 v29, v30, v29
	v_div_scale_f32 v30, vcc, 1.0, v24, 1.0
	v_mul_f32_e32 v31, v30, v29
	v_fma_f32 v32, -v28, v31, v30
	v_fmac_f32_e32 v31, v32, v29
	v_fma_f32 v28, -v28, v31, v30
	v_div_fmas_f32 v28, v28, v29, v31
	v_div_fixup_f32 v24, v28, v24, 1.0
	v_cvt_pk_bf16_f32 v68, v24, v25
	v_mul_f32_e32 v24, 0xbfb8aa3b, v26
	v_mul_f32_e32 v25, 0xbfb8aa3b, v27
	v_exp_f32_e32 v24, v24
	v_exp_f32_e32 v25, v25
	s_nop 0
	v_pk_add_f32 v[24:25], v[24:25], 1.0 op_sel_hi:[1,0]
	s_nop 0
	v_div_scale_f32 v26, s[22:23], v25, v25, 1.0
	v_rcp_f32_e32 v27, v26
	s_nop 0
	v_fma_f32 v28, -v26, v27, 1.0
	v_fmac_f32_e32 v27, v28, v27
	v_div_scale_f32 v28, vcc, 1.0, v25, 1.0
	v_mul_f32_e32 v29, v28, v27
	v_fma_f32 v30, -v26, v29, v28
	v_fmac_f32_e32 v29, v30, v27
	v_fma_f32 v26, -v26, v29, v28
	v_div_fmas_f32 v26, v26, v27, v29
	v_div_fixup_f32 v25, v26, v25, 1.0
	v_div_scale_f32 v26, s[22:23], v24, v24, 1.0
	v_rcp_f32_e32 v27, v26
	s_nop 0
	v_fma_f32 v28, -v26, v27, 1.0
	v_fmac_f32_e32 v27, v28, v27
	v_div_scale_f32 v28, vcc, 1.0, v24, 1.0
	v_mul_f32_e32 v29, v28, v27
	v_fma_f32 v30, -v26, v29, v28
	v_fmac_f32_e32 v29, v30, v27
	v_fma_f32 v26, -v26, v29, v28
	v_div_fmas_f32 v26, v26, v27, v29
	v_div_fixup_f32 v24, v26, v24, 1.0
	v_cvt_pk_bf16_f32 v69, v24, v25
	v_div_scale_f32 v24, s[22:23], v21, v21, 1.0
	v_rcp_f32_e32 v25, v24
	s_nop 0
	v_fma_f32 v26, -v24, v25, 1.0
	v_fmac_f32_e32 v25, v26, v25
	v_div_scale_f32 v26, vcc, 1.0, v21, 1.0
	v_mul_f32_e32 v27, v26, v25
	v_fma_f32 v28, -v24, v27, v26
	v_fmac_f32_e32 v27, v28, v25
	v_fma_f32 v24, -v24, v27, v26
	v_div_fmas_f32 v24, v24, v25, v27
	v_div_fixup_f32 v21, v24, v21, 1.0
	v_div_scale_f32 v24, s[22:23], v20, v20, 1.0
	v_rcp_f32_e32 v25, v24
	s_nop 0
	v_fma_f32 v26, -v24, v25, 1.0
	v_fmac_f32_e32 v25, v26, v25
	v_div_scale_f32 v26, vcc, 1.0, v20, 1.0
	v_mul_f32_e32 v27, v26, v25
	v_fma_f32 v28, -v24, v27, v26
	v_fmac_f32_e32 v27, v28, v25
	v_fma_f32 v24, -v24, v27, v26
	v_div_fmas_f32 v24, v24, v25, v27
	v_div_fixup_f32 v20, v24, v20, 1.0
	v_cvt_pk_bf16_f32 v70, v20, v21
	v_mul_f32_e32 v20, 0xbfb8aa3b, v22
	v_mul_f32_e32 v21, 0xbfb8aa3b, v23
	v_exp_f32_e32 v20, v20
	v_exp_f32_e32 v21, v21
	s_nop 0
	v_pk_add_f32 v[20:21], v[20:21], 1.0 op_sel_hi:[1,0]
	s_nop 0
	v_div_scale_f32 v22, s[22:23], v21, v21, 1.0
	v_rcp_f32_e32 v23, v22
	s_nop 0
	v_fma_f32 v24, -v22, v23, 1.0
	v_fmac_f32_e32 v23, v24, v23
	v_div_scale_f32 v24, vcc, 1.0, v21, 1.0
	v_mul_f32_e32 v25, v24, v23
	v_fma_f32 v26, -v22, v25, v24
	v_fmac_f32_e32 v25, v26, v23
	v_fma_f32 v22, -v22, v25, v24
	v_div_fmas_f32 v22, v22, v23, v25
	v_div_fixup_f32 v21, v22, v21, 1.0
; __device__ __forceinline__ float sigmoidf_(float x) { return 1.f / (1.f + __expf(-x)); }
; __device__ __forceinline__ void phase_merge(const Params& P, u16* sA, u16* sB) {
;     ...
; #pragma unroll
;       for (int mi = 0; mi < 4; mi++)
; #pragma unroll
;         for (int ni = 0; ni < 4; ni++) {
;           f32x4 g = ag[mi][ni];
;           gp[mi][ni] = u32x2{pk2bf(sigmoidf_(g[0]), sigmoidf_(g[1])), pk2bf(sigmoidf_(g[2]), sigmoidf_(g[3]))};
;         }
	v_div_scale_f32 v22, s[22:23], v20, v20, 1.0
	v_rcp_f32_e32 v23, v22
	s_nop 0
	v_fma_f32 v24, -v22, v23, 1.0
	v_fmac_f32_e32 v23, v24, v23
	v_div_scale_f32 v24, vcc, 1.0, v20, 1.0
	v_mul_f32_e32 v25, v24, v23
	v_fma_f32 v26, -v22, v25, v24
	v_fmac_f32_e32 v25, v26, v23
	v_fma_f32 v22, -v22, v25, v24
	v_div_fmas_f32 v22, v22, v23, v25
	v_div_fixup_f32 v20, v22, v20, 1.0
	v_cvt_pk_bf16_f32 v71, v20, v21
	v_div_scale_f32 v20, s[22:23], v17, v17, 1.0
	v_rcp_f32_e32 v21, v20
	s_nop 0
	v_fma_f32 v22, -v20, v21, 1.0
	v_fmac_f32_e32 v21, v22, v21
	v_div_scale_f32 v22, vcc, 1.0, v17, 1.0
	v_mul_f32_e32 v23, v22, v21
	v_fma_f32 v24, -v20, v23, v22
	v_fmac_f32_e32 v23, v24, v21
	v_fma_f32 v20, -v20, v23, v22
	v_div_fmas_f32 v20, v20, v21, v23
	v_div_fixup_f32 v17, v20, v17, 1.0
	v_div_scale_f32 v20, s[22:23], v16, v16, 1.0
	v_rcp_f32_e32 v21, v20
	s_nop 0
	v_fma_f32 v22, -v20, v21, 1.0
	v_fmac_f32_e32 v21, v22, v21
	v_div_scale_f32 v22, vcc, 1.0, v16, 1.0
	v_mul_f32_e32 v23, v22, v21
	v_fma_f32 v24, -v20, v23, v22
	v_fmac_f32_e32 v23, v24, v21
	v_fma_f32 v20, -v20, v23, v22
	v_div_fmas_f32 v20, v20, v21, v23
	v_div_fixup_f32 v16, v20, v16, 1.0
	v_cvt_pk_bf16_f32 v72, v16, v17
	v_mul_f32_e32 v16, 0xbfb8aa3b, v18
	v_mul_f32_e32 v17, 0xbfb8aa3b, v19
	v_exp_f32_e32 v16, v16
	v_exp_f32_e32 v17, v17
	s_nop 0
	v_pk_add_f32 v[16:17], v[16:17], 1.0 op_sel_hi:[1,0]
	s_nop 0
	v_div_scale_f32 v18, s[22:23], v17, v17, 1.0
	v_rcp_f32_e32 v19, v18
	s_nop 0
	v_fma_f32 v20, -v18, v19, 1.0
	v_fmac_f32_e32 v19, v20, v19
	v_div_scale_f32 v20, vcc, 1.0, v17, 1.0
	v_mul_f32_e32 v21, v20, v19
	v_fma_f32 v22, -v18, v21, v20
	v_fmac_f32_e32 v21, v22, v19
	v_fma_f32 v18, -v18, v21, v20
	v_div_fmas_f32 v18, v18, v19, v21
	v_div_fixup_f32 v17, v18, v17, 1.0
	v_div_scale_f32 v18, s[22:23], v16, v16, 1.0
	v_rcp_f32_e32 v19, v18
	s_nop 0
	v_fma_f32 v20, -v18, v19, 1.0
	v_fmac_f32_e32 v19, v20, v19
	v_div_scale_f32 v20, vcc, 1.0, v16, 1.0
	v_mul_f32_e32 v21, v20, v19
	v_fma_f32 v22, -v18, v21, v20
	v_fmac_f32_e32 v21, v22, v19
	v_fma_f32 v18, -v18, v21, v20
	v_div_fmas_f32 v18, v18, v19, v21
	v_div_fixup_f32 v16, v18, v16, 1.0
	v_cvt_pk_bf16_f32 v73, v16, v17
	v_div_scale_f32 v16, s[22:23], v13, v13, 1.0
	v_rcp_f32_e32 v17, v16
	s_nop 0
	v_fma_f32 v18, -v16, v17, 1.0
	v_fmac_f32_e32 v17, v18, v17
	v_div_scale_f32 v18, vcc, 1.0, v13, 1.0
	v_mul_f32_e32 v19, v18, v17
	v_fma_f32 v20, -v16, v19, v18
	v_fmac_f32_e32 v19, v20, v17
	v_fma_f32 v16, -v16, v19, v18
	v_div_fmas_f32 v16, v16, v17, v19
	v_div_fixup_f32 v13, v16, v13, 1.0
	v_div_scale_f32 v16, s[22:23], v12, v12, 1.0
	v_rcp_f32_e32 v17, v16
	s_nop 0
	v_fma_f32 v18, -v16, v17, 1.0
	v_fmac_f32_e32 v17, v18, v17
	v_div_scale_f32 v18, vcc, 1.0, v12, 1.0
	v_mul_f32_e32 v19, v18, v17
	v_fma_f32 v20, -v16, v19, v18
	v_fmac_f32_e32 v19, v20, v17
	v_fma_f32 v16, -v16, v19, v18
	v_div_fmas_f32 v16, v16, v17, v19
	v_div_fixup_f32 v12, v16, v12, 1.0
	v_cvt_pk_bf16_f32 v74, v12, v13
	v_mul_f32_e32 v12, 0xbfb8aa3b, v14
	v_mul_f32_e32 v13, 0xbfb8aa3b, v15
	v_exp_f32_e32 v12, v12
	v_exp_f32_e32 v13, v13
	s_nop 0
	v_pk_add_f32 v[12:13], v[12:13], 1.0 op_sel_hi:[1,0]
	s_nop 0
	v_div_scale_f32 v14, s[22:23], v13, v13, 1.0
	v_rcp_f32_e32 v15, v14
	s_nop 0
	v_fma_f32 v16, -v14, v15, 1.0
	v_fmac_f32_e32 v15, v16, v15
	v_div_scale_f32 v16, vcc, 1.0, v13, 1.0
	v_mul_f32_e32 v17, v16, v15
	v_fma_f32 v18, -v14, v17, v16
	v_fmac_f32_e32 v17, v18, v15
	v_fma_f32 v14, -v14, v17, v16
	v_div_fmas_f32 v14, v14, v15, v17
	v_div_fixup_f32 v13, v14, v13, 1.0
	v_div_scale_f32 v14, s[22:23], v12, v12, 1.0
	v_rcp_f32_e32 v15, v14
	s_nop 0
	v_fma_f32 v16, -v14, v15, 1.0
	v_fmac_f32_e32 v15, v16, v15
	v_div_scale_f32 v16, vcc, 1.0, v12, 1.0
	v_mul_f32_e32 v17, v16, v15
	v_fma_f32 v18, -v14, v17, v16
	v_fmac_f32_e32 v17, v18, v15
	v_fma_f32 v14, -v14, v17, v16
	v_div_fmas_f32 v14, v14, v15, v17
	v_div_fixup_f32 v12, v14, v12, 1.0
	v_cvt_pk_bf16_f32 v75, v12, v13
	v_div_scale_f32 v12, s[22:23], v9, v9, 1.0
	v_rcp_f32_e32 v13, v12
	s_nop 0
	v_fma_f32 v14, -v12, v13, 1.0
	v_fmac_f32_e32 v13, v14, v13
	v_div_scale_f32 v14, vcc, 1.0, v9, 1.0
	v_mul_f32_e32 v15, v14, v13
	v_fma_f32 v16, -v12, v15, v14
	v_fmac_f32_e32 v15, v16, v13
	v_fma_f32 v12, -v12, v15, v14
	v_div_fmas_f32 v12, v12, v13, v15
	v_div_fixup_f32 v9, v12, v9, 1.0
	v_div_scale_f32 v12, s[22:23], v8, v8, 1.0
	v_rcp_f32_e32 v13, v12
	s_nop 0
	v_fma_f32 v14, -v12, v13, 1.0
	v_fmac_f32_e32 v13, v14, v13
	v_div_scale_f32 v14, vcc, 1.0, v8, 1.0
	v_mul_f32_e32 v15, v14, v13
	v_fma_f32 v16, -v12, v15, v14
	v_fmac_f32_e32 v15, v16, v13
	v_fma_f32 v12, -v12, v15, v14
	v_div_fmas_f32 v12, v12, v13, v15
	v_div_fixup_f32 v8, v12, v8, 1.0
	v_cvt_pk_bf16_f32 v76, v8, v9
	v_mul_f32_e32 v8, 0xbfb8aa3b, v10
	v_mul_f32_e32 v9, 0xbfb8aa3b, v11
	v_exp_f32_e32 v8, v8
	v_exp_f32_e32 v9, v9
	s_nop 0
	v_pk_add_f32 v[8:9], v[8:9], 1.0 op_sel_hi:[1,0]
	s_nop 0
	v_div_scale_f32 v10, s[22:23], v9, v9, 1.0
	v_rcp_f32_e32 v11, v10
	s_nop 0
	v_fma_f32 v12, -v10, v11, 1.0
	v_fmac_f32_e32 v11, v12, v11
	v_div_scale_f32 v12, vcc, 1.0, v9, 1.0
	v_mul_f32_e32 v13, v12, v11
	v_fma_f32 v14, -v10, v13, v12
	v_fmac_f32_e32 v13, v14, v11
	v_fma_f32 v10, -v10, v13, v12
	v_div_fmas_f32 v10, v10, v11, v13
	v_div_fixup_f32 v9, v10, v9, 1.0
	v_div_scale_f32 v10, s[22:23], v8, v8, 1.0
	v_rcp_f32_e32 v11, v10
	s_nop 0
	v_fma_f32 v12, -v10, v11, 1.0
	v_fmac_f32_e32 v11, v12, v11
	v_div_scale_f32 v12, vcc, 1.0, v8, 1.0
	v_mul_f32_e32 v13, v12, v11
	v_fma_f32 v14, -v10, v13, v12
	v_fmac_f32_e32 v13, v14, v11
	v_fma_f32 v10, -v10, v13, v12
	v_div_fmas_f32 v10, v10, v11, v13
	v_div_fixup_f32 v8, v10, v8, 1.0
	v_cvt_pk_bf16_f32 v77, v8, v9
; __device__ __forceinline__ float sigmoidf_(float x) { return 1.f / (1.f + __expf(-x)); }
; __device__ __forceinline__ void phase_merge(const Params& P, u16* sA, u16* sB) {
;     ...
; #pragma unroll
;       for (int mi = 0; mi < 4; mi++)
; #pragma unroll
;         for (int ni = 0; ni < 4; ni++) {
;           f32x4 g = ag[mi][ni];
;           gp[mi][ni] = u32x2{pk2bf(sigmoidf_(g[0]), sigmoidf_(g[1])), pk2bf(sigmoidf_(g[2]), sigmoidf_(g[3]))};
;         }
;     }
;     f32x4 macc[4];
; #pragma unroll
;     for (int mi = 0; mi < 4; mi++) macc[mi] = f32x4{0.f, 0.f, 0.f, 0.f};
; #pragma unroll
;     for (int i = 0; i < 4; i++) {
;       f32x4 ap[4][1];
;       zero_acc<1>(ap);
;       gemm_main<1>(Y + i * 256, 1024, (const u16*)(ws + O_WB) + (size_t)i * 1024 * 256, 256, 256, m0, n0, ap, sA, sB);
	v_div_scale_f32 v8, s[22:23], v5, v5, 1.0
	v_rcp_f32_e32 v9, v8
	s_nop 0
	v_fma_f32 v10, -v8, v9, 1.0
	v_fmac_f32_e32 v9, v10, v9
	v_div_scale_f32 v10, vcc, 1.0, v5, 1.0
	v_mul_f32_e32 v11, v10, v9
	v_fma_f32 v12, -v8, v11, v10
	v_fmac_f32_e32 v11, v12, v9
	v_fma_f32 v8, -v8, v11, v10
	v_div_fmas_f32 v8, v8, v9, v11
	v_div_fixup_f32 v5, v8, v5, 1.0
	v_div_scale_f32 v8, s[22:23], v4, v4, 1.0
	v_rcp_f32_e32 v9, v8
	s_nop 0
	v_fma_f32 v10, -v8, v9, 1.0
	v_fmac_f32_e32 v9, v10, v9
	v_div_scale_f32 v10, vcc, 1.0, v4, 1.0
	v_mul_f32_e32 v11, v10, v9
	v_fma_f32 v12, -v8, v11, v10
	v_fmac_f32_e32 v11, v12, v9
	v_fma_f32 v8, -v8, v11, v10
	v_div_fmas_f32 v8, v8, v9, v11
	v_div_fixup_f32 v4, v8, v4, 1.0
	v_cvt_pk_bf16_f32 v78, v4, v5
	v_mul_f32_e32 v4, 0xbfb8aa3b, v6
	v_mul_f32_e32 v5, 0xbfb8aa3b, v7
	v_exp_f32_e32 v4, v4
	v_exp_f32_e32 v5, v5
	s_nop 0
	v_pk_add_f32 v[4:5], v[4:5], 1.0 op_sel_hi:[1,0]
	s_nop 0
	v_div_scale_f32 v6, s[22:23], v5, v5, 1.0
	v_rcp_f32_e32 v7, v6
	s_nop 0
	v_fma_f32 v8, -v6, v7, 1.0
	v_fmac_f32_e32 v7, v8, v7
	v_div_scale_f32 v8, vcc, 1.0, v5, 1.0
	v_mul_f32_e32 v9, v8, v7
	v_fma_f32 v10, -v6, v9, v8
	v_fmac_f32_e32 v9, v10, v7
	v_fma_f32 v6, -v6, v9, v8
	v_div_fmas_f32 v6, v6, v7, v9
	v_div_fixup_f32 v5, v6, v5, 1.0
	v_div_scale_f32 v6, s[22:23], v4, v4, 1.0
	v_rcp_f32_e32 v7, v6
	s_nop 0
	v_fma_f32 v8, -v6, v7, 1.0
	v_fmac_f32_e32 v7, v8, v7
	v_div_scale_f32 v8, vcc, 1.0, v4, 1.0
	v_mul_f32_e32 v9, v8, v7
	v_fma_f32 v10, -v6, v9, v8
	v_fmac_f32_e32 v9, v10, v7
	v_fma_f32 v6, -v6, v9, v8
	v_div_fmas_f32 v6, v6, v7, v9
	v_div_fixup_f32 v4, v6, v4, 1.0
	v_cvt_pk_bf16_f32 v79, v4, v5
	v_div_scale_f32 v4, s[22:23], v1, v1, 1.0
	v_rcp_f32_e32 v5, v4
	s_nop 0
	v_fma_f32 v6, -v4, v5, 1.0
	v_fmac_f32_e32 v5, v6, v5
	v_div_scale_f32 v6, vcc, 1.0, v1, 1.0
	v_mul_f32_e32 v7, v6, v5
	v_fma_f32 v8, -v4, v7, v6
	v_fmac_f32_e32 v7, v8, v5
	v_fma_f32 v4, -v4, v7, v6
	v_div_fmas_f32 v4, v4, v5, v7
	v_div_fixup_f32 v1, v4, v1, 1.0
	v_div_scale_f32 v4, s[22:23], v0, v0, 1.0
	v_rcp_f32_e32 v5, v4
	s_nop 0
	v_fma_f32 v6, -v4, v5, 1.0
	v_fmac_f32_e32 v5, v6, v5
	v_div_scale_f32 v6, vcc, 1.0, v0, 1.0
	v_mul_f32_e32 v7, v6, v5
	v_fma_f32 v8, -v4, v7, v6
	v_fmac_f32_e32 v7, v8, v5
	v_fma_f32 v4, -v4, v7, v6
	v_div_fmas_f32 v4, v4, v5, v7
	v_div_fixup_f32 v0, v4, v0, 1.0
	v_cvt_pk_bf16_f32 v80, v0, v1
	v_mul_f32_e32 v0, 0xbfb8aa3b, v2
	v_mul_f32_e32 v1, 0xbfb8aa3b, v3
	v_exp_f32_e32 v0, v0
	v_exp_f32_e32 v1, v1
	s_nop 0
	v_pk_add_f32 v[0:1], v[0:1], 1.0 op_sel_hi:[1,0]
	s_nop 0
	v_div_scale_f32 v2, s[22:23], v1, v1, 1.0
	v_rcp_f32_e32 v3, v2
	s_nop 0
	v_fma_f32 v4, -v2, v3, 1.0
	v_fmac_f32_e32 v3, v4, v3
	v_div_scale_f32 v4, vcc, 1.0, v1, 1.0
	v_mul_f32_e32 v5, v4, v3
	v_fma_f32 v6, -v2, v5, v4
	v_fmac_f32_e32 v5, v6, v3
	v_fma_f32 v2, -v2, v5, v4
	v_div_fmas_f32 v2, v2, v3, v5
	v_div_fixup_f32 v1, v2, v1, 1.0
	v_div_scale_f32 v2, s[22:23], v0, v0, 1.0
	v_rcp_f32_e32 v3, v2
	s_movk_i32 s22, 0xff80
	v_and_or_b32 v118, v83, s22, v85
	v_bfe_u32 v83, v82, 4, 2
	v_fma_f32 v4, -v2, v3, 1.0
	v_fmac_f32_e32 v3, v4, v3
	v_div_scale_f32 v4, vcc, 1.0, v0, 1.0
	v_mul_f32_e32 v5, v4, v3
	v_fma_f32 v6, -v2, v5, v4
	v_fmac_f32_e32 v5, v6, v3
	v_fma_f32 v2, -v2, v5, v4
	v_div_fmas_f32 v2, v2, v3, v5
	v_ashrrev_i32_e32 v4, 3, v82
	v_div_fixup_f32 v0, v2, v0, 1.0
	v_add_u32_e32 v2, s20, v4
	v_ashrrev_i32_e32 v3, 31, v2
	v_cvt_pk_bf16_f32 v81, v0, v1
	v_lshl_add_u64 v[0:1], s[4:5], 0, v[130:131]
	v_lshlrev_b64 v[2:3], 9, v[2:3]
	v_lshl_add_u64 v[40:41], v[0:1], 0, v[2:3]
	v_add_u32_e32 v0, s19, v4
	v_ashrrev_i32_e32 v1, 31, v0
	v_lshlrev_b64 v[0:1], 11, v[0:1]
	v_lshl_add_u64 v[0:1], s[0:1], 0, v[0:1]
	v_lshl_add_u64 v[42:43], v[0:1], 0, v[130:131]
	v_add_co_u32_e32 v44, vcc, s33, v42
	global_load_dwordx4 v[20:23], v[42:43], off
	s_nop 0
	v_addc_co_u32_e32 v45, vcc, 0, v43, vcc
	v_add_co_u32_e32 v46, vcc, s56, v42
	global_load_dwordx4 v[24:27], v[44:45], off
	s_nop 0
	v_addc_co_u32_e32 v47, vcc, 0, v43, vcc
	global_load_dwordx4 v[28:31], v[46:47], off
	v_add_co_u32_e32 v48, vcc, s57, v42
	v_lshlrev_b32_e32 v85, 5, v82
	s_nop 0
	v_addc_co_u32_e32 v49, vcc, 0, v43, vcc
	global_load_dwordx4 v[32:35], v[48:49], off
	global_load_dwordx4 v[36:39], v[40:41], off
	global_load_dwordx4 v[0:3], v[42:43], off offset:128
	global_load_dwordx4 v[4:7], v[44:45], off offset:128
	global_load_dwordx4 v[8:11], v[46:47], off offset:128
	global_load_dwordx4 v[12:15], v[48:49], off offset:128
	global_load_dwordx4 v[16:19], v[40:41], off offset:128
	s_barrier
	s_waitcnt vmcnt(9)
	ds_write_b128 v118, v[20:23]
	s_waitcnt vmcnt(8)
	ds_write_b128 v118, v[24:27] offset:4096
	s_waitcnt vmcnt(7)
	ds_write_b128 v118, v[28:31] offset:8192
	s_waitcnt vmcnt(6)
	ds_write_b128 v118, v[32:35] offset:12288
	s_waitcnt vmcnt(5)
	ds_write_b128 v118, v[36:39] offset:16384
	s_waitcnt lgkmcnt(0)
	s_barrier
; #define GLOAD(ra, rb, koff)                                                        \
;   {                                                                                \
;     _Pragma("unroll") for (int j = 0; j < 4; j++) ra[j] = *(const u32x4*)(pa + j * sa32 + (koff));   \
;     _Pragma("unroll") for (int j = 0; j < NB_; j++) rb[j] = *(const u32x4*)(pbv[j] + (koff));         \
;   }
; template <int NT, bool PRE> ...
;     ...
;   if (!PRE) {
;     GLOAD(ra0, rb0, 0);
;     GLOAD(ra1, rb1, 64);
;   }
;   __syncthreads();
;   for (int k0 = 0; k0 < K; k0 += 128) {
;     LSTORE(ra0, rb0, 0);
;     __syncthreads();
;     GLOAD(ra0, rb0, min(k0 + 128, K - 128));
;     __builtin_amdgcn_sched_barrier(0);
;     COMPUTE(0);
;     LSTORE(ra1, rb1, 1);
;     __syncthreads();
;     GLOAD(ra1, rb1, min(k0 + 192, K - 64));
;     __builtin_amdgcn_sched_barrier(0);
;     COMPUTE(1);
;   }
	global_load_dwordx4 v[20:23], v[42:43], off offset:256
	global_load_dwordx4 v[24:27], v[44:45], off offset:256
	global_load_dwordx4 v[28:31], v[46:47], off offset:256
	global_load_dwordx4 v[32:35], v[48:49], off offset:256
	global_load_dwordx4 v[36:39], v[40:41], off offset:256
	v_lshlrev_b32_e32 v82, 6, v82
	v_bitop3_b32 v83, v83, v87, 4 bitop3:0x36
	v_and_or_b32 v85, v85, s21, v86
	v_and_b32_e32 v82, 0xffffe000, v82
	v_lshlrev_b32_e32 v83, 4, v83
	v_or3_b32 v119, v84, v82, v86
	v_or_b32_e32 v120, v85, v84
	v_or3_b32 v121, v83, v82, v86
	v_or_b32_e32 v122, v85, v83
	ds_read_b128 v[82:85], v119
	ds_read_b128 v[86:89], v119 offset:2048
	ds_read_b128 v[90:93], v119 offset:4096
	ds_read_b128 v[94:97], v119 offset:6144
	ds_read_b128 v[98:101], v120 offset:16384
	s_setprio 1
	s_waitcnt lgkmcnt(0)
	v_mfma_f32_16x16x32_bf16 v[82:85], v[98:101], v[82:85], 0
	v_mfma_f32_16x16x32_bf16 v[86:89], v[98:101], v[86:89], 0
	v_mfma_f32_16x16x32_bf16 v[90:93], v[98:101], v[90:93], 0
	v_mfma_f32_16x16x32_bf16 v[94:97], v[98:101], v[94:97], 0
	s_setprio 0
	ds_read_b128 v[98:101], v121
	ds_read_b128 v[102:105], v121 offset:2048
	ds_read_b128 v[106:109], v121 offset:4096
	ds_read_b128 v[110:113], v121 offset:6144
	ds_read_b128 v[114:117], v122 offset:16384
	s_setprio 1
	s_waitcnt lgkmcnt(0)
	v_mfma_f32_16x16x32_bf16 v[82:85], v[114:117], v[98:101], v[82:85]
	v_mfma_f32_16x16x32_bf16 v[86:89], v[114:117], v[102:105], v[86:89]
	v_mfma_f32_16x16x32_bf16 v[90:93], v[114:117], v[106:109], v[90:93]
	v_mfma_f32_16x16x32_bf16 v[94:97], v[114:117], v[110:113], v[94:97]
	s_setprio 0
	s_waitcnt vmcnt(9)
	ds_write_b128 v118, v[0:3] offset:32768
	s_waitcnt vmcnt(8)
	ds_write_b128 v118, v[4:7] offset:36864
	s_waitcnt vmcnt(7)
	ds_write_b128 v118, v[8:11] offset:40960
	s_waitcnt vmcnt(6)
	ds_write_b128 v118, v[12:15] offset:45056
	s_waitcnt vmcnt(5)
	ds_write_b128 v118, v[16:19] offset:49152
	s_waitcnt lgkmcnt(0)
	s_barrier
	global_load_dwordx4 v[0:3], v[44:45], off offset:384
	global_load_dwordx4 v[4:7], v[46:47], off offset:384
	global_load_dwordx4 v[8:11], v[48:49], off offset:384
	global_load_dwordx4 v[12:15], v[42:43], off offset:384
	global_load_dwordx4 v[16:19], v[40:41], off offset:384
	ds_read_b128 v[40:43], v119 offset:32768
	ds_read_b128 v[44:47], v119 offset:34816
	ds_read_b128 v[98:101], v119 offset:36864
	ds_read_b128 v[102:105], v119 offset:38912
	ds_read_b128 v[106:109], v120 offset:49152
	s_setprio 1
	s_waitcnt lgkmcnt(0)
	v_mfma_f32_16x16x32_bf16 v[40:43], v[106:109], v[40:43], v[82:85]
	v_mfma_f32_16x16x32_bf16 v[44:47], v[106:109], v[44:47], v[86:89]
	v_mfma_f32_16x16x32_bf16 v[82:85], v[106:109], v[98:101], v[90:93]
	v_mfma_f32_16x16x32_bf16 v[86:89], v[106:109], v[102:105], v[94:97]
	s_setprio 0
	s_nop 0
	ds_read_b128 v[90:93], v121 offset:32768
	ds_read_b128 v[94:97], v121 offset:34816
	ds_read_b128 v[98:101], v121 offset:36864
	ds_read_b128 v[102:105], v121 offset:38912
	ds_read_b128 v[106:109], v122 offset:49152
	s_setprio 1
	s_waitcnt lgkmcnt(0)
	v_mfma_f32_16x16x32_bf16 v[40:43], v[106:109], v[90:93], v[40:43]
	v_mfma_f32_16x16x32_bf16 v[44:47], v[106:109], v[94:97], v[44:47]
	v_mfma_f32_16x16x32_bf16 v[82:85], v[106:109], v[98:101], v[82:85]
	v_mfma_f32_16x16x32_bf16 v[86:89], v[106:109], v[102:105], v[86:89]
	s_setprio 0
	s_waitcnt vmcnt(9)
	ds_write_b128 v118, v[20:23]
	s_waitcnt vmcnt(8)
	ds_write_b128 v118, v[24:27] offset:4096
	s_waitcnt vmcnt(7)
	ds_write_b128 v118, v[28:31] offset:8192
	s_waitcnt vmcnt(6)
	ds_write_b128 v118, v[32:35] offset:12288
	s_waitcnt vmcnt(5)
	ds_write_b128 v118, v[36:39] offset:16384
	s_waitcnt lgkmcnt(0)
	s_barrier
	ds_read_b128 v[20:23], v119
	ds_read_b128 v[24:27], v119 offset:2048
	ds_read_b128 v[28:31], v119 offset:4096
	ds_read_b128 v[32:35], v119 offset:6144
	ds_read_b128 v[36:39], v120 offset:16384
	s_setprio 1
	s_waitcnt lgkmcnt(0)
	v_mfma_f32_16x16x32_bf16 v[20:23], v[36:39], v[20:23], v[40:43]
	v_mfma_f32_16x16x32_bf16 v[24:27], v[36:39], v[24:27], v[44:47]
	v_mfma_f32_16x16x32_bf16 v[28:31], v[36:39], v[28:31], v[82:85]
	v_mfma_f32_16x16x32_bf16 v[32:35], v[36:39], v[32:35], v[86:89]
	s_setprio 0
	ds_read_b128 v[36:39], v121
	ds_read_b128 v[40:43], v121 offset:2048
	ds_read_b128 v[44:47], v121 offset:4096
	ds_read_b128 v[82:85], v121 offset:6144
	ds_read_b128 v[86:89], v122 offset:16384
	s_setprio 1
	s_waitcnt lgkmcnt(0)
	v_mfma_f32_16x16x32_bf16 v[20:23], v[86:89], v[36:39], v[20:23]
	v_mfma_f32_16x16x32_bf16 v[24:27], v[86:89], v[40:43], v[24:27]
	v_mfma_f32_16x16x32_bf16 v[28:31], v[86:89], v[44:47], v[28:31]
	v_mfma_f32_16x16x32_bf16 v[32:35], v[86:89], v[82:85], v[32:35]
	s_setprio 0
	s_waitcnt vmcnt(1)
	ds_write_b128 v118, v[12:15] offset:32768
	ds_write_b128 v118, v[0:3] offset:36864
	ds_write_b128 v118, v[4:7] offset:40960
	ds_write_b128 v118, v[8:11] offset:45056
	s_waitcnt vmcnt(0)
	ds_write_b128 v118, v[16:19] offset:49152
	s_waitcnt lgkmcnt(0)
	s_barrier
; #define GLOAD(ra, rb, koff)                                                        \
;   {                                                                                \
;     _Pragma("unroll") for (int j = 0; j < 4; j++) ra[j] = *(const u32x4*)(pa + j * sa32 + (koff));   \
;     _Pragma("unroll") for (int j = 0; j < NB_; j++) rb[j] = *(const u32x4*)(pbv[j] + (koff));         \
;   }
; template <int NT, bool PRE> ...
;     ...
;   if (!PRE) {
;     GLOAD(ra0, rb0, 0);
;     GLOAD(ra1, rb1, 64);
;   }
;   __syncthreads();
;   for (int k0 = 0; k0 < K; k0 += 128) {
;     LSTORE(ra0, rb0, 0);
;     __syncthreads();
;     GLOAD(ra0, rb0, min(k0 + 128, K - 128));
;     __builtin_amdgcn_sched_barrier(0);
;     COMPUTE(0);
;     LSTORE(ra1, rb1, 1);
;     __syncthreads();
;     GLOAD(ra1, rb1, min(k0 + 192, K - 64));
;     __builtin_amdgcn_sched_barrier(0);
;     COMPUTE(1);
;   }
; template <int NT>
; __device__ __forceinline__ void gemm_main(const u16* __restrict__ A, int lda, const u16* __restrict__ Bt, int ldb,
;                                           int K, int m0, int n0, f32x4 (&acc)[4][NT], u16* sA, u16* sB) {
;   const int tid = TID();
;   const u16* pa = A + (size_t)(m0 + (tid >> 3)) * lda + (tid & 7) * 8;
;   const u16* pbv[NT];
; #pragma unroll
;   for (int j = 0; j < NT; j++) pbv[j] = Bt + (size_t)(n0 + (tid >> 3) + 32 * j) * ldb + (tid & 7) * 8;
;   gemm_core<NT>(pa, (size_t)32 * lda, pbv, K, acc, sA, sB, tid);
	ds_read_b128 v[0:3], v119 offset:32768
	ds_read_b128 v[4:7], v119 offset:34816
	ds_read_b128 v[8:11], v119 offset:36864
	ds_read_b128 v[12:15], v119 offset:38912
	ds_read_b128 v[16:19], v120 offset:49152
	s_setprio 1
	s_waitcnt lgkmcnt(0)
	v_mfma_f32_16x16x32_bf16 v[0:3], v[16:19], v[0:3], v[20:23]
	v_mfma_f32_16x16x32_bf16 v[4:7], v[16:19], v[4:7], v[24:27]
	v_mfma_f32_16x16x32_bf16 v[20:23], v[16:19], v[8:11], v[28:31]
	v_mfma_f32_16x16x32_bf16 v[16:19], v[16:19], v[12:15], v[32:35]
	s_setprio 0
	ds_read_b128 v[8:11], v121 offset:32768
	ds_read_b128 v[24:27], v121 offset:34816
	ds_read_b128 v[28:31], v121 offset:36864
	ds_read_b128 v[32:35], v121 offset:38912
	ds_read_b128 v[36:39], v122 offset:49152
	s_setprio 1
	s_waitcnt lgkmcnt(0)
	v_mfma_f32_16x16x32_bf16 v[12:15], v[36:39], v[8:11], v[0:3]
	v_mfma_f32_16x16x32_bf16 v[8:11], v[36:39], v[24:27], v[4:7]
	v_mfma_f32_16x16x32_bf16 v[4:7], v[36:39], v[28:31], v[20:23]
	v_mfma_f32_16x16x32_bf16 v[0:3], v[36:39], v[32:35], v[16:19]
	s_setprio 0
	v_mov_b32_e32 v90, v169
	s_nop 0
	v_ashrrev_i32_e32 v20, 3, v90
	v_lshlrev_b32_e32 v36, 4, v90
	v_add_u32_e32 v18, s20, v20
	v_and_b32_e32 v130, 0x70, v36
	v_ashrrev_i32_e32 v19, 31, v18
	v_lshl_add_u64 v[16:17], s[8:9], 0, v[130:131]
	v_lshlrev_b64 v[18:19], 9, v[18:19]
	v_lshl_add_u64 v[48:49], v[16:17], 0, v[18:19]
	v_add_u32_e32 v16, s19, v20
	v_ashrrev_i32_e32 v17, 31, v16
	v_lshlrev_b64 v[16:17], 11, v[16:17]
	v_lshl_add_u64 v[16:17], s[6:7], 0, v[16:17]
	v_lshl_add_u64 v[126:127], v[16:17], 0, v[130:131]
	v_add_co_u32_e32 v136, vcc, s33, v126
	global_load_dwordx4 v[16:19], v[126:127], off
	s_nop 0
	v_addc_co_u32_e32 v137, vcc, 0, v127, vcc
	v_add_co_u32_e32 v138, vcc, s56, v126
	global_load_dwordx4 v[20:23], v[136:137], off
	s_nop 0
	v_addc_co_u32_e32 v139, vcc, 0, v127, vcc
	global_load_dwordx4 v[24:27], v[138:139], off
	global_load_dwordx4 v[28:31], v[48:49], off
	v_add_co_u32_e32 v140, vcc, s57, v126
	v_lshrrev_b32_e32 v91, 4, v90
	s_nop 0
	v_addc_co_u32_e32 v141, vcc, 0, v127, vcc
	global_load_dwordx4 v[32:35], v[140:141], off
	v_xor_b32_e32 v37, v91, v90
	v_lshlrev_b32_e32 v37, 4, v37
	v_and_b32_e32 v37, 0x70, v37
	v_and_or_b32 v130, v36, s22, v37
	global_load_dwordx4 v[36:39], v[48:49], off offset:128
	global_load_dwordx4 v[40:43], v[126:127], off offset:128
	global_load_dwordx4 v[44:47], v[136:137], off offset:128
	global_load_dwordx4 v[82:85], v[138:139], off offset:128
	global_load_dwordx4 v[86:89], v[140:141], off offset:128
	s_barrier
	v_and_b32_e32 v92, 15, v90
	v_bfe_u32 v93, v90, 1, 3
	v_bfe_u32 v94, v90, 4, 2
	v_lshlrev_b32_e32 v95, 5, v90
	v_lshlrev_b32_e32 v92, 7, v92
	v_bitop3_b32 v91, v91, v93, 3 bitop3:0x6c
	v_lshlrev_b32_e32 v90, 6, v90
	v_and_or_b32 v95, v95, s21, v92
	v_lshlrev_b32_e32 v91, 4, v91
	v_and_b32_e32 v90, 0xffffe000, v90
	v_or3_b32 v142, v91, v90, v92
	v_or_b32_e32 v143, v95, v91
	v_bitop3_b32 v91, v94, v93, 4 bitop3:0x36
	v_lshlrev_b32_e32 v91, 4, v91
	v_or3_b32 v144, v91, v90, v92
	v_or_b32_e32 v145, v95, v91
	s_waitcnt vmcnt(6)
	ds_write_b128 v130, v[28:31] offset:16384
	ds_write_b128 v130, v[16:19]
	ds_write_b128 v130, v[20:23] offset:4096
	ds_write_b128 v130, v[24:27] offset:8192
	s_waitcnt vmcnt(5)
	ds_write_b128 v130, v[32:35] offset:12288
	s_waitcnt lgkmcnt(0)
	s_barrier
	global_load_dwordx4 v[16:19], v[136:137], off offset:256
	global_load_dwordx4 v[20:23], v[138:139], off offset:256
	global_load_dwordx4 v[24:27], v[140:141], off offset:256
	global_load_dwordx4 v[28:31], v[126:127], off offset:256
	global_load_dwordx4 v[32:35], v[48:49], off offset:256
	ds_read_b128 v[90:93], v142
	ds_read_b128 v[94:97], v142 offset:2048
	ds_read_b128 v[98:101], v142 offset:4096
	ds_read_b128 v[102:105], v142 offset:6144
	ds_read_b128 v[106:109], v143 offset:16384
	s_setprio 1
	s_waitcnt lgkmcnt(0)
	v_mfma_f32_16x16x32_bf16 v[90:93], v[106:109], v[90:93], 0
	v_mfma_f32_16x16x32_bf16 v[94:97], v[106:109], v[94:97], 0
	v_mfma_f32_16x16x32_bf16 v[98:101], v[106:109], v[98:101], 0
	v_mfma_f32_16x16x32_bf16 v[102:105], v[106:109], v[102:105], 0
	s_setprio 0
	ds_read_b128 v[106:109], v144
	ds_read_b128 v[110:113], v144 offset:2048
	ds_read_b128 v[114:117], v144 offset:4096
	ds_read_b128 v[118:121], v144 offset:6144
	ds_read_b128 v[122:125], v145 offset:16384
	s_setprio 1
	s_waitcnt lgkmcnt(0)
	v_mfma_f32_16x16x32_bf16 v[90:93], v[122:125], v[106:109], v[90:93]
	v_mfma_f32_16x16x32_bf16 v[94:97], v[122:125], v[110:113], v[94:97]
	v_mfma_f32_16x16x32_bf16 v[98:101], v[122:125], v[114:117], v[98:101]
	v_mfma_f32_16x16x32_bf16 v[102:105], v[122:125], v[118:121], v[102:105]
	s_setprio 0
	s_waitcnt vmcnt(8)
	ds_write_b128 v130, v[40:43] offset:32768
	s_waitcnt vmcnt(7)
	ds_write_b128 v130, v[44:47] offset:36864
	s_waitcnt vmcnt(6)
	ds_write_b128 v130, v[82:85] offset:40960
	s_waitcnt vmcnt(5)
	ds_write_b128 v130, v[86:89] offset:45056
	ds_write_b128 v130, v[36:39] offset:49152
	s_waitcnt lgkmcnt(0)
	s_barrier
; #define GLOAD(ra, rb, koff)                                                        \
;   {                                                                                \
;     _Pragma("unroll") for (int j = 0; j < 4; j++) ra[j] = *(const u32x4*)(pa + j * sa32 + (koff));   \
;     _Pragma("unroll") for (int j = 0; j < NB_; j++) rb[j] = *(const u32x4*)(pbv[j] + (koff));         \
;   }
; template <int NT, bool PRE> ...
;     ...
;   if (!PRE) {
;     GLOAD(ra0, rb0, 0);
;     GLOAD(ra1, rb1, 64);
;   }
;   __syncthreads();
;   for (int k0 = 0; k0 < K; k0 += 128) {
;     LSTORE(ra0, rb0, 0);
;     __syncthreads();
;     GLOAD(ra0, rb0, min(k0 + 128, K - 128));
;     __builtin_amdgcn_sched_barrier(0);
;     COMPUTE(0);
;     LSTORE(ra1, rb1, 1);
;     __syncthreads();
;     GLOAD(ra1, rb1, min(k0 + 192, K - 64));
;     __builtin_amdgcn_sched_barrier(0);
;     COMPUTE(1);
;   }
; template <int NT>
; __device__ __forceinline__ void gemm_main(const u16* __restrict__ A, int lda, const u16* __restrict__ Bt, int ldb,
;                                           int K, int m0, int n0, f32x4 (&acc)[4][NT], u16* sA, u16* sB) {
;   const int tid = TID();
;   const u16* pa = A + (size_t)(m0 + (tid >> 3)) * lda + (tid & 7) * 8;
;   const u16* pbv[NT];
; #pragma unroll
;   for (int j = 0; j < NT; j++) pbv[j] = Bt + (size_t)(n0 + (tid >> 3) + 32 * j) * ldb + (tid & 7) * 8;
;   gemm_core<NT>(pa, (size_t)32 * lda, pbv, K, acc, sA, sB, tid);
	global_load_dwordx4 v[36:39], v[136:137], off offset:384
	global_load_dwordx4 v[40:43], v[138:139], off offset:384
	global_load_dwordx4 v[44:47], v[140:141], off offset:384
	global_load_dwordx4 v[82:85], v[126:127], off offset:384
	global_load_dwordx4 v[86:89], v[48:49], off offset:384
	ds_read_b128 v[106:109], v142 offset:32768
	ds_read_b128 v[110:113], v142 offset:34816
	ds_read_b128 v[114:117], v142 offset:36864
	ds_read_b128 v[118:121], v142 offset:38912
	ds_read_b128 v[122:125], v143 offset:49152
	s_setprio 1
	s_waitcnt lgkmcnt(0)
	v_mfma_f32_16x16x32_bf16 v[90:93], v[122:125], v[106:109], v[90:93]
	v_mfma_f32_16x16x32_bf16 v[94:97], v[122:125], v[110:113], v[94:97]
	v_mfma_f32_16x16x32_bf16 v[98:101], v[122:125], v[114:117], v[98:101]
	v_mfma_f32_16x16x32_bf16 v[102:105], v[122:125], v[118:121], v[102:105]
	s_setprio 0
	ds_read_b128 v[106:109], v144 offset:32768
	ds_read_b128 v[110:113], v144 offset:34816
	ds_read_b128 v[114:117], v144 offset:36864
	ds_read_b128 v[118:121], v144 offset:38912
	ds_read_b128 v[122:125], v145 offset:49152
	s_setprio 1
	s_waitcnt lgkmcnt(0)
	v_mfma_f32_16x16x32_bf16 v[90:93], v[122:125], v[106:109], v[90:93]
	v_mfma_f32_16x16x32_bf16 v[94:97], v[122:125], v[110:113], v[94:97]
	v_mfma_f32_16x16x32_bf16 v[98:101], v[122:125], v[114:117], v[98:101]
	v_mfma_f32_16x16x32_bf16 v[102:105], v[122:125], v[118:121], v[102:105]
	s_setprio 0
	s_waitcnt vmcnt(6)
	ds_write_b128 v130, v[28:31]
	ds_write_b128 v130, v[16:19] offset:4096
	ds_write_b128 v130, v[20:23] offset:8192
	ds_write_b128 v130, v[24:27] offset:12288
	s_waitcnt vmcnt(5)
	ds_write_b128 v130, v[32:35] offset:16384
	s_waitcnt lgkmcnt(0)
	s_barrier
	ds_read_b128 v[16:19], v142
	ds_read_b128 v[20:23], v142 offset:2048
	ds_read_b128 v[24:27], v142 offset:4096
	ds_read_b128 v[28:31], v142 offset:6144
	ds_read_b128 v[32:35], v143 offset:16384
	s_setprio 1
	s_waitcnt lgkmcnt(0)
	v_mfma_f32_16x16x32_bf16 v[16:19], v[32:35], v[16:19], v[90:93]
	v_mfma_f32_16x16x32_bf16 v[20:23], v[32:35], v[20:23], v[94:97]
	v_mfma_f32_16x16x32_bf16 v[24:27], v[32:35], v[24:27], v[98:101]
	v_mfma_f32_16x16x32_bf16 v[28:31], v[32:35], v[28:31], v[102:105]
	s_setprio 0
	ds_read_b128 v[32:35], v144
	ds_read_b128 v[90:93], v144 offset:2048
	ds_read_b128 v[94:97], v144 offset:4096
	ds_read_b128 v[98:101], v144 offset:6144
	ds_read_b128 v[102:105], v145 offset:16384
	s_setprio 1
	s_waitcnt lgkmcnt(0)
	v_mfma_f32_16x16x32_bf16 v[16:19], v[102:105], v[32:35], v[16:19]
	v_mfma_f32_16x16x32_bf16 v[20:23], v[102:105], v[90:93], v[20:23]
	v_mfma_f32_16x16x32_bf16 v[24:27], v[102:105], v[94:97], v[24:27]
	v_mfma_f32_16x16x32_bf16 v[28:31], v[102:105], v[98:101], v[28:31]
	s_setprio 0
	s_waitcnt vmcnt(1)
	ds_write_b128 v130, v[82:85] offset:32768
	ds_write_b128 v130, v[36:39] offset:36864
	ds_write_b128 v130, v[40:43] offset:40960
	ds_write_b128 v130, v[44:47] offset:45056
	s_waitcnt vmcnt(0)
	ds_write_b128 v130, v[86:89] offset:49152
	s_waitcnt lgkmcnt(0)
	s_barrier
	ds_read_b128 v[32:35], v142 offset:32768
	ds_read_b128 v[36:39], v142 offset:34816
	ds_read_b128 v[40:43], v142 offset:36864
	ds_read_b128 v[44:47], v142 offset:38912
	ds_read_b128 v[82:85], v143 offset:49152
	s_setprio 1
	s_waitcnt lgkmcnt(0)
	v_mfma_f32_16x16x32_bf16 v[16:19], v[82:85], v[32:35], v[16:19]
	v_mfma_f32_16x16x32_bf16 v[20:23], v[82:85], v[36:39], v[20:23]
	v_mfma_f32_16x16x32_bf16 v[32:35], v[82:85], v[40:43], v[24:27]
	v_mfma_f32_16x16x32_bf16 v[36:39], v[82:85], v[44:47], v[28:31]
	s_setprio 0
	s_nop 0
	ds_read_b128 v[24:27], v144 offset:32768
	ds_read_b128 v[40:43], v144 offset:34816
	ds_read_b128 v[44:47], v144 offset:36864
	ds_read_b128 v[82:85], v144 offset:38912
	ds_read_b128 v[86:89], v145 offset:49152
	s_setprio 1
	s_waitcnt lgkmcnt(0)
	v_mfma_f32_16x16x32_bf16 v[28:31], v[86:89], v[24:27], v[16:19]
	v_mfma_f32_16x16x32_bf16 v[24:27], v[86:89], v[40:43], v[20:23]
	v_mfma_f32_16x16x32_bf16 v[20:23], v[86:89], v[44:47], v[32:35]
	v_mfma_f32_16x16x32_bf16 v[16:19], v[86:89], v[82:85], v[36:39]
	s_setprio 0
	v_mov_b32_e32 v106, v169
	s_nop 0
	v_ashrrev_i32_e32 v36, 3, v106
	v_lshlrev_b32_e32 v86, 4, v106
	v_add_u32_e32 v34, s20, v36
	v_and_b32_e32 v130, 0x70, v86
	v_ashrrev_i32_e32 v35, 31, v34
	v_lshl_add_u64 v[32:33], s[12:13], 0, v[130:131]
	v_lshlrev_b64 v[34:35], 9, v[34:35]
	v_lshl_add_u64 v[48:49], v[32:33], 0, v[34:35]
	v_add_u32_e32 v32, s19, v36
	v_ashrrev_i32_e32 v33, 31, v32
	v_lshlrev_b64 v[32:33], 11, v[32:33]
	v_lshl_add_u64 v[32:33], s[10:11], 0, v[32:33]
	v_lshl_add_u64 v[126:127], v[32:33], 0, v[130:131]
	v_add_co_u32_e32 v144, vcc, s33, v126
	global_load_dwordx4 v[32:35], v[126:127], off
	s_nop 0
	v_addc_co_u32_e32 v145, vcc, 0, v127, vcc
	v_add_co_u32_e32 v166, vcc, s56, v126
	global_load_dwordx4 v[36:39], v[144:145], off
	s_nop 0
	v_addc_co_u32_e32 v167, vcc, 0, v127, vcc
	global_load_dwordx4 v[40:43], v[166:167], off
	global_load_dwordx4 v[44:47], v[48:49], off
	v_add_co_u32_e32 v198, vcc, s57, v126
	v_lshrrev_b32_e32 v107, 4, v106
	s_nop 0
	v_addc_co_u32_e32 v199, vcc, 0, v127, vcc
	global_load_dwordx4 v[82:85], v[198:199], off
	v_xor_b32_e32 v87, v107, v106
	v_lshlrev_b32_e32 v87, 4, v87
	v_and_b32_e32 v87, 0x70, v87
	v_and_or_b32 v130, v86, s22, v87
	global_load_dwordx4 v[86:89], v[48:49], off offset:128
	global_load_dwordx4 v[90:93], v[126:127], off offset:128
	global_load_dwordx4 v[94:97], v[144:145], off offset:128
	global_load_dwordx4 v[98:101], v[166:167], off offset:128
	global_load_dwordx4 v[102:105], v[198:199], off offset:128
	s_barrier
; #define GLOAD(ra, rb, koff)                                                        \
;   {                                                                                \
;     _Pragma("unroll") for (int j = 0; j < 4; j++) ra[j] = *(const u32x4*)(pa + j * sa32 + (koff));   \
;     _Pragma("unroll") for (int j = 0; j < NB_; j++) rb[j] = *(const u32x4*)(pbv[j] + (koff));         \
;   }
; template <int NT, bool PRE> ...
;     ...
;   if (!PRE) {
;     GLOAD(ra0, rb0, 0);
;     GLOAD(ra1, rb1, 64);
;   }
;   __syncthreads();
;   for (int k0 = 0; k0 < K; k0 += 128) {
;     LSTORE(ra0, rb0, 0);
;     __syncthreads();
;     GLOAD(ra0, rb0, min(k0 + 128, K - 128));
;     __builtin_amdgcn_sched_barrier(0);
;     COMPUTE(0);
;     LSTORE(ra1, rb1, 1);
;     __syncthreads();
;     GLOAD(ra1, rb1, min(k0 + 192, K - 64));
;     __builtin_amdgcn_sched_barrier(0);
;     COMPUTE(1);
;   }
	v_and_b32_e32 v108, 15, v106
	v_bfe_u32 v109, v106, 1, 3
	v_bfe_u32 v110, v106, 4, 2
	v_lshlrev_b32_e32 v111, 5, v106
	v_lshlrev_b32_e32 v108, 7, v108
	v_bitop3_b32 v107, v107, v109, 3 bitop3:0x6c
	v_lshlrev_b32_e32 v106, 6, v106
	v_and_or_b32 v111, v111, s21, v108
	v_lshlrev_b32_e32 v107, 4, v107
	v_and_b32_e32 v106, 0xffffe000, v106
	v_or3_b32 v157, v107, v106, v108
	v_or_b32_e32 v168, v111, v107
	v_bitop3_b32 v107, v110, v109, 4 bitop3:0x36
	v_lshlrev_b32_e32 v107, 4, v107
	v_or3_b32 v197, v107, v106, v108
	v_or_b32_e32 v200, v111, v107
	s_waitcnt vmcnt(6)
	ds_write_b128 v130, v[44:47] offset:16384
	ds_write_b128 v130, v[32:35]
	ds_write_b128 v130, v[36:39] offset:4096
	ds_write_b128 v130, v[40:43] offset:8192
	s_waitcnt vmcnt(5)
	ds_write_b128 v130, v[82:85] offset:12288
	s_waitcnt lgkmcnt(0)
	s_barrier
	global_load_dwordx4 v[32:35], v[144:145], off offset:256
	global_load_dwordx4 v[36:39], v[166:167], off offset:256
	global_load_dwordx4 v[40:43], v[198:199], off offset:256
	global_load_dwordx4 v[44:47], v[126:127], off offset:256
	global_load_dwordx4 v[82:85], v[48:49], off offset:256
	ds_read_b128 v[106:109], v157
	ds_read_b128 v[110:113], v157 offset:2048
	ds_read_b128 v[114:117], v157 offset:4096
	ds_read_b128 v[118:121], v157 offset:6144
	ds_read_b128 v[122:125], v168 offset:16384
	s_setprio 1
	s_waitcnt lgkmcnt(0)
	v_mfma_f32_16x16x32_bf16 v[106:109], v[122:125], v[106:109], 0
	v_mfma_f32_16x16x32_bf16 v[110:113], v[122:125], v[110:113], 0
	v_mfma_f32_16x16x32_bf16 v[114:117], v[122:125], v[114:117], 0
	v_mfma_f32_16x16x32_bf16 v[118:121], v[122:125], v[118:121], 0
	s_setprio 0
	ds_read_b128 v[122:125], v197
	ds_read_b128 v[136:139], v197 offset:2048
	ds_read_b128 v[140:143], v197 offset:4096
	ds_read_b128 v[158:161], v197 offset:6144
	ds_read_b128 v[162:165], v200 offset:16384
	s_setprio 1
	s_waitcnt lgkmcnt(0)
	v_mfma_f32_16x16x32_bf16 v[106:109], v[162:165], v[122:125], v[106:109]
	v_mfma_f32_16x16x32_bf16 v[110:113], v[162:165], v[136:139], v[110:113]
	v_mfma_f32_16x16x32_bf16 v[114:117], v[162:165], v[140:143], v[114:117]
	v_mfma_f32_16x16x32_bf16 v[118:121], v[162:165], v[158:161], v[118:121]
	s_setprio 0
	s_waitcnt vmcnt(8)
	ds_write_b128 v130, v[90:93] offset:32768
	s_waitcnt vmcnt(7)
	ds_write_b128 v130, v[94:97] offset:36864
	s_waitcnt vmcnt(6)
	ds_write_b128 v130, v[98:101] offset:40960
	s_waitcnt vmcnt(5)
	ds_write_b128 v130, v[102:105] offset:45056
	ds_write_b128 v130, v[86:89] offset:49152
	s_waitcnt lgkmcnt(0)
	s_barrier
	global_load_dwordx4 v[86:89], v[144:145], off offset:384
	global_load_dwordx4 v[90:93], v[166:167], off offset:384
	global_load_dwordx4 v[94:97], v[198:199], off offset:384
	global_load_dwordx4 v[98:101], v[126:127], off offset:384
	global_load_dwordx4 v[102:105], v[48:49], off offset:384
	ds_read_b128 v[122:125], v157 offset:32768
	ds_read_b128 v[136:139], v157 offset:34816
	ds_read_b128 v[140:143], v157 offset:36864
	ds_read_b128 v[158:161], v157 offset:38912
	ds_read_b128 v[162:165], v168 offset:49152
	s_setprio 1
	s_waitcnt lgkmcnt(0)
	v_mfma_f32_16x16x32_bf16 v[106:109], v[162:165], v[122:125], v[106:109]
	v_mfma_f32_16x16x32_bf16 v[110:113], v[162:165], v[136:139], v[110:113]
	v_mfma_f32_16x16x32_bf16 v[114:117], v[162:165], v[140:143], v[114:117]
	v_mfma_f32_16x16x32_bf16 v[118:121], v[162:165], v[158:161], v[118:121]
	s_setprio 0
	ds_read_b128 v[122:125], v197 offset:32768
	ds_read_b128 v[136:139], v197 offset:34816
	ds_read_b128 v[140:143], v197 offset:36864
	ds_read_b128 v[158:161], v197 offset:38912
	ds_read_b128 v[162:165], v200 offset:49152
	s_setprio 1
	s_waitcnt lgkmcnt(0)
	v_mfma_f32_16x16x32_bf16 v[106:109], v[162:165], v[122:125], v[106:109]
	v_mfma_f32_16x16x32_bf16 v[110:113], v[162:165], v[136:139], v[110:113]
	v_mfma_f32_16x16x32_bf16 v[114:117], v[162:165], v[140:143], v[114:117]
	v_mfma_f32_16x16x32_bf16 v[118:121], v[162:165], v[158:161], v[118:121]
	s_setprio 0
	s_waitcnt vmcnt(6)
	ds_write_b128 v130, v[44:47]
	ds_write_b128 v130, v[32:35] offset:4096
	ds_write_b128 v130, v[36:39] offset:8192
	ds_write_b128 v130, v[40:43] offset:12288
	s_waitcnt vmcnt(5)
	ds_write_b128 v130, v[82:85] offset:16384
	s_waitcnt lgkmcnt(0)
	s_barrier
	ds_read_b128 v[32:35], v157
	ds_read_b128 v[36:39], v157 offset:2048
	ds_read_b128 v[40:43], v157 offset:4096
	ds_read_b128 v[44:47], v157 offset:6144
	ds_read_b128 v[82:85], v168 offset:16384
	s_setprio 1
	s_waitcnt lgkmcnt(0)
	v_mfma_f32_16x16x32_bf16 v[32:35], v[82:85], v[32:35], v[106:109]
	v_mfma_f32_16x16x32_bf16 v[36:39], v[82:85], v[36:39], v[110:113]
	v_mfma_f32_16x16x32_bf16 v[40:43], v[82:85], v[40:43], v[114:117]
	v_mfma_f32_16x16x32_bf16 v[44:47], v[82:85], v[44:47], v[118:121]
	s_setprio 0
	ds_read_b128 v[82:85], v197
	ds_read_b128 v[106:109], v197 offset:2048
	ds_read_b128 v[110:113], v197 offset:4096
	ds_read_b128 v[114:117], v197 offset:6144
	ds_read_b128 v[118:121], v200 offset:16384
	s_setprio 1
	s_waitcnt lgkmcnt(0)
	v_mfma_f32_16x16x32_bf16 v[32:35], v[118:121], v[82:85], v[32:35]
	v_mfma_f32_16x16x32_bf16 v[36:39], v[118:121], v[106:109], v[36:39]
	v_mfma_f32_16x16x32_bf16 v[40:43], v[118:121], v[110:113], v[40:43]
	v_mfma_f32_16x16x32_bf16 v[44:47], v[118:121], v[114:117], v[44:47]
	s_setprio 0
	s_waitcnt vmcnt(1)
	ds_write_b128 v130, v[98:101] offset:32768
	ds_write_b128 v130, v[86:89] offset:36864
	ds_write_b128 v130, v[90:93] offset:40960
	ds_write_b128 v130, v[94:97] offset:45056
	s_waitcnt vmcnt(0)
	ds_write_b128 v130, v[102:105] offset:49152
	s_waitcnt lgkmcnt(0)
	s_barrier
; #define GLOAD(ra, rb, koff)                                                        \
;   {                                                                                \
;     _Pragma("unroll") for (int j = 0; j < 4; j++) ra[j] = *(const u32x4*)(pa + j * sa32 + (koff));   \
;     _Pragma("unroll") for (int j = 0; j < NB_; j++) rb[j] = *(const u32x4*)(pbv[j] + (koff));         \
;   }
; template <int NT, bool PRE> ...
;     ...
;   if (!PRE) {
;     GLOAD(ra0, rb0, 0);
;     GLOAD(ra1, rb1, 64);
;   }
;   __syncthreads();
;   for (int k0 = 0; k0 < K; k0 += 128) {
;     LSTORE(ra0, rb0, 0);
;     __syncthreads();
;     GLOAD(ra0, rb0, min(k0 + 128, K - 128));
;     __builtin_amdgcn_sched_barrier(0);
;     COMPUTE(0);
;     LSTORE(ra1, rb1, 1);
;     __syncthreads();
;     GLOAD(ra1, rb1, min(k0 + 192, K - 64));
;     __builtin_amdgcn_sched_barrier(0);
;     COMPUTE(1);
;   }
	ds_read_b128 v[82:85], v157 offset:32768
	ds_read_b128 v[86:89], v157 offset:34816
	ds_read_b128 v[90:93], v157 offset:36864
	ds_read_b128 v[94:97], v157 offset:38912
	ds_read_b128 v[98:101], v168 offset:49152
	s_setprio 1
	s_waitcnt lgkmcnt(0)
	v_mfma_f32_16x16x32_bf16 v[32:35], v[98:101], v[82:85], v[32:35]
	v_mfma_f32_16x16x32_bf16 v[36:39], v[98:101], v[86:89], v[36:39]
	v_mfma_f32_16x16x32_bf16 v[82:85], v[98:101], v[90:93], v[40:43]
	v_mfma_f32_16x16x32_bf16 v[86:89], v[98:101], v[94:97], v[44:47]
	s_setprio 0
	s_nop 0
	ds_read_b128 v[40:43], v197 offset:32768
	ds_read_b128 v[90:93], v197 offset:34816
	ds_read_b128 v[94:97], v197 offset:36864
	ds_read_b128 v[98:101], v197 offset:38912
	ds_read_b128 v[102:105], v200 offset:49152
	s_setprio 1
	s_waitcnt lgkmcnt(0)
	v_mfma_f32_16x16x32_bf16 v[44:47], v[102:105], v[40:43], v[32:35]
	v_mfma_f32_16x16x32_bf16 v[40:43], v[102:105], v[90:93], v[36:39]
	v_mfma_f32_16x16x32_bf16 v[36:39], v[102:105], v[94:97], v[82:85]
	v_mfma_f32_16x16x32_bf16 v[32:35], v[102:105], v[98:101], v[86:89]
	s_setprio 0
	v_mov_b32_e32 v122, v169
	s_nop 0
	v_ashrrev_i32_e32 v84, 3, v122
	v_lshlrev_b32_e32 v102, 4, v122
	v_add_u32_e32 v82, s20, v84
	v_and_b32_e32 v130, 0x70, v102
	v_ashrrev_i32_e32 v83, 31, v82
	v_lshl_add_u64 v[48:49], s[16:17], 0, v[130:131]
	v_lshlrev_b64 v[82:83], 9, v[82:83]
	v_lshl_add_u64 v[48:49], v[48:49], 0, v[82:83]
	v_add_u32_e32 v82, s19, v84
	v_ashrrev_i32_e32 v83, 31, v82
	v_lshlrev_b64 v[82:83], 11, v[82:83]
	v_lshl_add_u64 v[82:83], s[14:15], 0, v[82:83]
	v_lshl_add_u64 v[126:127], v[82:83], 0, v[130:131]
	v_add_co_u32_e32 v144, vcc, s33, v126
	global_load_dwordx4 v[82:85], v[126:127], off
	s_nop 0
	v_addc_co_u32_e32 v145, vcc, 0, v127, vcc
	v_add_co_u32_e32 v166, vcc, s56, v126
	global_load_dwordx4 v[86:89], v[144:145], off
	s_nop 0
	v_addc_co_u32_e32 v167, vcc, 0, v127, vcc
	global_load_dwordx4 v[90:93], v[166:167], off
	global_load_dwordx4 v[94:97], v[48:49], off
	v_add_co_u32_e32 v214, vcc, s57, v126
	v_lshrrev_b32_e32 v123, 4, v122
	s_nop 0
	v_addc_co_u32_e32 v215, vcc, 0, v127, vcc
	global_load_dwordx4 v[98:101], v[214:215], off
	v_xor_b32_e32 v103, v123, v122
	v_lshlrev_b32_e32 v103, 4, v103
	v_and_b32_e32 v103, 0x70, v103
	v_and_or_b32 v130, v102, s22, v103
	global_load_dwordx4 v[102:105], v[48:49], off offset:128
	global_load_dwordx4 v[106:109], v[126:127], off offset:128
	global_load_dwordx4 v[110:113], v[144:145], off offset:128
	global_load_dwordx4 v[114:117], v[166:167], off offset:128
	global_load_dwordx4 v[118:121], v[214:215], off offset:128
	s_barrier
	v_and_b32_e32 v124, 15, v122
	v_bfe_u32 v125, v122, 1, 3
	v_bfe_u32 v136, v122, 4, 2
	v_lshlrev_b32_e32 v137, 5, v122
	v_lshlrev_b32_e32 v124, 7, v124
	v_bitop3_b32 v123, v123, v125, 3 bitop3:0x6c
	v_lshlrev_b32_e32 v122, 6, v122
	v_and_or_b32 v137, v137, s21, v124
	v_lshlrev_b32_e32 v123, 4, v123
	v_and_b32_e32 v122, 0xffffe000, v122
	v_or3_b32 v157, v123, v122, v124
	v_or_b32_e32 v168, v137, v123
	v_bitop3_b32 v123, v136, v125, 4 bitop3:0x36
	v_lshlrev_b32_e32 v123, 4, v123
	v_or3_b32 v197, v123, v122, v124
	v_or_b32_e32 v216, v137, v123
	s_waitcnt vmcnt(6)
	ds_write_b128 v130, v[94:97] offset:16384
	ds_write_b128 v130, v[82:85]
	ds_write_b128 v130, v[86:89] offset:4096
	ds_write_b128 v130, v[90:93] offset:8192
	s_waitcnt vmcnt(5)
	ds_write_b128 v130, v[98:101] offset:12288
	s_waitcnt lgkmcnt(0)
	s_barrier
	global_load_dwordx4 v[82:85], v[144:145], off offset:256
	global_load_dwordx4 v[86:89], v[166:167], off offset:256
	global_load_dwordx4 v[90:93], v[214:215], off offset:256
	global_load_dwordx4 v[94:97], v[126:127], off offset:256
	global_load_dwordx4 v[98:101], v[48:49], off offset:256
	ds_read_b128 v[122:125], v157
	ds_read_b128 v[136:139], v157 offset:2048
	ds_read_b128 v[140:143], v157 offset:4096
	ds_read_b128 v[158:161], v157 offset:6144
	ds_read_b128 v[162:165], v168 offset:16384
	s_setprio 1
	s_waitcnt lgkmcnt(0)
	v_mfma_f32_16x16x32_bf16 v[122:125], v[162:165], v[122:125], 0
	v_mfma_f32_16x16x32_bf16 v[136:139], v[162:165], v[136:139], 0
	v_mfma_f32_16x16x32_bf16 v[140:143], v[162:165], v[140:143], 0
	v_mfma_f32_16x16x32_bf16 v[158:161], v[162:165], v[158:161], 0
	s_setprio 0
	ds_read_b128 v[162:165], v197
	ds_read_b128 v[198:201], v197 offset:2048
	ds_read_b128 v[202:205], v197 offset:4096
	ds_read_b128 v[206:209], v197 offset:6144
	ds_read_b128 v[210:213], v216 offset:16384
	s_setprio 1
	s_waitcnt lgkmcnt(0)
	v_mfma_f32_16x16x32_bf16 v[122:125], v[210:213], v[162:165], v[122:125]
	v_mfma_f32_16x16x32_bf16 v[136:139], v[210:213], v[198:201], v[136:139]
	v_mfma_f32_16x16x32_bf16 v[140:143], v[210:213], v[202:205], v[140:143]
	v_mfma_f32_16x16x32_bf16 v[158:161], v[210:213], v[206:209], v[158:161]
	s_setprio 0
	s_waitcnt vmcnt(8)
	ds_write_b128 v130, v[106:109] offset:32768
	s_waitcnt vmcnt(7)
	ds_write_b128 v130, v[110:113] offset:36864
	s_waitcnt vmcnt(6)
	ds_write_b128 v130, v[114:117] offset:40960
	s_waitcnt vmcnt(5)
	ds_write_b128 v130, v[118:121] offset:45056
	ds_write_b128 v130, v[102:105] offset:49152
	s_waitcnt lgkmcnt(0)
	s_barrier
; #define GLOAD(ra, rb, koff)                                                        \
;   {                                                                                \
;     _Pragma("unroll") for (int j = 0; j < 4; j++) ra[j] = *(const u32x4*)(pa + j * sa32 + (koff));   \
;     _Pragma("unroll") for (int j = 0; j < NB_; j++) rb[j] = *(const u32x4*)(pbv[j] + (koff));         \
;   }
; template <int NT, bool PRE> ...
;     ...
;   if (!PRE) {
;     GLOAD(ra0, rb0, 0);
;     GLOAD(ra1, rb1, 64);
;   }
;   __syncthreads();
;   for (int k0 = 0; k0 < K; k0 += 128) {
;     LSTORE(ra0, rb0, 0);
;     __syncthreads();
;     GLOAD(ra0, rb0, min(k0 + 128, K - 128));
;     __builtin_amdgcn_sched_barrier(0);
;     COMPUTE(0);
;     LSTORE(ra1, rb1, 1);
;     __syncthreads();
;     GLOAD(ra1, rb1, min(k0 + 192, K - 64));
;     __builtin_amdgcn_sched_barrier(0);
;     COMPUTE(1);
;   }
	global_load_dwordx4 v[102:105], v[144:145], off offset:384
	global_load_dwordx4 v[106:109], v[166:167], off offset:384
	global_load_dwordx4 v[110:113], v[214:215], off offset:384
	global_load_dwordx4 v[114:117], v[126:127], off offset:384
	global_load_dwordx4 v[118:121], v[48:49], off offset:384
	ds_read_b128 v[162:165], v157 offset:32768
	ds_read_b128 v[198:201], v157 offset:34816
	ds_read_b128 v[202:205], v157 offset:36864
	ds_read_b128 v[206:209], v157 offset:38912
	ds_read_b128 v[210:213], v168 offset:49152
	s_setprio 1
	s_waitcnt lgkmcnt(0)
	v_mfma_f32_16x16x32_bf16 v[122:125], v[210:213], v[162:165], v[122:125]
	v_mfma_f32_16x16x32_bf16 v[136:139], v[210:213], v[198:201], v[136:139]
	v_mfma_f32_16x16x32_bf16 v[140:143], v[210:213], v[202:205], v[140:143]
	v_mfma_f32_16x16x32_bf16 v[158:161], v[210:213], v[206:209], v[158:161]
	s_setprio 0
	ds_read_b128 v[162:165], v197 offset:32768
	ds_read_b128 v[198:201], v197 offset:34816
	ds_read_b128 v[202:205], v197 offset:36864
	ds_read_b128 v[206:209], v197 offset:38912
	ds_read_b128 v[210:213], v216 offset:49152
	s_setprio 1
	s_waitcnt lgkmcnt(0)
	v_mfma_f32_16x16x32_bf16 v[122:125], v[210:213], v[162:165], v[122:125]
	v_mfma_f32_16x16x32_bf16 v[136:139], v[210:213], v[198:201], v[136:139]
	v_mfma_f32_16x16x32_bf16 v[140:143], v[210:213], v[202:205], v[140:143]
	v_mfma_f32_16x16x32_bf16 v[158:161], v[210:213], v[206:209], v[158:161]
	s_setprio 0
	s_waitcnt vmcnt(6)
	ds_write_b128 v130, v[94:97]
	ds_write_b128 v130, v[82:85] offset:4096
	ds_write_b128 v130, v[86:89] offset:8192
	ds_write_b128 v130, v[90:93] offset:12288
	s_waitcnt vmcnt(5)
	ds_write_b128 v130, v[98:101] offset:16384
	s_waitcnt lgkmcnt(0)
	s_barrier
	ds_read_b128 v[82:85], v157
	ds_read_b128 v[86:89], v157 offset:2048
	ds_read_b128 v[90:93], v157 offset:4096
	ds_read_b128 v[94:97], v157 offset:6144
	ds_read_b128 v[98:101], v168 offset:16384
	s_setprio 1
	s_waitcnt lgkmcnt(0)
	v_mfma_f32_16x16x32_bf16 v[82:85], v[98:101], v[82:85], v[122:125]
	v_mfma_f32_16x16x32_bf16 v[86:89], v[98:101], v[86:89], v[136:139]
	v_mfma_f32_16x16x32_bf16 v[90:93], v[98:101], v[90:93], v[140:143]
	v_mfma_f32_16x16x32_bf16 v[94:97], v[98:101], v[94:97], v[158:161]
	s_setprio 0
	ds_read_b128 v[98:101], v197
	ds_read_b128 v[122:125], v197 offset:2048
	ds_read_b128 v[136:139], v197 offset:4096
	ds_read_b128 v[140:143], v197 offset:6144
	ds_read_b128 v[158:161], v216 offset:16384
	s_setprio 1
	s_waitcnt lgkmcnt(0)
	v_mfma_f32_16x16x32_bf16 v[82:85], v[158:161], v[98:101], v[82:85]
	v_mfma_f32_16x16x32_bf16 v[86:89], v[158:161], v[122:125], v[86:89]
	v_mfma_f32_16x16x32_bf16 v[90:93], v[158:161], v[136:139], v[90:93]
	v_mfma_f32_16x16x32_bf16 v[94:97], v[158:161], v[140:143], v[94:97]
	s_setprio 0
	s_waitcnt vmcnt(1)
	ds_write_b128 v130, v[114:117] offset:32768
	ds_write_b128 v130, v[102:105] offset:36864
	ds_write_b128 v130, v[106:109] offset:40960
	ds_write_b128 v130, v[110:113] offset:45056
	s_waitcnt vmcnt(0)
	ds_write_b128 v130, v[118:121] offset:49152
	s_waitcnt lgkmcnt(0)
	s_barrier
; __device__ __forceinline__ float bf2f(u16 h) { return __uint_as_float(((unsigned)h) << 16); }
; __device__ __forceinline__ void phase_merge(const Params& P, u16* sA, u16* sB) {
;     ...
; #pragma unroll
;       for (int mi = 0; mi < 4; mi++) {
;         u32x2 q = gp[mi][i];
;         macc[mi][0] += bf2f(q[0] & 0xffff) * ap[mi][0][0];
;         macc[mi][1] += bf2f(q[0] >> 16) * ap[mi][0][1];
;         macc[mi][2] += bf2f(q[1] & 0xffff) * ap[mi][0][2];
;         macc[mi][3] += bf2f(q[1] >> 16) * ap[mi][0][3];
;       }
;     }
;     const int col = n0 + ((tq >> 6) & 1) * 16 + ((tq & 63) >> 4) * 4;
; #pragma unroll
;     for (int mi = 0; mi < 4; mi++) {
;       int row = m0 + ((tq >> 6) >> 1) * 64 + mi * 16 + (tq & 15);
;       *(uint2*)(MM + (size_t)row * 1024 + col) = pack4(macc[mi]);
;     }
;   }
	ds_read_b128 v[98:101], v157 offset:32768
	ds_read_b128 v[102:105], v157 offset:34816
	ds_read_b128 v[106:109], v157 offset:36864
	ds_read_b128 v[110:113], v157 offset:38912
	ds_read_b128 v[114:117], v168 offset:49152
	s_setprio 1
	s_waitcnt lgkmcnt(0)
	v_mfma_f32_16x16x32_bf16 v[82:85], v[114:117], v[98:101], v[82:85]
	v_mfma_f32_16x16x32_bf16 v[86:89], v[114:117], v[102:105], v[86:89]
	v_mfma_f32_16x16x32_bf16 v[90:93], v[114:117], v[106:109], v[90:93]
	v_mfma_f32_16x16x32_bf16 v[94:97], v[114:117], v[110:113], v[94:97]
	s_setprio 0
	ds_read_b128 v[98:101], v197 offset:32768
	ds_read_b128 v[102:105], v197 offset:34816
	ds_read_b128 v[106:109], v197 offset:36864
	ds_read_b128 v[110:113], v197 offset:38912
	ds_read_b128 v[114:117], v216 offset:49152
	s_setprio 1
	s_waitcnt lgkmcnt(0)
	v_mfma_f32_16x16x32_bf16 v[82:85], v[114:117], v[98:101], v[82:85]
	v_mfma_f32_16x16x32_bf16 v[86:89], v[114:117], v[102:105], v[86:89]
	v_mfma_f32_16x16x32_bf16 v[90:93], v[114:117], v[106:109], v[90:93]
	v_mfma_f32_16x16x32_bf16 v[94:97], v[114:117], v[110:113], v[94:97]
	s_setprio 0
	v_and_b32_e32 v49, 0xffff0000, v60
	v_lshlrev_b32_e32 v48, 16, v60
	v_pk_fma_f32 v[12:13], v[12:13], v[48:49], 0 op_sel_hi:[1,1,0]
	v_and_b32_e32 v49, 0xffff0000, v56
	v_lshlrev_b32_e32 v48, 16, v56
	v_pk_fma_f32 v[12:13], v[28:29], v[48:49], v[12:13]
	v_and_b32_e32 v29, 0xffff0000, v52
	v_lshlrev_b32_e32 v28, 16, v52
	v_pk_fma_f32 v[12:13], v[44:45], v[28:29], v[12:13]
	v_and_b32_e32 v29, 0xffff0000, v54
	v_lshlrev_b32_e32 v28, 16, v54
	v_pk_fma_f32 v[12:13], v[82:83], v[28:29], v[12:13]
	v_and_b32_e32 v29, 0xffff0000, v61
	v_lshlrev_b32_e32 v28, 16, v61
	v_pk_fma_f32 v[14:15], v[14:15], v[28:29], 0 op_sel_hi:[1,1,0]
	v_and_b32_e32 v29, 0xffff0000, v57
	v_lshlrev_b32_e32 v28, 16, v57
	v_pk_fma_f32 v[14:15], v[30:31], v[28:29], v[14:15]
	v_and_b32_e32 v29, 0xffff0000, v53
	v_lshlrev_b32_e32 v28, 16, v53
	v_pk_fma_f32 v[14:15], v[46:47], v[28:29], v[14:15]
	v_and_b32_e32 v29, 0xffff0000, v50
	v_lshlrev_b32_e32 v28, 16, v50
	v_pk_fma_f32 v[14:15], v[84:85], v[28:29], v[14:15]
	v_and_b32_e32 v29, 0xffff0000, v51
	v_lshlrev_b32_e32 v28, 16, v51
	v_pk_fma_f32 v[8:9], v[8:9], v[28:29], 0 op_sel_hi:[1,1,0]
	v_and_b32_e32 v29, 0xffff0000, v58
	v_lshlrev_b32_e32 v28, 16, v58
	v_pk_fma_f32 v[8:9], v[24:25], v[28:29], v[8:9]
	v_and_b32_e32 v25, 0xffff0000, v62
	v_lshlrev_b32_e32 v24, 16, v62
	v_pk_fma_f32 v[8:9], v[40:41], v[24:25], v[8:9]
	v_and_b32_e32 v25, 0xffff0000, v64
	v_lshlrev_b32_e32 v24, 16, v64
	v_pk_fma_f32 v[8:9], v[86:87], v[24:25], v[8:9]
	v_and_b32_e32 v25, 0xffff0000, v55
	v_lshlrev_b32_e32 v24, 16, v55
	v_pk_fma_f32 v[10:11], v[10:11], v[24:25], 0 op_sel_hi:[1,1,0]
	v_and_b32_e32 v25, 0xffff0000, v59
	v_lshlrev_b32_e32 v24, 16, v59
	v_pk_fma_f32 v[10:11], v[26:27], v[24:25], v[10:11]
	v_and_b32_e32 v25, 0xffff0000, v63
	v_lshlrev_b32_e32 v24, 16, v63
	v_pk_fma_f32 v[10:11], v[42:43], v[24:25], v[10:11]
	v_and_b32_e32 v25, 0xffff0000, v65
	v_lshlrev_b32_e32 v24, 16, v65
	v_pk_fma_f32 v[10:11], v[88:89], v[24:25], v[10:11]
	v_and_b32_e32 v25, 0xffff0000, v66
	v_lshlrev_b32_e32 v24, 16, v66
	v_pk_fma_f32 v[4:5], v[4:5], v[24:25], 0 op_sel_hi:[1,1,0]
	v_and_b32_e32 v25, 0xffff0000, v68
	v_lshlrev_b32_e32 v24, 16, v68
	v_pk_fma_f32 v[4:5], v[20:21], v[24:25], v[4:5]
	v_and_b32_e32 v21, 0xffff0000, v70
	v_lshlrev_b32_e32 v20, 16, v70
	v_pk_fma_f32 v[4:5], v[36:37], v[20:21], v[4:5]
	v_and_b32_e32 v21, 0xffff0000, v72
	v_lshlrev_b32_e32 v20, 16, v72
	v_pk_fma_f32 v[4:5], v[90:91], v[20:21], v[4:5]
	v_and_b32_e32 v21, 0xffff0000, v67
	v_lshlrev_b32_e32 v20, 16, v67
	v_pk_fma_f32 v[6:7], v[6:7], v[20:21], 0 op_sel_hi:[1,1,0]
	v_and_b32_e32 v21, 0xffff0000, v69
	v_lshlrev_b32_e32 v20, 16, v69
	v_pk_fma_f32 v[6:7], v[22:23], v[20:21], v[6:7]
	v_and_b32_e32 v21, 0xffff0000, v71
	v_lshlrev_b32_e32 v20, 16, v71
	v_pk_fma_f32 v[6:7], v[38:39], v[20:21], v[6:7]
	v_and_b32_e32 v21, 0xffff0000, v73
	v_lshlrev_b32_e32 v20, 16, v73
	v_pk_fma_f32 v[6:7], v[92:93], v[20:21], v[6:7]
	v_and_b32_e32 v21, 0xffff0000, v74
	v_lshlrev_b32_e32 v20, 16, v74
	v_pk_fma_f32 v[0:1], v[0:1], v[20:21], 0 op_sel_hi:[1,1,0]
	v_and_b32_e32 v21, 0xffff0000, v76
	v_lshlrev_b32_e32 v20, 16, v76
	v_pk_fma_f32 v[0:1], v[16:17], v[20:21], v[0:1]
	v_and_b32_e32 v17, 0xffff0000, v78
	v_lshlrev_b32_e32 v16, 16, v78
	v_pk_fma_f32 v[0:1], v[32:33], v[16:17], v[0:1]
	v_and_b32_e32 v17, 0xffff0000, v80
	v_lshlrev_b32_e32 v16, 16, v80
	v_pk_fma_f32 v[0:1], v[94:95], v[16:17], v[0:1]
	v_and_b32_e32 v17, 0xffff0000, v75
	v_lshlrev_b32_e32 v16, 16, v75
	v_pk_fma_f32 v[2:3], v[2:3], v[16:17], 0 op_sel_hi:[1,1,0]
	v_and_b32_e32 v17, 0xffff0000, v77
	v_lshlrev_b32_e32 v16, 16, v77
	v_pk_fma_f32 v[2:3], v[18:19], v[16:17], v[2:3]
	v_and_b32_e32 v17, 0xffff0000, v79
	v_lshlrev_b32_e32 v16, 16, v79
	v_pk_fma_f32 v[2:3], v[34:35], v[16:17], v[2:3]
	v_and_b32_e32 v17, 0xffff0000, v81
	v_lshlrev_b32_e32 v16, 16, v81
	v_pk_fma_f32 v[2:3], v[96:97], v[16:17], v[2:3]
	v_or_b32_e32 v16, s20, v149
	v_add_u32_e32 v18, s19, v150
	v_ashrrev_i32_e32 v17, 31, v16
	v_ashrrev_i32_e32 v19, 31, v18
	v_lshl_add_u64 v[16:17], v[16:17], 1, s[2:3]
	v_cvt_pk_bf16_f32 v12, v12, v13
	v_cvt_pk_bf16_f32 v13, v14, v15
	v_lshlrev_b64 v[14:15], 11, v[18:19]
	v_lshl_add_u64 v[14:15], v[16:17], 0, v[14:15]
	global_store_dwordx2 v[14:15], v[12:13], off
	v_or_b32_e32 v12, 16, v18
	v_ashrrev_i32_e32 v13, 31, v12
	v_cvt_pk_bf16_f32 v8, v8, v9
	v_cvt_pk_bf16_f32 v9, v10, v11
	v_lshlrev_b64 v[10:11], 11, v[12:13]
	v_lshl_add_u64 v[10:11], v[16:17], 0, v[10:11]
	global_store_dwordx2 v[10:11], v[8:9], off
	v_or_b32_e32 v8, 32, v18
	v_ashrrev_i32_e32 v9, 31, v8
	v_cvt_pk_bf16_f32 v4, v4, v5
	v_cvt_pk_bf16_f32 v5, v6, v7
	v_lshlrev_b64 v[6:7], 11, v[8:9]
	v_lshl_add_u64 v[6:7], v[16:17], 0, v[6:7]
	global_store_dwordx2 v[6:7], v[4:5], off
	v_or_b32_e32 v4, 48, v18
	v_ashrrev_i32_e32 v5, 31, v4
	v_cvt_pk_bf16_f32 v0, v0, v1
	v_cvt_pk_bf16_f32 v1, v2, v3
	v_lshlrev_b64 v[2:3], 11, v[4:5]
	s_add_i32 s18, s18, s90
	v_lshl_add_u64 v[2:3], v[16:17], 0, v[2:3]
	s_cmpk_lt_i32 s18, 0x1080
	global_store_dwordx2 v[2:3], v[0:1], off
	s_cbranch_scc1 .LBB0_1988

; #define GLOAD(ra, rb, koff)                                                        \
;   {                                                                                \
;     _Pragma("unroll") for (int j = 0; j < 4; j++) ra[j] = *(const u32x4*)(pa + j * sa32 + (koff));   \
;     _Pragma("unroll") for (int j = 0; j < NB_; j++) rb[j] = *(const u32x4*)(pbv[j] + (koff));         \
;   }
; template <int NT, bool PRE> ...
;     ...
;   const int wsw = ((tid & 7) ^ ((tid >> 4) & 7)) * 8;
;   const int rsw = (lane & 15) >> 1;
;     ...
;   if (!PRE) {
;     GLOAD(ra0, rb0, 0);
;     GLOAD(ra1, rb1, 64);
;   }
;   __syncthreads();
;   for (int k0 = 0; k0 < K; k0 += 128) {
;     LSTORE(ra0, rb0, 0);
;     __syncthreads();
;     GLOAD(ra0, rb0, min(k0 + 128, K - 128));
;     __builtin_amdgcn_sched_barrier(0);
;     COMPUTE(0);
;     LSTORE(ra1, rb1, 1);
;     __syncthreads();
;     GLOAD(ra1, rb1, min(k0 + 192, K - 64));
;     __builtin_amdgcn_sched_barrier(0);
;     COMPUTE(1);
;   }
.LBB0_2043:
	s_add_i32 s5, s4, 0x100
	s_min_u32 s5, s5, 0x380
	s_lshl_b32 s54, s5, 1
	ds_read_b128 v[156:159], v152
	ds_read_b128 v[202:205], v153 offset:16384
	ds_read_b128 v[206:209], v153 offset:18432
	ds_read_b128 v[210:213], v153 offset:20480
	ds_read_b128 v[214:217], v153 offset:22528
	ds_read_b128 v[160:163], v152 offset:2048
	ds_read_b128 v[164:167], v152 offset:4096
	ds_read_b128 v[198:201], v152 offset:6144
	ds_read_b128 v[218:221], v154
	ds_read_b128 v[222:225], v154 offset:2048
	ds_read_b128 v[226:229], v154 offset:4096
	ds_read_b128 v[230:233], v154 offset:6144
	ds_read_b128 v[234:237], v155 offset:16384
	ds_read_b128 v[238:241], v155 offset:18432
	ds_read_b128 v[242:245], v155 offset:20480
	v_lshl_add_u64 v[8:9], v[142:143], 0, s[54:55]
	v_add_co_u32_e32 v16, vcc, s33, v8
	v_lshl_add_u64 v[0:1], v[134:135], 0, s[54:55]
	s_nop 0
	v_addc_co_u32_e32 v17, vcc, 0, v9, vcc
	v_add_co_u32_e32 v32, vcc, s56, v8
	v_lshl_add_u64 v[2:3], v[136:137], 0, s[54:55]
	s_nop 0
	v_addc_co_u32_e32 v33, vcc, 0, v9, vcc
	v_add_co_u32_e32 v48, vcc, s57, v8
	v_lshl_add_u64 v[4:5], v[138:139], 0, s[54:55]
	v_lshl_add_u64 v[10:11], v[140:141], 0, s[54:55]
	v_addc_co_u32_e32 v49, vcc, 0, v9, vcc
	s_addk_i32 s4, 0x80
	s_setprio 1
	s_waitcnt lgkmcnt(13)
	v_mfma_f32_16x16x32_bf16 v[124:127], v[202:205], v[156:159], v[124:127]
	s_waitcnt lgkmcnt(12)
	v_mfma_f32_16x16x32_bf16 v[116:119], v[206:209], v[156:159], v[116:119]
	s_waitcnt lgkmcnt(11)
	v_mfma_f32_16x16x32_bf16 v[112:115], v[210:213], v[156:159], v[112:115]
	s_waitcnt lgkmcnt(10)
	v_mfma_f32_16x16x32_bf16 v[108:111], v[214:217], v[156:159], v[108:111]
	ds_read_b128 v[156:159], v155 offset:22528
	global_load_dwordx4 v[20:23], v[0:1], off
	s_nop 0
	global_load_dwordx4 v[0:3], v[2:3], off
	s_waitcnt lgkmcnt(10)
	v_mfma_f32_16x16x32_bf16 v[120:123], v[202:205], v[160:163], v[120:123]
	v_mfma_f32_16x16x32_bf16 v[104:107], v[206:209], v[160:163], v[104:107]
	v_mfma_f32_16x16x32_bf16 v[96:99], v[210:213], v[160:163], v[96:99]
	v_mfma_f32_16x16x32_bf16 v[92:95], v[214:217], v[160:163], v[92:95]
	global_load_dwordx4 v[4:7], v[4:5], off
	s_nop 0
	global_load_dwordx4 v[52:55], v[10:11], off
	s_waitcnt lgkmcnt(9)
	v_mfma_f32_16x16x32_bf16 v[100:103], v[202:205], v[164:167], v[100:103]
	v_mfma_f32_16x16x32_bf16 v[88:91], v[206:209], v[164:167], v[88:91]
	v_mfma_f32_16x16x32_bf16 v[84:87], v[210:213], v[164:167], v[84:87]
	v_mfma_f32_16x16x32_bf16 v[76:79], v[214:217], v[164:167], v[76:79]
	global_load_dwordx4 v[8:11], v[8:9], off
	s_nop 0
	global_load_dwordx4 v[16:19], v[16:17], off
	s_waitcnt lgkmcnt(8)
	v_mfma_f32_16x16x32_bf16 v[80:83], v[202:205], v[198:201], v[80:83]
	v_mfma_f32_16x16x32_bf16 v[72:75], v[206:209], v[198:201], v[72:75]
	v_mfma_f32_16x16x32_bf16 v[68:71], v[210:213], v[198:201], v[68:71]
	v_mfma_f32_16x16x32_bf16 v[64:67], v[214:217], v[198:201], v[64:67]
	global_load_dwordx4 v[32:35], v[32:33], off
	s_nop 0
	global_load_dwordx4 v[48:51], v[48:49], off
	s_waitcnt lgkmcnt(3)
	v_mfma_f32_16x16x32_bf16 v[124:127], v[234:237], v[218:221], v[124:127]
	v_mfma_f32_16x16x32_bf16 v[120:123], v[234:237], v[222:225], v[120:123]
	v_mfma_f32_16x16x32_bf16 v[100:103], v[234:237], v[226:229], v[100:103]
	v_mfma_f32_16x16x32_bf16 v[80:83], v[234:237], v[230:233], v[80:83]
	s_waitcnt vmcnt(14)
	ds_write_b128 v150, v[28:31] offset:49152
	ds_write_b128 v150, v[36:39] offset:53248
	s_waitcnt lgkmcnt(4)
	v_mfma_f32_16x16x32_bf16 v[116:119], v[238:241], v[218:221], v[116:119]
	v_mfma_f32_16x16x32_bf16 v[104:107], v[238:241], v[222:225], v[104:107]
	v_mfma_f32_16x16x32_bf16 v[88:91], v[238:241], v[226:229], v[88:91]
	v_mfma_f32_16x16x32_bf16 v[72:75], v[238:241], v[230:233], v[72:75]
	s_waitcnt vmcnt(11)
	ds_write_b128 v150, v[44:47] offset:57344
	ds_write_b128 v150, v[12:15] offset:32768
	s_waitcnt lgkmcnt(5)
	v_mfma_f32_16x16x32_bf16 v[112:115], v[242:245], v[218:221], v[112:115]
	v_mfma_f32_16x16x32_bf16 v[96:99], v[242:245], v[222:225], v[96:99]
	v_mfma_f32_16x16x32_bf16 v[84:87], v[242:245], v[226:229], v[84:87]
	v_mfma_f32_16x16x32_bf16 v[68:71], v[242:245], v[230:233], v[68:71]
	s_waitcnt vmcnt(9)
	ds_write_b128 v150, v[24:27] offset:36864
	ds_write_b128 v150, v[40:43] offset:40960
	s_waitcnt lgkmcnt(6)
	v_mfma_f32_16x16x32_bf16 v[108:111], v[156:159], v[218:221], v[108:111]
	v_mfma_f32_16x16x32_bf16 v[92:95], v[156:159], v[222:225], v[92:95]
	v_mfma_f32_16x16x32_bf16 v[76:79], v[156:159], v[226:229], v[76:79]
	v_mfma_f32_16x16x32_bf16 v[64:67], v[156:159], v[230:233], v[64:67]
	s_waitcnt vmcnt(8)
	ds_write_b128 v150, v[56:59] offset:45056
	ds_write_b128 v150, v[60:63] offset:61440
	s_setprio 0
	s_waitcnt lgkmcnt(0)
	s_barrier
; #define GLOAD(ra, rb, koff)                                                        \
;   {                                                                                \
;     _Pragma("unroll") for (int j = 0; j < 4; j++) ra[j] = *(const u32x4*)(pa + j * sa32 + (koff));   \
;     _Pragma("unroll") for (int j = 0; j < NB_; j++) rb[j] = *(const u32x4*)(pbv[j] + (koff));         \
;   }
; template <int NT, bool PRE> ...
;     ...
;   const int wsw = ((tid & 7) ^ ((tid >> 4) & 7)) * 8;
;   const int rsw = (lane & 15) >> 1;
;     ...
;   if (!PRE) {
;     GLOAD(ra0, rb0, 0);
;     GLOAD(ra1, rb1, 64);
;   }
;   __syncthreads();
;   for (int k0 = 0; k0 < K; k0 += 128) {
;     LSTORE(ra0, rb0, 0);
;     __syncthreads();
;     GLOAD(ra0, rb0, min(k0 + 128, K - 128));
;     __builtin_amdgcn_sched_barrier(0);
;     COMPUTE(0);
;     LSTORE(ra1, rb1, 1);
;     __syncthreads();
;     GLOAD(ra1, rb1, min(k0 + 192, K - 64));
;     __builtin_amdgcn_sched_barrier(0);
;     COMPUTE(1);
;   }
	s_min_u32 s5, s4, 0x300
	s_lshl_b32 s54, s5, 1
	ds_read_b128 v[156:159], v152 offset:32768
	ds_read_b128 v[202:205], v153 offset:49152
	ds_read_b128 v[206:209], v153 offset:51200
	ds_read_b128 v[210:213], v153 offset:53248
	ds_read_b128 v[214:217], v153 offset:55296
	ds_read_b128 v[160:163], v152 offset:34816
	ds_read_b128 v[164:167], v152 offset:36864
	ds_read_b128 v[198:201], v152 offset:38912
	ds_read_b128 v[218:221], v154 offset:32768
	ds_read_b128 v[222:225], v154 offset:34816
	ds_read_b128 v[226:229], v154 offset:36864
	ds_read_b128 v[230:233], v154 offset:38912
	ds_read_b128 v[234:237], v155 offset:49152
	ds_read_b128 v[238:241], v155 offset:51200
	ds_read_b128 v[242:245], v155 offset:53248
	v_lshl_add_u64 v[12:13], v[142:143], 0, s[54:55]
	v_add_co_u32_e32 v42, vcc, s33, v12
	v_lshl_add_u64 v[14:15], v[134:135], 0, s[54:55]
	s_nop 0
	v_addc_co_u32_e32 v43, vcc, 0, v13, vcc
	v_add_co_u32_e32 v56, vcc, s56, v12
	v_lshl_add_u64 v[24:25], v[136:137], 0, s[54:55]
	s_nop 0
	v_addc_co_u32_e32 v57, vcc, 0, v13, vcc
	v_add_co_u32_e32 v58, vcc, s57, v12
	v_lshl_add_u64 v[26:27], v[138:139], 0, s[54:55]
	v_lshl_add_u64 v[40:41], v[140:141], 0, s[54:55]
	v_addc_co_u32_e32 v59, vcc, 0, v13, vcc
	s_setprio 1
	s_waitcnt lgkmcnt(13)
	v_mfma_f32_16x16x32_bf16 v[124:127], v[202:205], v[156:159], v[124:127]
	s_waitcnt lgkmcnt(12)
	v_mfma_f32_16x16x32_bf16 v[116:119], v[206:209], v[156:159], v[116:119]
	s_waitcnt lgkmcnt(11)
	v_mfma_f32_16x16x32_bf16 v[112:115], v[210:213], v[156:159], v[112:115]
	s_waitcnt lgkmcnt(10)
	v_mfma_f32_16x16x32_bf16 v[108:111], v[214:217], v[156:159], v[108:111]
	ds_read_b128 v[156:159], v155 offset:55296
	global_load_dwordx4 v[28:31], v[14:15], off offset:384
	s_nop 0
	global_load_dwordx4 v[36:39], v[24:25], off offset:384
	s_waitcnt lgkmcnt(10)
	v_mfma_f32_16x16x32_bf16 v[120:123], v[202:205], v[160:163], v[120:123]
	v_mfma_f32_16x16x32_bf16 v[104:107], v[206:209], v[160:163], v[104:107]
	v_mfma_f32_16x16x32_bf16 v[96:99], v[210:213], v[160:163], v[96:99]
	v_mfma_f32_16x16x32_bf16 v[92:95], v[214:217], v[160:163], v[92:95]
	global_load_dwordx4 v[44:47], v[26:27], off offset:384
	s_nop 0
	global_load_dwordx4 v[60:63], v[40:41], off offset:384
	s_waitcnt lgkmcnt(9)
	v_mfma_f32_16x16x32_bf16 v[100:103], v[202:205], v[164:167], v[100:103]
	v_mfma_f32_16x16x32_bf16 v[88:91], v[206:209], v[164:167], v[88:91]
	v_mfma_f32_16x16x32_bf16 v[84:87], v[210:213], v[164:167], v[84:87]
	v_mfma_f32_16x16x32_bf16 v[76:79], v[214:217], v[164:167], v[76:79]
	global_load_dwordx4 v[12:15], v[12:13], off offset:384
	s_nop 0
	global_load_dwordx4 v[24:27], v[42:43], off offset:384
	s_waitcnt lgkmcnt(8)
	v_mfma_f32_16x16x32_bf16 v[80:83], v[202:205], v[198:201], v[80:83]
	v_mfma_f32_16x16x32_bf16 v[72:75], v[206:209], v[198:201], v[72:75]
	v_mfma_f32_16x16x32_bf16 v[68:71], v[210:213], v[198:201], v[68:71]
	v_mfma_f32_16x16x32_bf16 v[64:67], v[214:217], v[198:201], v[64:67]
	global_load_dwordx4 v[40:43], v[56:57], off offset:384
	s_nop 0
	global_load_dwordx4 v[56:59], v[58:59], off offset:384
	s_waitcnt lgkmcnt(3)
	v_mfma_f32_16x16x32_bf16 v[124:127], v[234:237], v[218:221], v[124:127]
	v_mfma_f32_16x16x32_bf16 v[120:123], v[234:237], v[222:225], v[120:123]
	v_mfma_f32_16x16x32_bf16 v[100:103], v[234:237], v[226:229], v[100:103]
	v_mfma_f32_16x16x32_bf16 v[80:83], v[234:237], v[230:233], v[80:83]
	s_waitcnt vmcnt(14)
	ds_write_b128 v150, v[20:23] offset:16384
	ds_write_b128 v150, v[0:3] offset:20480
	s_waitcnt lgkmcnt(4)
	v_mfma_f32_16x16x32_bf16 v[116:119], v[238:241], v[218:221], v[116:119]
	v_mfma_f32_16x16x32_bf16 v[104:107], v[238:241], v[222:225], v[104:107]
	v_mfma_f32_16x16x32_bf16 v[88:91], v[238:241], v[226:229], v[88:91]
	v_mfma_f32_16x16x32_bf16 v[72:75], v[238:241], v[230:233], v[72:75]
	s_waitcnt vmcnt(12)
	ds_write_b128 v150, v[4:7] offset:24576
	ds_write_b128 v150, v[52:55] offset:28672
	s_waitcnt lgkmcnt(5)
	v_mfma_f32_16x16x32_bf16 v[112:115], v[242:245], v[218:221], v[112:115]
	v_mfma_f32_16x16x32_bf16 v[96:99], v[242:245], v[222:225], v[96:99]
	v_mfma_f32_16x16x32_bf16 v[84:87], v[242:245], v[226:229], v[84:87]
	v_mfma_f32_16x16x32_bf16 v[68:71], v[242:245], v[230:233], v[68:71]
	s_waitcnt vmcnt(10)
	ds_write_b128 v150, v[8:11]
	ds_write_b128 v150, v[16:19] offset:4096
	s_waitcnt lgkmcnt(6)
	v_mfma_f32_16x16x32_bf16 v[108:111], v[156:159], v[218:221], v[108:111]
	v_mfma_f32_16x16x32_bf16 v[92:95], v[156:159], v[222:225], v[92:95]
	v_mfma_f32_16x16x32_bf16 v[76:79], v[156:159], v[226:229], v[76:79]
	v_mfma_f32_16x16x32_bf16 v[64:67], v[156:159], v[230:233], v[64:67]
	s_waitcnt vmcnt(8)
	ds_write_b128 v150, v[32:35] offset:8192
	ds_write_b128 v150, v[48:51] offset:12288
	s_setprio 0
	s_waitcnt lgkmcnt(0)
	s_barrier
	s_cmpk_lt_u32 s4, 0x300
	s_cbranch_scc1 .LBB0_2043
; #define GLOAD(ra, rb, koff)                                                        \
;   {                                                                                \
;     _Pragma("unroll") for (int j = 0; j < 4; j++) ra[j] = *(const u32x4*)(pa + j * sa32 + (koff));   \
;     _Pragma("unroll") for (int j = 0; j < NB_; j++) rb[j] = *(const u32x4*)(pbv[j] + (koff));         \
;   }
; template <int NT, bool PRE> ...
;     ...
;   if (!PRE) {
;     GLOAD(ra0, rb0, 0);
;     GLOAD(ra1, rb1, 64);
;   }
;   __syncthreads();
;   for (int k0 = 0; k0 < K; k0 += 128) {
;     LSTORE(ra0, rb0, 0);
;     __syncthreads();
;     GLOAD(ra0, rb0, min(k0 + 128, K - 128));
;     __builtin_amdgcn_sched_barrier(0);
;     COMPUTE(0);
;     LSTORE(ra1, rb1, 1);
;     __syncthreads();
;     GLOAD(ra1, rb1, min(k0 + 192, K - 64));
;     __builtin_amdgcn_sched_barrier(0);
;     COMPUTE(1);
;   }
	ds_read_b128 v[156:159], v152
	ds_read_b128 v[202:205], v153 offset:16384
	ds_read_b128 v[206:209], v153 offset:18432
	ds_read_b128 v[210:213], v153 offset:20480
	ds_read_b128 v[214:217], v153 offset:22528
	ds_read_b128 v[160:163], v152 offset:2048
	ds_read_b128 v[164:167], v152 offset:4096
	ds_read_b128 v[198:201], v152 offset:6144
	ds_read_b128 v[218:221], v154
	ds_read_b128 v[222:225], v154 offset:2048
	ds_read_b128 v[226:229], v154 offset:4096
	ds_read_b128 v[230:233], v154 offset:6144
	ds_read_b128 v[234:237], v155 offset:16384
	ds_read_b128 v[238:241], v155 offset:18432
	ds_read_b128 v[242:245], v155 offset:20480
	s_addk_i32 s4, 0x80
	s_setprio 1
	s_waitcnt lgkmcnt(13)
	v_mfma_f32_16x16x32_bf16 v[124:127], v[202:205], v[156:159], v[124:127]
	s_waitcnt lgkmcnt(12)
	v_mfma_f32_16x16x32_bf16 v[116:119], v[206:209], v[156:159], v[116:119]
	s_waitcnt lgkmcnt(11)
	v_mfma_f32_16x16x32_bf16 v[112:115], v[210:213], v[156:159], v[112:115]
	s_waitcnt lgkmcnt(10)
	v_mfma_f32_16x16x32_bf16 v[108:111], v[214:217], v[156:159], v[108:111]
	ds_read_b128 v[156:159], v155 offset:22528
	s_waitcnt lgkmcnt(10)
	v_mfma_f32_16x16x32_bf16 v[120:123], v[202:205], v[160:163], v[120:123]
	v_mfma_f32_16x16x32_bf16 v[104:107], v[206:209], v[160:163], v[104:107]
	v_mfma_f32_16x16x32_bf16 v[96:99], v[210:213], v[160:163], v[96:99]
	v_mfma_f32_16x16x32_bf16 v[92:95], v[214:217], v[160:163], v[92:95]
	s_waitcnt lgkmcnt(9)
	v_mfma_f32_16x16x32_bf16 v[100:103], v[202:205], v[164:167], v[100:103]
	v_mfma_f32_16x16x32_bf16 v[88:91], v[206:209], v[164:167], v[88:91]
	v_mfma_f32_16x16x32_bf16 v[84:87], v[210:213], v[164:167], v[84:87]
	v_mfma_f32_16x16x32_bf16 v[76:79], v[214:217], v[164:167], v[76:79]
	s_waitcnt lgkmcnt(8)
	v_mfma_f32_16x16x32_bf16 v[80:83], v[202:205], v[198:201], v[80:83]
	v_mfma_f32_16x16x32_bf16 v[72:75], v[206:209], v[198:201], v[72:75]
	v_mfma_f32_16x16x32_bf16 v[68:71], v[210:213], v[198:201], v[68:71]
	v_mfma_f32_16x16x32_bf16 v[64:67], v[214:217], v[198:201], v[64:67]
	s_waitcnt lgkmcnt(3)
	v_mfma_f32_16x16x32_bf16 v[124:127], v[234:237], v[218:221], v[124:127]
	v_mfma_f32_16x16x32_bf16 v[120:123], v[234:237], v[222:225], v[120:123]
	v_mfma_f32_16x16x32_bf16 v[100:103], v[234:237], v[226:229], v[100:103]
	v_mfma_f32_16x16x32_bf16 v[80:83], v[234:237], v[230:233], v[80:83]
	s_waitcnt vmcnt(6)
	ds_write_b128 v150, v[28:31] offset:49152
	ds_write_b128 v150, v[36:39] offset:53248
	s_waitcnt lgkmcnt(4)
	v_mfma_f32_16x16x32_bf16 v[116:119], v[238:241], v[218:221], v[116:119]
	v_mfma_f32_16x16x32_bf16 v[104:107], v[238:241], v[222:225], v[104:107]
	v_mfma_f32_16x16x32_bf16 v[88:91], v[238:241], v[226:229], v[88:91]
	v_mfma_f32_16x16x32_bf16 v[72:75], v[238:241], v[230:233], v[72:75]
	s_waitcnt vmcnt(3)
	ds_write_b128 v150, v[44:47] offset:57344
	ds_write_b128 v150, v[12:15] offset:32768
	s_waitcnt lgkmcnt(5)
	v_mfma_f32_16x16x32_bf16 v[112:115], v[242:245], v[218:221], v[112:115]
	v_mfma_f32_16x16x32_bf16 v[96:99], v[242:245], v[222:225], v[96:99]
	v_mfma_f32_16x16x32_bf16 v[84:87], v[242:245], v[226:229], v[84:87]
	v_mfma_f32_16x16x32_bf16 v[68:71], v[242:245], v[230:233], v[68:71]
	s_waitcnt vmcnt(1)
	ds_write_b128 v150, v[24:27] offset:36864
	ds_write_b128 v150, v[40:43] offset:40960
	s_waitcnt lgkmcnt(6)
	v_mfma_f32_16x16x32_bf16 v[108:111], v[156:159], v[218:221], v[108:111]
	v_mfma_f32_16x16x32_bf16 v[92:95], v[156:159], v[222:225], v[92:95]
	v_mfma_f32_16x16x32_bf16 v[76:79], v[156:159], v[226:229], v[76:79]
	v_mfma_f32_16x16x32_bf16 v[64:67], v[156:159], v[230:233], v[64:67]
	s_waitcnt vmcnt(0)
	ds_write_b128 v150, v[56:59] offset:45056
	ds_write_b128 v150, v[60:63] offset:61440
	s_setprio 0
	s_waitcnt lgkmcnt(0)
	s_barrier
; template <int EPI>
; __device__ __forceinline__ void phase_gemm(const Params& P, const u16* A, int lda, const u16* Bt, int K, int N, u16* sA, u16* sB) {
;     ...
;     for (; t < Tfull; t += G) {
;       const int m0 = (t % 132) * 128, n0 = (t / 132) * 128;
;       f32x4 acc[4][4];
;       zero_acc<4>(acc);
;       gemm_core_r<4, true>(pa, (size_t)32 * lda, pbv, K, acc, sA, sB, tq, ra0, rb0, ra1, rb1);
;       if (t + G < Tfull) {
;         PG_PTRS(t + G);
;         gemm_preload<4>(pa, (size_t)32 * lda, pbv, ra0, rb0, ra1, rb1);
;       }
	ds_read_b128 v[156:159], v152 offset:32768
	ds_read_b128 v[202:205], v153 offset:49152
	ds_read_b128 v[206:209], v153 offset:51200
	ds_read_b128 v[210:213], v153 offset:53248
	ds_read_b128 v[214:217], v153 offset:55296
	ds_read_b128 v[160:163], v152 offset:34816
	ds_read_b128 v[164:167], v152 offset:36864
	ds_read_b128 v[198:201], v152 offset:38912
	ds_read_b128 v[218:221], v154 offset:32768
	ds_read_b128 v[222:225], v154 offset:34816
	ds_read_b128 v[226:229], v154 offset:36864
	ds_read_b128 v[230:233], v154 offset:38912
	ds_read_b128 v[234:237], v155 offset:49152
	ds_read_b128 v[238:241], v155 offset:51200
	ds_read_b128 v[242:245], v155 offset:53248
	s_setprio 1
	s_waitcnt lgkmcnt(13)
	v_mfma_f32_16x16x32_bf16 v[124:127], v[202:205], v[156:159], v[124:127]
	s_waitcnt lgkmcnt(12)
	v_mfma_f32_16x16x32_bf16 v[116:119], v[206:209], v[156:159], v[116:119]
	s_waitcnt lgkmcnt(11)
	v_mfma_f32_16x16x32_bf16 v[112:115], v[210:213], v[156:159], v[112:115]
	s_waitcnt lgkmcnt(10)
	v_mfma_f32_16x16x32_bf16 v[108:111], v[214:217], v[156:159], v[108:111]
	ds_read_b128 v[156:159], v155 offset:55296
	s_waitcnt lgkmcnt(10)
	v_mfma_f32_16x16x32_bf16 v[120:123], v[202:205], v[160:163], v[120:123]
	v_mfma_f32_16x16x32_bf16 v[104:107], v[206:209], v[160:163], v[104:107]
	v_mfma_f32_16x16x32_bf16 v[96:99], v[210:213], v[160:163], v[96:99]
	v_mfma_f32_16x16x32_bf16 v[92:95], v[214:217], v[160:163], v[92:95]
	s_waitcnt lgkmcnt(9)
	v_mfma_f32_16x16x32_bf16 v[100:103], v[202:205], v[164:167], v[100:103]
	v_mfma_f32_16x16x32_bf16 v[88:91], v[206:209], v[164:167], v[88:91]
	v_mfma_f32_16x16x32_bf16 v[84:87], v[210:213], v[164:167], v[84:87]
	v_mfma_f32_16x16x32_bf16 v[76:79], v[214:217], v[164:167], v[76:79]
	s_waitcnt lgkmcnt(8)
	v_mfma_f32_16x16x32_bf16 v[80:83], v[202:205], v[198:201], v[80:83]
	v_mfma_f32_16x16x32_bf16 v[72:75], v[206:209], v[198:201], v[72:75]
	v_mfma_f32_16x16x32_bf16 v[68:71], v[210:213], v[198:201], v[68:71]
	v_mfma_f32_16x16x32_bf16 v[64:67], v[214:217], v[198:201], v[64:67]
	s_waitcnt lgkmcnt(3)
	v_mfma_f32_16x16x32_bf16 v[124:127], v[234:237], v[218:221], v[124:127]
	v_mfma_f32_16x16x32_bf16 v[120:123], v[234:237], v[222:225], v[120:123]
	v_mfma_f32_16x16x32_bf16 v[100:103], v[234:237], v[226:229], v[100:103]
	v_mfma_f32_16x16x32_bf16 v[80:83], v[234:237], v[230:233], v[80:83]
	s_waitcnt lgkmcnt(2)
	v_mfma_f32_16x16x32_bf16 v[116:119], v[238:241], v[218:221], v[116:119]
	v_mfma_f32_16x16x32_bf16 v[104:107], v[238:241], v[222:225], v[104:107]
	v_mfma_f32_16x16x32_bf16 v[88:91], v[238:241], v[226:229], v[88:91]
	v_mfma_f32_16x16x32_bf16 v[72:75], v[238:241], v[230:233], v[72:75]
	s_waitcnt lgkmcnt(1)
	v_mfma_f32_16x16x32_bf16 v[112:115], v[242:245], v[218:221], v[112:115]
	v_mfma_f32_16x16x32_bf16 v[96:99], v[242:245], v[222:225], v[96:99]
	v_mfma_f32_16x16x32_bf16 v[84:87], v[242:245], v[226:229], v[84:87]
	v_mfma_f32_16x16x32_bf16 v[68:71], v[242:245], v[230:233], v[68:71]
	s_waitcnt lgkmcnt(0)
	v_mfma_f32_16x16x32_bf16 v[108:111], v[156:159], v[218:221], v[108:111]
	v_mfma_f32_16x16x32_bf16 v[92:95], v[156:159], v[222:225], v[92:95]
	v_mfma_f32_16x16x32_bf16 v[76:79], v[156:159], v[226:229], v[76:79]
	v_mfma_f32_16x16x32_bf16 v[64:67], v[156:159], v[230:233], v[64:67]
	s_setprio 0
	s_waitcnt lgkmcnt(0)
	s_add_i32 s7, s6, s90
	s_cmp_ge_i32 s7, s16
	s_cselect_b64 s[4:5], -1, 0
	s_and_b64 vcc, exec, s[4:5]
	s_cbranch_vccnz .LBB0_2041
	s_cmp_lg_u32 s90, 0x200
	s_cbranch_scc1 .Lrm_wop_orig
	s_and_b32 s54, s7, 7
	s_lshl_b32 s54, s54, 6
	s_bfe_u32 s8, s7, 0x60003
	s_or_b32 s54, s54, s8
	s_andn2_b32 s8, s7, 0x1ff
	s_or_b32 s54, s54, s8
	s_cmp_lt_u32 s54, 0
	s_cbranch_scc0 .Lrm_wop_b
	s_lshr_b32 s8, s54, 3
	s_mul_hi_u32 s8, s8, 0x3e0f83e1
	s_lshr_b32 s8, s8, 5
	s_mul_i32 s9, s8, 1056
	s_sub_i32 s54, s54, s9
	s_lshl_b32 s8, s8, 3
	s_and_b32 s9, s54, 7
	s_add_i32 s8, s8, s9
	s_lshr_b32 s9, s54, 3
	s_branch .Lrm_wop_done

; #define GLOAD(ra, rb, koff)                                                        \
;   {                                                                                \
;     _Pragma("unroll") for (int j = 0; j < 4; j++) ra[j] = *(const u32x4*)(pa + j * sa32 + (koff));   \
;     _Pragma("unroll") for (int j = 0; j < NB_; j++) rb[j] = *(const u32x4*)(pbv[j] + (koff));         \
;   }
; template <int NT, bool PRE> ...
;     ...
;   const int wsw = ((tid & 7) ^ ((tid >> 4) & 7)) * 8;
;   const int rsw = (lane & 15) >> 1;
;     ...
;   if (!PRE) {
;     GLOAD(ra0, rb0, 0);
;     GLOAD(ra1, rb1, 64);
;   }
;   __syncthreads();
;   for (int k0 = 0; k0 < K; k0 += 128) {
;     LSTORE(ra0, rb0, 0);
;     __syncthreads();
;     GLOAD(ra0, rb0, min(k0 + 128, K - 128));
;     __builtin_amdgcn_sched_barrier(0);
;     COMPUTE(0);
;     LSTORE(ra1, rb1, 1);
;     __syncthreads();
;     GLOAD(ra1, rb1, min(k0 + 192, K - 64));
;     __builtin_amdgcn_sched_barrier(0);
;     COMPUTE(1);
;   }
.LBB0_2230:
	s_add_i32 s5, s4, 0x100
	s_min_u32 s5, s5, 0x380
	s_lshl_b32 s54, s5, 1
	ds_read_b128 v[156:159], v152
	ds_read_b128 v[202:205], v153 offset:16384
	ds_read_b128 v[206:209], v153 offset:18432
	ds_read_b128 v[210:213], v153 offset:20480
	ds_read_b128 v[214:217], v153 offset:22528
	ds_read_b128 v[160:163], v152 offset:2048
	ds_read_b128 v[164:167], v152 offset:4096
	ds_read_b128 v[198:201], v152 offset:6144
	ds_read_b128 v[218:221], v154
	ds_read_b128 v[222:225], v154 offset:2048
	ds_read_b128 v[226:229], v154 offset:4096
	ds_read_b128 v[230:233], v154 offset:6144
	ds_read_b128 v[234:237], v155 offset:16384
	ds_read_b128 v[238:241], v155 offset:18432
	ds_read_b128 v[242:245], v155 offset:20480
	v_lshl_add_u64 v[8:9], v[142:143], 0, s[54:55]
	v_add_co_u32_e32 v16, vcc, s33, v8
	v_lshl_add_u64 v[0:1], v[134:135], 0, s[54:55]
	s_nop 0
	v_addc_co_u32_e32 v17, vcc, 0, v9, vcc
	v_add_co_u32_e32 v32, vcc, s56, v8
	v_lshl_add_u64 v[2:3], v[136:137], 0, s[54:55]
	s_nop 0
	v_addc_co_u32_e32 v33, vcc, 0, v9, vcc
	v_add_co_u32_e32 v48, vcc, s57, v8
	v_lshl_add_u64 v[4:5], v[138:139], 0, s[54:55]
	v_lshl_add_u64 v[10:11], v[140:141], 0, s[54:55]
	v_addc_co_u32_e32 v49, vcc, 0, v9, vcc
	s_addk_i32 s4, 0x80
	s_setprio 1
	s_waitcnt lgkmcnt(13)
	v_mfma_f32_16x16x32_bf16 v[124:127], v[202:205], v[156:159], v[124:127]
	s_waitcnt lgkmcnt(12)
	v_mfma_f32_16x16x32_bf16 v[112:115], v[206:209], v[156:159], v[112:115]
	s_waitcnt lgkmcnt(11)
	v_mfma_f32_16x16x32_bf16 v[96:99], v[210:213], v[156:159], v[96:99]
	s_waitcnt lgkmcnt(10)
	v_mfma_f32_16x16x32_bf16 v[80:83], v[214:217], v[156:159], v[80:83]
	ds_read_b128 v[156:159], v155 offset:22528
	global_load_dwordx4 v[20:23], v[0:1], off
	s_nop 0
	global_load_dwordx4 v[0:3], v[2:3], off
	s_waitcnt lgkmcnt(10)
	v_mfma_f32_16x16x32_bf16 v[120:123], v[202:205], v[160:163], v[120:123]
	v_mfma_f32_16x16x32_bf16 v[104:107], v[206:209], v[160:163], v[104:107]
	v_mfma_f32_16x16x32_bf16 v[88:91], v[210:213], v[160:163], v[88:91]
	v_mfma_f32_16x16x32_bf16 v[72:75], v[214:217], v[160:163], v[72:75]
	global_load_dwordx4 v[4:7], v[4:5], off
	s_nop 0
	global_load_dwordx4 v[52:55], v[10:11], off
	s_waitcnt lgkmcnt(9)
	v_mfma_f32_16x16x32_bf16 v[116:119], v[202:205], v[164:167], v[116:119]
	v_mfma_f32_16x16x32_bf16 v[100:103], v[206:209], v[164:167], v[100:103]
	v_mfma_f32_16x16x32_bf16 v[84:87], v[210:213], v[164:167], v[84:87]
	v_mfma_f32_16x16x32_bf16 v[68:71], v[214:217], v[164:167], v[68:71]
	global_load_dwordx4 v[8:11], v[8:9], off
	s_nop 0
	global_load_dwordx4 v[16:19], v[16:17], off
	s_waitcnt lgkmcnt(8)
	v_mfma_f32_16x16x32_bf16 v[108:111], v[202:205], v[198:201], v[108:111]
	v_mfma_f32_16x16x32_bf16 v[92:95], v[206:209], v[198:201], v[92:95]
	v_mfma_f32_16x16x32_bf16 v[76:79], v[210:213], v[198:201], v[76:79]
	v_mfma_f32_16x16x32_bf16 v[64:67], v[214:217], v[198:201], v[64:67]
	global_load_dwordx4 v[32:35], v[32:33], off
	s_nop 0
	global_load_dwordx4 v[48:51], v[48:49], off
	s_waitcnt lgkmcnt(3)
	v_mfma_f32_16x16x32_bf16 v[124:127], v[234:237], v[218:221], v[124:127]
	v_mfma_f32_16x16x32_bf16 v[120:123], v[234:237], v[222:225], v[120:123]
	v_mfma_f32_16x16x32_bf16 v[116:119], v[234:237], v[226:229], v[116:119]
	v_mfma_f32_16x16x32_bf16 v[108:111], v[234:237], v[230:233], v[108:111]
	s_waitcnt vmcnt(14)
	ds_write_b128 v150, v[28:31] offset:49152
	ds_write_b128 v150, v[36:39] offset:53248
	s_waitcnt lgkmcnt(4)
	v_mfma_f32_16x16x32_bf16 v[112:115], v[238:241], v[218:221], v[112:115]
	v_mfma_f32_16x16x32_bf16 v[104:107], v[238:241], v[222:225], v[104:107]
	v_mfma_f32_16x16x32_bf16 v[100:103], v[238:241], v[226:229], v[100:103]
	v_mfma_f32_16x16x32_bf16 v[92:95], v[238:241], v[230:233], v[92:95]
	s_waitcnt vmcnt(11)
	ds_write_b128 v150, v[44:47] offset:57344
	ds_write_b128 v150, v[12:15] offset:32768
	s_waitcnt lgkmcnt(5)
	v_mfma_f32_16x16x32_bf16 v[96:99], v[242:245], v[218:221], v[96:99]
	v_mfma_f32_16x16x32_bf16 v[88:91], v[242:245], v[222:225], v[88:91]
	v_mfma_f32_16x16x32_bf16 v[84:87], v[242:245], v[226:229], v[84:87]
	v_mfma_f32_16x16x32_bf16 v[76:79], v[242:245], v[230:233], v[76:79]
	s_waitcnt vmcnt(9)
	ds_write_b128 v150, v[24:27] offset:36864
	ds_write_b128 v150, v[40:43] offset:40960
	s_waitcnt lgkmcnt(6)
	v_mfma_f32_16x16x32_bf16 v[80:83], v[156:159], v[218:221], v[80:83]
	v_mfma_f32_16x16x32_bf16 v[72:75], v[156:159], v[222:225], v[72:75]
	v_mfma_f32_16x16x32_bf16 v[68:71], v[156:159], v[226:229], v[68:71]
	v_mfma_f32_16x16x32_bf16 v[64:67], v[156:159], v[230:233], v[64:67]
	s_waitcnt vmcnt(8)
	ds_write_b128 v150, v[56:59] offset:45056
	ds_write_b128 v150, v[60:63] offset:61440
	s_setprio 0
	s_waitcnt lgkmcnt(0)
	s_barrier
; #define GLOAD(ra, rb, koff)                                                        \
;   {                                                                                \
;     _Pragma("unroll") for (int j = 0; j < 4; j++) ra[j] = *(const u32x4*)(pa + j * sa32 + (koff));   \
;     _Pragma("unroll") for (int j = 0; j < NB_; j++) rb[j] = *(const u32x4*)(pbv[j] + (koff));         \
;   }
; template <int NT, bool PRE> ...
;     ...
;   const int wsw = ((tid & 7) ^ ((tid >> 4) & 7)) * 8;
;   const int rsw = (lane & 15) >> 1;
;     ...
;   if (!PRE) {
;     GLOAD(ra0, rb0, 0);
;     GLOAD(ra1, rb1, 64);
;   }
;   __syncthreads();
;   for (int k0 = 0; k0 < K; k0 += 128) {
;     LSTORE(ra0, rb0, 0);
;     __syncthreads();
;     GLOAD(ra0, rb0, min(k0 + 128, K - 128));
;     __builtin_amdgcn_sched_barrier(0);
;     COMPUTE(0);
;     LSTORE(ra1, rb1, 1);
;     __syncthreads();
;     GLOAD(ra1, rb1, min(k0 + 192, K - 64));
;     __builtin_amdgcn_sched_barrier(0);
;     COMPUTE(1);
;   }
	s_min_u32 s5, s4, 0x300
	s_lshl_b32 s54, s5, 1
	ds_read_b128 v[156:159], v152 offset:32768
	ds_read_b128 v[202:205], v153 offset:49152
	ds_read_b128 v[206:209], v153 offset:51200
	ds_read_b128 v[210:213], v153 offset:53248
	ds_read_b128 v[214:217], v153 offset:55296
	ds_read_b128 v[160:163], v152 offset:34816
	ds_read_b128 v[164:167], v152 offset:36864
	ds_read_b128 v[198:201], v152 offset:38912
	ds_read_b128 v[218:221], v154 offset:32768
	ds_read_b128 v[222:225], v154 offset:34816
	ds_read_b128 v[226:229], v154 offset:36864
	ds_read_b128 v[230:233], v154 offset:38912
	ds_read_b128 v[234:237], v155 offset:49152
	ds_read_b128 v[238:241], v155 offset:51200
	ds_read_b128 v[242:245], v155 offset:53248
	v_lshl_add_u64 v[12:13], v[142:143], 0, s[54:55]
	v_add_co_u32_e32 v42, vcc, s33, v12
	v_lshl_add_u64 v[14:15], v[134:135], 0, s[54:55]
	s_nop 0
	v_addc_co_u32_e32 v43, vcc, 0, v13, vcc
	v_add_co_u32_e32 v56, vcc, s56, v12
	v_lshl_add_u64 v[24:25], v[136:137], 0, s[54:55]
	s_nop 0
	v_addc_co_u32_e32 v57, vcc, 0, v13, vcc
	v_add_co_u32_e32 v58, vcc, s57, v12
	v_lshl_add_u64 v[26:27], v[138:139], 0, s[54:55]
	v_lshl_add_u64 v[40:41], v[140:141], 0, s[54:55]
	v_addc_co_u32_e32 v59, vcc, 0, v13, vcc
	s_setprio 1
	s_waitcnt lgkmcnt(13)
	v_mfma_f32_16x16x32_bf16 v[124:127], v[202:205], v[156:159], v[124:127]
	s_waitcnt lgkmcnt(12)
	v_mfma_f32_16x16x32_bf16 v[112:115], v[206:209], v[156:159], v[112:115]
	s_waitcnt lgkmcnt(11)
	v_mfma_f32_16x16x32_bf16 v[96:99], v[210:213], v[156:159], v[96:99]
	s_waitcnt lgkmcnt(10)
	v_mfma_f32_16x16x32_bf16 v[80:83], v[214:217], v[156:159], v[80:83]
	ds_read_b128 v[156:159], v155 offset:55296
	global_load_dwordx4 v[28:31], v[14:15], off offset:384
	s_nop 0
	global_load_dwordx4 v[36:39], v[24:25], off offset:384
	s_waitcnt lgkmcnt(10)
	v_mfma_f32_16x16x32_bf16 v[120:123], v[202:205], v[160:163], v[120:123]
	v_mfma_f32_16x16x32_bf16 v[104:107], v[206:209], v[160:163], v[104:107]
	v_mfma_f32_16x16x32_bf16 v[88:91], v[210:213], v[160:163], v[88:91]
	v_mfma_f32_16x16x32_bf16 v[72:75], v[214:217], v[160:163], v[72:75]
	global_load_dwordx4 v[44:47], v[26:27], off offset:384
	s_nop 0
	global_load_dwordx4 v[60:63], v[40:41], off offset:384
	s_waitcnt lgkmcnt(9)
	v_mfma_f32_16x16x32_bf16 v[116:119], v[202:205], v[164:167], v[116:119]
	v_mfma_f32_16x16x32_bf16 v[100:103], v[206:209], v[164:167], v[100:103]
	v_mfma_f32_16x16x32_bf16 v[84:87], v[210:213], v[164:167], v[84:87]
	v_mfma_f32_16x16x32_bf16 v[68:71], v[214:217], v[164:167], v[68:71]
	global_load_dwordx4 v[12:15], v[12:13], off offset:384
	s_nop 0
	global_load_dwordx4 v[24:27], v[42:43], off offset:384
	s_waitcnt lgkmcnt(8)
	v_mfma_f32_16x16x32_bf16 v[108:111], v[202:205], v[198:201], v[108:111]
	v_mfma_f32_16x16x32_bf16 v[92:95], v[206:209], v[198:201], v[92:95]
	v_mfma_f32_16x16x32_bf16 v[76:79], v[210:213], v[198:201], v[76:79]
	v_mfma_f32_16x16x32_bf16 v[64:67], v[214:217], v[198:201], v[64:67]
	global_load_dwordx4 v[40:43], v[56:57], off offset:384
	s_nop 0
	global_load_dwordx4 v[56:59], v[58:59], off offset:384
	s_waitcnt lgkmcnt(3)
	v_mfma_f32_16x16x32_bf16 v[124:127], v[234:237], v[218:221], v[124:127]
	v_mfma_f32_16x16x32_bf16 v[120:123], v[234:237], v[222:225], v[120:123]
	v_mfma_f32_16x16x32_bf16 v[116:119], v[234:237], v[226:229], v[116:119]
	v_mfma_f32_16x16x32_bf16 v[108:111], v[234:237], v[230:233], v[108:111]
	s_waitcnt vmcnt(14)
	ds_write_b128 v150, v[20:23] offset:16384
	ds_write_b128 v150, v[0:3] offset:20480
	s_waitcnt lgkmcnt(4)
	v_mfma_f32_16x16x32_bf16 v[112:115], v[238:241], v[218:221], v[112:115]
	v_mfma_f32_16x16x32_bf16 v[104:107], v[238:241], v[222:225], v[104:107]
	v_mfma_f32_16x16x32_bf16 v[100:103], v[238:241], v[226:229], v[100:103]
	v_mfma_f32_16x16x32_bf16 v[92:95], v[238:241], v[230:233], v[92:95]
	s_waitcnt vmcnt(12)
	ds_write_b128 v150, v[4:7] offset:24576
	ds_write_b128 v150, v[52:55] offset:28672
	s_waitcnt lgkmcnt(5)
	v_mfma_f32_16x16x32_bf16 v[96:99], v[242:245], v[218:221], v[96:99]
	v_mfma_f32_16x16x32_bf16 v[88:91], v[242:245], v[222:225], v[88:91]
	v_mfma_f32_16x16x32_bf16 v[84:87], v[242:245], v[226:229], v[84:87]
	v_mfma_f32_16x16x32_bf16 v[76:79], v[242:245], v[230:233], v[76:79]
	s_waitcnt vmcnt(10)
	ds_write_b128 v150, v[8:11]
	ds_write_b128 v150, v[16:19] offset:4096
	s_waitcnt lgkmcnt(6)
	v_mfma_f32_16x16x32_bf16 v[80:83], v[156:159], v[218:221], v[80:83]
	v_mfma_f32_16x16x32_bf16 v[72:75], v[156:159], v[222:225], v[72:75]
	v_mfma_f32_16x16x32_bf16 v[68:71], v[156:159], v[226:229], v[68:71]
	v_mfma_f32_16x16x32_bf16 v[64:67], v[156:159], v[230:233], v[64:67]
	s_waitcnt vmcnt(8)
	ds_write_b128 v150, v[32:35] offset:8192
	ds_write_b128 v150, v[48:51] offset:12288
	s_setprio 0
	s_waitcnt lgkmcnt(0)
	s_barrier
	s_cmpk_lt_u32 s4, 0x300
	s_cbranch_scc1 .LBB0_2230
; #define GLOAD(ra, rb, koff)                                                        \
;   {                                                                                \
;     _Pragma("unroll") for (int j = 0; j < 4; j++) ra[j] = *(const u32x4*)(pa + j * sa32 + (koff));   \
;     _Pragma("unroll") for (int j = 0; j < NB_; j++) rb[j] = *(const u32x4*)(pbv[j] + (koff));         \
;   }
; template <int NT, bool PRE> ...
;     ...
;   if (!PRE) {
;     GLOAD(ra0, rb0, 0);
;     GLOAD(ra1, rb1, 64);
;   }
;   __syncthreads();
;   for (int k0 = 0; k0 < K; k0 += 128) {
;     LSTORE(ra0, rb0, 0);
;     __syncthreads();
;     GLOAD(ra0, rb0, min(k0 + 128, K - 128));
;     __builtin_amdgcn_sched_barrier(0);
;     COMPUTE(0);
;     LSTORE(ra1, rb1, 1);
;     __syncthreads();
;     GLOAD(ra1, rb1, min(k0 + 192, K - 64));
;     __builtin_amdgcn_sched_barrier(0);
;     COMPUTE(1);
;   }
	ds_read_b128 v[156:159], v152
	ds_read_b128 v[202:205], v153 offset:16384
	ds_read_b128 v[206:209], v153 offset:18432
	ds_read_b128 v[210:213], v153 offset:20480
	ds_read_b128 v[214:217], v153 offset:22528
	ds_read_b128 v[160:163], v152 offset:2048
	ds_read_b128 v[164:167], v152 offset:4096
	ds_read_b128 v[198:201], v152 offset:6144
	ds_read_b128 v[218:221], v154
	ds_read_b128 v[222:225], v154 offset:2048
	ds_read_b128 v[226:229], v154 offset:4096
	ds_read_b128 v[230:233], v154 offset:6144
	ds_read_b128 v[234:237], v155 offset:16384
	ds_read_b128 v[238:241], v155 offset:18432
	ds_read_b128 v[242:245], v155 offset:20480
	s_addk_i32 s4, 0x80
	s_setprio 1
	s_waitcnt lgkmcnt(13)
	v_mfma_f32_16x16x32_bf16 v[124:127], v[202:205], v[156:159], v[124:127]
	s_waitcnt lgkmcnt(12)
	v_mfma_f32_16x16x32_bf16 v[112:115], v[206:209], v[156:159], v[112:115]
	s_waitcnt lgkmcnt(11)
	v_mfma_f32_16x16x32_bf16 v[96:99], v[210:213], v[156:159], v[96:99]
	s_waitcnt lgkmcnt(10)
	v_mfma_f32_16x16x32_bf16 v[80:83], v[214:217], v[156:159], v[80:83]
	ds_read_b128 v[156:159], v155 offset:22528
	s_waitcnt lgkmcnt(10)
	v_mfma_f32_16x16x32_bf16 v[120:123], v[202:205], v[160:163], v[120:123]
	v_mfma_f32_16x16x32_bf16 v[104:107], v[206:209], v[160:163], v[104:107]
	v_mfma_f32_16x16x32_bf16 v[88:91], v[210:213], v[160:163], v[88:91]
	v_mfma_f32_16x16x32_bf16 v[72:75], v[214:217], v[160:163], v[72:75]
	s_waitcnt lgkmcnt(9)
	v_mfma_f32_16x16x32_bf16 v[116:119], v[202:205], v[164:167], v[116:119]
	v_mfma_f32_16x16x32_bf16 v[100:103], v[206:209], v[164:167], v[100:103]
	v_mfma_f32_16x16x32_bf16 v[84:87], v[210:213], v[164:167], v[84:87]
	v_mfma_f32_16x16x32_bf16 v[68:71], v[214:217], v[164:167], v[68:71]
	s_waitcnt lgkmcnt(8)
	v_mfma_f32_16x16x32_bf16 v[108:111], v[202:205], v[198:201], v[108:111]
	v_mfma_f32_16x16x32_bf16 v[92:95], v[206:209], v[198:201], v[92:95]
	v_mfma_f32_16x16x32_bf16 v[76:79], v[210:213], v[198:201], v[76:79]
	v_mfma_f32_16x16x32_bf16 v[64:67], v[214:217], v[198:201], v[64:67]
	s_waitcnt lgkmcnt(3)
	v_mfma_f32_16x16x32_bf16 v[124:127], v[234:237], v[218:221], v[124:127]
	v_mfma_f32_16x16x32_bf16 v[120:123], v[234:237], v[222:225], v[120:123]
	v_mfma_f32_16x16x32_bf16 v[116:119], v[234:237], v[226:229], v[116:119]
	v_mfma_f32_16x16x32_bf16 v[108:111], v[234:237], v[230:233], v[108:111]
	s_waitcnt vmcnt(6)
	ds_write_b128 v150, v[28:31] offset:49152
	ds_write_b128 v150, v[36:39] offset:53248
	s_waitcnt lgkmcnt(4)
	v_mfma_f32_16x16x32_bf16 v[112:115], v[238:241], v[218:221], v[112:115]
	v_mfma_f32_16x16x32_bf16 v[104:107], v[238:241], v[222:225], v[104:107]
	v_mfma_f32_16x16x32_bf16 v[100:103], v[238:241], v[226:229], v[100:103]
	v_mfma_f32_16x16x32_bf16 v[92:95], v[238:241], v[230:233], v[92:95]
	s_waitcnt vmcnt(3)
	ds_write_b128 v150, v[44:47] offset:57344
	ds_write_b128 v150, v[12:15] offset:32768
	s_waitcnt lgkmcnt(5)
	v_mfma_f32_16x16x32_bf16 v[96:99], v[242:245], v[218:221], v[96:99]
	v_mfma_f32_16x16x32_bf16 v[88:91], v[242:245], v[222:225], v[88:91]
	v_mfma_f32_16x16x32_bf16 v[84:87], v[242:245], v[226:229], v[84:87]
	v_mfma_f32_16x16x32_bf16 v[76:79], v[242:245], v[230:233], v[76:79]
	s_waitcnt vmcnt(1)
	ds_write_b128 v150, v[24:27] offset:36864
	ds_write_b128 v150, v[40:43] offset:40960
	s_waitcnt lgkmcnt(6)
	v_mfma_f32_16x16x32_bf16 v[80:83], v[156:159], v[218:221], v[80:83]
	v_mfma_f32_16x16x32_bf16 v[72:75], v[156:159], v[222:225], v[72:75]
	v_mfma_f32_16x16x32_bf16 v[68:71], v[156:159], v[226:229], v[68:71]
	v_mfma_f32_16x16x32_bf16 v[64:67], v[156:159], v[230:233], v[64:67]
	s_waitcnt vmcnt(0)
	ds_write_b128 v150, v[56:59] offset:45056
	ds_write_b128 v150, v[60:63] offset:61440
	s_setprio 0
	s_waitcnt lgkmcnt(0)
	s_barrier
; template <int EPI>
; __device__ __forceinline__ void phase_gemm(const Params& P, const u16* A, int lda, const u16* Bt, int K, int N, u16* sA, u16* sB) {
;     ...
;     for (; t < Tfull; t += G) {
;       const int m0 = (t % 132) * 128, n0 = (t / 132) * 128;
;       f32x4 acc[4][4];
;       zero_acc<4>(acc);
;       gemm_core_r<4, true>(pa, (size_t)32 * lda, pbv, K, acc, sA, sB, tq, ra0, rb0, ra1, rb1);
;       if (t + G < Tfull) {
;         PG_PTRS(t + G);
;         gemm_preload<4>(pa, (size_t)32 * lda, pbv, ra0, rb0, ra1, rb1);
	ds_read_b128 v[156:159], v152 offset:32768
	ds_read_b128 v[202:205], v153 offset:49152
	ds_read_b128 v[206:209], v153 offset:51200
	ds_read_b128 v[210:213], v153 offset:53248
	ds_read_b128 v[214:217], v153 offset:55296
	ds_read_b128 v[160:163], v152 offset:34816
	ds_read_b128 v[164:167], v152 offset:36864
	ds_read_b128 v[198:201], v152 offset:38912
	ds_read_b128 v[218:221], v154 offset:32768
	ds_read_b128 v[222:225], v154 offset:34816
	ds_read_b128 v[226:229], v154 offset:36864
	ds_read_b128 v[230:233], v154 offset:38912
	ds_read_b128 v[234:237], v155 offset:49152
	ds_read_b128 v[238:241], v155 offset:51200
	ds_read_b128 v[242:245], v155 offset:53248
	s_setprio 1
	s_waitcnt lgkmcnt(13)
	v_mfma_f32_16x16x32_bf16 v[124:127], v[202:205], v[156:159], v[124:127]
	s_waitcnt lgkmcnt(12)
	v_mfma_f32_16x16x32_bf16 v[112:115], v[206:209], v[156:159], v[112:115]
	s_waitcnt lgkmcnt(11)
	v_mfma_f32_16x16x32_bf16 v[96:99], v[210:213], v[156:159], v[96:99]
	s_waitcnt lgkmcnt(10)
	v_mfma_f32_16x16x32_bf16 v[80:83], v[214:217], v[156:159], v[80:83]
	ds_read_b128 v[156:159], v155 offset:55296
	s_waitcnt lgkmcnt(10)
	v_mfma_f32_16x16x32_bf16 v[120:123], v[202:205], v[160:163], v[120:123]
	v_mfma_f32_16x16x32_bf16 v[104:107], v[206:209], v[160:163], v[104:107]
	v_mfma_f32_16x16x32_bf16 v[88:91], v[210:213], v[160:163], v[88:91]
	v_mfma_f32_16x16x32_bf16 v[72:75], v[214:217], v[160:163], v[72:75]
	s_waitcnt lgkmcnt(9)
	v_mfma_f32_16x16x32_bf16 v[116:119], v[202:205], v[164:167], v[116:119]
	v_mfma_f32_16x16x32_bf16 v[100:103], v[206:209], v[164:167], v[100:103]
	v_mfma_f32_16x16x32_bf16 v[84:87], v[210:213], v[164:167], v[84:87]
	v_mfma_f32_16x16x32_bf16 v[68:71], v[214:217], v[164:167], v[68:71]
	s_waitcnt lgkmcnt(8)
	v_mfma_f32_16x16x32_bf16 v[108:111], v[202:205], v[198:201], v[108:111]
	v_mfma_f32_16x16x32_bf16 v[92:95], v[206:209], v[198:201], v[92:95]
	v_mfma_f32_16x16x32_bf16 v[76:79], v[210:213], v[198:201], v[76:79]
	v_mfma_f32_16x16x32_bf16 v[64:67], v[214:217], v[198:201], v[64:67]
	s_waitcnt lgkmcnt(3)
	v_mfma_f32_16x16x32_bf16 v[124:127], v[234:237], v[218:221], v[124:127]
	v_mfma_f32_16x16x32_bf16 v[120:123], v[234:237], v[222:225], v[120:123]
	v_mfma_f32_16x16x32_bf16 v[116:119], v[234:237], v[226:229], v[116:119]
	v_mfma_f32_16x16x32_bf16 v[108:111], v[234:237], v[230:233], v[108:111]
	s_waitcnt lgkmcnt(2)
	v_mfma_f32_16x16x32_bf16 v[112:115], v[238:241], v[218:221], v[112:115]
	v_mfma_f32_16x16x32_bf16 v[104:107], v[238:241], v[222:225], v[104:107]
	v_mfma_f32_16x16x32_bf16 v[100:103], v[238:241], v[226:229], v[100:103]
	v_mfma_f32_16x16x32_bf16 v[92:95], v[238:241], v[230:233], v[92:95]
	s_waitcnt lgkmcnt(1)
	v_mfma_f32_16x16x32_bf16 v[96:99], v[242:245], v[218:221], v[96:99]
	v_mfma_f32_16x16x32_bf16 v[88:91], v[242:245], v[222:225], v[88:91]
	v_mfma_f32_16x16x32_bf16 v[84:87], v[242:245], v[226:229], v[84:87]
	v_mfma_f32_16x16x32_bf16 v[76:79], v[242:245], v[230:233], v[76:79]
	s_waitcnt lgkmcnt(0)
	v_mfma_f32_16x16x32_bf16 v[80:83], v[156:159], v[218:221], v[80:83]
	v_mfma_f32_16x16x32_bf16 v[72:75], v[156:159], v[222:225], v[72:75]
	v_mfma_f32_16x16x32_bf16 v[68:71], v[156:159], v[226:229], v[68:71]
	v_mfma_f32_16x16x32_bf16 v[64:67], v[156:159], v[230:233], v[64:67]
	s_setprio 0
	s_waitcnt lgkmcnt(0)
	s_add_i32 s7, s6, s90
	s_cmp_ge_i32 s7, s19
	s_cselect_b64 s[4:5], -1, 0
	s_and_b64 vcc, exec, s[4:5]
	s_cbranch_vccnz .LBB0_2228
	s_cmp_lg_u32 s90, 0x200
	s_cbranch_scc1 .Lrm_w1p_orig
	s_and_b32 s54, s7, 7
	s_lshl_b32 s54, s54, 6
	s_bfe_u32 s8, s7, 0x60003
	s_or_b32 s54, s54, s8
	s_andn2_b32 s8, s7, 0x1ff
	s_or_b32 s54, s54, s8
	s_cmp_lt_u32 s54, 3168
	s_cbranch_scc0 .Lrm_w1p_b
	s_lshr_b32 s8, s54, 3
	s_mul_hi_u32 s8, s8, 0x3e0f83e1
	s_lshr_b32 s8, s8, 5
	s_mul_i32 s9, s8, 1056
	s_sub_i32 s54, s54, s9
	s_lshl_b32 s8, s8, 3
	s_and_b32 s9, s54, 7
	s_add_i32 s8, s8, s9
	s_lshr_b32 s9, s54, 3
	s_branch .Lrm_w1p_done

; #define GLOAD(ra, rb, koff)                                                        \
;   {                                                                                \
;     _Pragma("unroll") for (int j = 0; j < 4; j++) ra[j] = *(const u32x4*)(pa + j * sa32 + (koff));   \
;     _Pragma("unroll") for (int j = 0; j < NB_; j++) rb[j] = *(const u32x4*)(pbv[j] + (koff));         \
;   }
; template <int NT, bool PRE> ...
;     ...
;   const int wsw = ((tid & 7) ^ ((tid >> 4) & 7)) * 8;
;   const int rsw = (lane & 15) >> 1;
;     ...
;   if (!PRE) {
;     GLOAD(ra0, rb0, 0);
;     GLOAD(ra1, rb1, 64);
;   }
;   __syncthreads();
;   for (int k0 = 0; k0 < K; k0 += 128) {
;     LSTORE(ra0, rb0, 0);
;     __syncthreads();
;     GLOAD(ra0, rb0, min(k0 + 128, K - 128));
;     __builtin_amdgcn_sched_barrier(0);
;     COMPUTE(0);
;     LSTORE(ra1, rb1, 1);
;     __syncthreads();
;     GLOAD(ra1, rb1, min(k0 + 192, K - 64));
;     __builtin_amdgcn_sched_barrier(0);
;     COMPUTE(1);
.LBB0_2289:
	s_add_i32 s5, s4, 0x100
	s_min_u32 s5, s5, 0xf80
	s_lshl_b32 s54, s5, 1
	ds_read_b128 v[156:159], v152
	ds_read_b128 v[202:205], v153 offset:16384
	ds_read_b128 v[206:209], v153 offset:18432
	ds_read_b128 v[210:213], v153 offset:20480
	ds_read_b128 v[214:217], v153 offset:22528
	ds_read_b128 v[160:163], v152 offset:2048
	ds_read_b128 v[164:167], v152 offset:4096
	ds_read_b128 v[198:201], v152 offset:6144
	ds_read_b128 v[218:221], v154
	ds_read_b128 v[222:225], v154 offset:2048
	ds_read_b128 v[226:229], v154 offset:4096
	ds_read_b128 v[230:233], v154 offset:6144
	ds_read_b128 v[234:237], v155 offset:16384
	ds_read_b128 v[238:241], v155 offset:18432
	ds_read_b128 v[242:245], v155 offset:20480
	v_lshl_add_u64 v[8:9], v[142:143], 0, s[54:55]
	v_add_co_u32_e32 v16, vcc, s19, v8
	v_lshl_add_u64 v[0:1], v[134:135], 0, s[54:55]
	s_nop 0
	v_addc_co_u32_e32 v17, vcc, 0, v9, vcc
	v_add_co_u32_e32 v32, vcc, s20, v8
	v_lshl_add_u64 v[2:3], v[136:137], 0, s[54:55]
	s_nop 0
	v_addc_co_u32_e32 v33, vcc, 0, v9, vcc
	v_add_co_u32_e32 v48, vcc, s21, v8
	v_lshl_add_u64 v[4:5], v[138:139], 0, s[54:55]
	v_lshl_add_u64 v[10:11], v[140:141], 0, s[54:55]
	v_addc_co_u32_e32 v49, vcc, 0, v9, vcc
	s_addk_i32 s4, 0x80
	s_setprio 1
	s_waitcnt lgkmcnt(13)
	v_mfma_f32_16x16x32_bf16 v[124:127], v[202:205], v[156:159], v[124:127]
	s_waitcnt lgkmcnt(12)
	v_mfma_f32_16x16x32_bf16 v[116:119], v[206:209], v[156:159], v[116:119]
	s_waitcnt lgkmcnt(11)
	v_mfma_f32_16x16x32_bf16 v[112:115], v[210:213], v[156:159], v[112:115]
	s_waitcnt lgkmcnt(10)
	v_mfma_f32_16x16x32_bf16 v[108:111], v[214:217], v[156:159], v[108:111]
	ds_read_b128 v[156:159], v155 offset:22528
	global_load_dwordx4 v[20:23], v[0:1], off
	s_nop 0
	global_load_dwordx4 v[0:3], v[2:3], off
	s_waitcnt lgkmcnt(10)
	v_mfma_f32_16x16x32_bf16 v[120:123], v[202:205], v[160:163], v[120:123]
	v_mfma_f32_16x16x32_bf16 v[104:107], v[206:209], v[160:163], v[104:107]
	v_mfma_f32_16x16x32_bf16 v[96:99], v[210:213], v[160:163], v[96:99]
	v_mfma_f32_16x16x32_bf16 v[92:95], v[214:217], v[160:163], v[92:95]
	global_load_dwordx4 v[4:7], v[4:5], off
	s_nop 0
	global_load_dwordx4 v[52:55], v[10:11], off
	s_waitcnt lgkmcnt(9)
	v_mfma_f32_16x16x32_bf16 v[100:103], v[202:205], v[164:167], v[100:103]
	v_mfma_f32_16x16x32_bf16 v[88:91], v[206:209], v[164:167], v[88:91]
	v_mfma_f32_16x16x32_bf16 v[84:87], v[210:213], v[164:167], v[84:87]
	v_mfma_f32_16x16x32_bf16 v[76:79], v[214:217], v[164:167], v[76:79]
	global_load_dwordx4 v[8:11], v[8:9], off
	s_nop 0
	global_load_dwordx4 v[16:19], v[16:17], off
	s_waitcnt lgkmcnt(8)
	v_mfma_f32_16x16x32_bf16 v[80:83], v[202:205], v[198:201], v[80:83]
	v_mfma_f32_16x16x32_bf16 v[72:75], v[206:209], v[198:201], v[72:75]
	v_mfma_f32_16x16x32_bf16 v[68:71], v[210:213], v[198:201], v[68:71]
	v_mfma_f32_16x16x32_bf16 v[64:67], v[214:217], v[198:201], v[64:67]
	global_load_dwordx4 v[32:35], v[32:33], off
	s_nop 0
	global_load_dwordx4 v[48:51], v[48:49], off
	s_waitcnt lgkmcnt(3)
	v_mfma_f32_16x16x32_bf16 v[124:127], v[234:237], v[218:221], v[124:127]
	v_mfma_f32_16x16x32_bf16 v[120:123], v[234:237], v[222:225], v[120:123]
	v_mfma_f32_16x16x32_bf16 v[100:103], v[234:237], v[226:229], v[100:103]
	v_mfma_f32_16x16x32_bf16 v[80:83], v[234:237], v[230:233], v[80:83]
	s_waitcnt vmcnt(14)
	ds_write_b128 v150, v[28:31] offset:49152
	ds_write_b128 v150, v[36:39] offset:53248
	s_waitcnt lgkmcnt(4)
	v_mfma_f32_16x16x32_bf16 v[116:119], v[238:241], v[218:221], v[116:119]
	v_mfma_f32_16x16x32_bf16 v[104:107], v[238:241], v[222:225], v[104:107]
	v_mfma_f32_16x16x32_bf16 v[88:91], v[238:241], v[226:229], v[88:91]
	v_mfma_f32_16x16x32_bf16 v[72:75], v[238:241], v[230:233], v[72:75]
	s_waitcnt vmcnt(11)
	ds_write_b128 v150, v[44:47] offset:57344
	ds_write_b128 v150, v[12:15] offset:32768
	s_waitcnt lgkmcnt(5)
	v_mfma_f32_16x16x32_bf16 v[112:115], v[242:245], v[218:221], v[112:115]
	v_mfma_f32_16x16x32_bf16 v[96:99], v[242:245], v[222:225], v[96:99]
	v_mfma_f32_16x16x32_bf16 v[84:87], v[242:245], v[226:229], v[84:87]
	v_mfma_f32_16x16x32_bf16 v[68:71], v[242:245], v[230:233], v[68:71]
	s_waitcnt vmcnt(9)
	ds_write_b128 v150, v[24:27] offset:36864
	ds_write_b128 v150, v[40:43] offset:40960
	s_waitcnt lgkmcnt(6)
	v_mfma_f32_16x16x32_bf16 v[108:111], v[156:159], v[218:221], v[108:111]
	v_mfma_f32_16x16x32_bf16 v[92:95], v[156:159], v[222:225], v[92:95]
	v_mfma_f32_16x16x32_bf16 v[76:79], v[156:159], v[226:229], v[76:79]
	v_mfma_f32_16x16x32_bf16 v[64:67], v[156:159], v[230:233], v[64:67]
	s_waitcnt vmcnt(8)
	ds_write_b128 v150, v[56:59] offset:45056
	ds_write_b128 v150, v[60:63] offset:61440
	s_setprio 0
	s_waitcnt lgkmcnt(0)
	s_barrier
; #define GLOAD(ra, rb, koff)                                                        \
;   {                                                                                \
;     _Pragma("unroll") for (int j = 0; j < 4; j++) ra[j] = *(const u32x4*)(pa + j * sa32 + (koff));   \
;     _Pragma("unroll") for (int j = 0; j < NB_; j++) rb[j] = *(const u32x4*)(pbv[j] + (koff));         \
;   }
; template <int NT, bool PRE> ...
;     ...
;   const int wsw = ((tid & 7) ^ ((tid >> 4) & 7)) * 8;
;   const int rsw = (lane & 15) >> 1;
;     ...
;   if (!PRE) {
;     GLOAD(ra0, rb0, 0);
;     GLOAD(ra1, rb1, 64);
;   }
;   __syncthreads();
;   for (int k0 = 0; k0 < K; k0 += 128) {
;     LSTORE(ra0, rb0, 0);
;     __syncthreads();
;     GLOAD(ra0, rb0, min(k0 + 128, K - 128));
;     __builtin_amdgcn_sched_barrier(0);
;     COMPUTE(0);
;     LSTORE(ra1, rb1, 1);
;     __syncthreads();
;     GLOAD(ra1, rb1, min(k0 + 192, K - 64));
;     __builtin_amdgcn_sched_barrier(0);
;     COMPUTE(1);
	s_min_u32 s5, s4, 0xf00
	s_lshl_b32 s54, s5, 1
	ds_read_b128 v[156:159], v152 offset:32768
	ds_read_b128 v[202:205], v153 offset:49152
	ds_read_b128 v[206:209], v153 offset:51200
	ds_read_b128 v[210:213], v153 offset:53248
	ds_read_b128 v[214:217], v153 offset:55296
	ds_read_b128 v[160:163], v152 offset:34816
	ds_read_b128 v[164:167], v152 offset:36864
	ds_read_b128 v[198:201], v152 offset:38912
	ds_read_b128 v[218:221], v154 offset:32768
	ds_read_b128 v[222:225], v154 offset:34816
	ds_read_b128 v[226:229], v154 offset:36864
	ds_read_b128 v[230:233], v154 offset:38912
	ds_read_b128 v[234:237], v155 offset:49152
	ds_read_b128 v[238:241], v155 offset:51200
	ds_read_b128 v[242:245], v155 offset:53248
	v_lshl_add_u64 v[12:13], v[142:143], 0, s[54:55]
	v_add_co_u32_e32 v42, vcc, s19, v12
	v_lshl_add_u64 v[14:15], v[134:135], 0, s[54:55]
	s_nop 0
	v_addc_co_u32_e32 v43, vcc, 0, v13, vcc
	v_add_co_u32_e32 v56, vcc, s20, v12
	v_lshl_add_u64 v[24:25], v[136:137], 0, s[54:55]
	s_nop 0
	v_addc_co_u32_e32 v57, vcc, 0, v13, vcc
	v_add_co_u32_e32 v58, vcc, s21, v12
	v_lshl_add_u64 v[26:27], v[138:139], 0, s[54:55]
	v_lshl_add_u64 v[40:41], v[140:141], 0, s[54:55]
	v_addc_co_u32_e32 v59, vcc, 0, v13, vcc
	s_setprio 1
	s_waitcnt lgkmcnt(13)
	v_mfma_f32_16x16x32_bf16 v[124:127], v[202:205], v[156:159], v[124:127]
	s_waitcnt lgkmcnt(12)
	v_mfma_f32_16x16x32_bf16 v[116:119], v[206:209], v[156:159], v[116:119]
	s_waitcnt lgkmcnt(11)
	v_mfma_f32_16x16x32_bf16 v[112:115], v[210:213], v[156:159], v[112:115]
	s_waitcnt lgkmcnt(10)
	v_mfma_f32_16x16x32_bf16 v[108:111], v[214:217], v[156:159], v[108:111]
	ds_read_b128 v[156:159], v155 offset:55296
	global_load_dwordx4 v[28:31], v[14:15], off offset:384
	s_nop 0
	global_load_dwordx4 v[36:39], v[24:25], off offset:384
	s_waitcnt lgkmcnt(10)
	v_mfma_f32_16x16x32_bf16 v[120:123], v[202:205], v[160:163], v[120:123]
	v_mfma_f32_16x16x32_bf16 v[104:107], v[206:209], v[160:163], v[104:107]
	v_mfma_f32_16x16x32_bf16 v[96:99], v[210:213], v[160:163], v[96:99]
	v_mfma_f32_16x16x32_bf16 v[92:95], v[214:217], v[160:163], v[92:95]
	global_load_dwordx4 v[44:47], v[26:27], off offset:384
	s_nop 0
	global_load_dwordx4 v[60:63], v[40:41], off offset:384
	s_waitcnt lgkmcnt(9)
	v_mfma_f32_16x16x32_bf16 v[100:103], v[202:205], v[164:167], v[100:103]
	v_mfma_f32_16x16x32_bf16 v[88:91], v[206:209], v[164:167], v[88:91]
	v_mfma_f32_16x16x32_bf16 v[84:87], v[210:213], v[164:167], v[84:87]
	v_mfma_f32_16x16x32_bf16 v[76:79], v[214:217], v[164:167], v[76:79]
	global_load_dwordx4 v[12:15], v[12:13], off offset:384
	s_nop 0
	global_load_dwordx4 v[24:27], v[42:43], off offset:384
	s_waitcnt lgkmcnt(8)
	v_mfma_f32_16x16x32_bf16 v[80:83], v[202:205], v[198:201], v[80:83]
	v_mfma_f32_16x16x32_bf16 v[72:75], v[206:209], v[198:201], v[72:75]
	v_mfma_f32_16x16x32_bf16 v[68:71], v[210:213], v[198:201], v[68:71]
	v_mfma_f32_16x16x32_bf16 v[64:67], v[214:217], v[198:201], v[64:67]
	global_load_dwordx4 v[40:43], v[56:57], off offset:384
	s_nop 0
	global_load_dwordx4 v[56:59], v[58:59], off offset:384
	s_waitcnt lgkmcnt(3)
	v_mfma_f32_16x16x32_bf16 v[124:127], v[234:237], v[218:221], v[124:127]
	v_mfma_f32_16x16x32_bf16 v[120:123], v[234:237], v[222:225], v[120:123]
	v_mfma_f32_16x16x32_bf16 v[100:103], v[234:237], v[226:229], v[100:103]
	v_mfma_f32_16x16x32_bf16 v[80:83], v[234:237], v[230:233], v[80:83]
	s_waitcnt vmcnt(14)
	ds_write_b128 v150, v[20:23] offset:16384
	ds_write_b128 v150, v[0:3] offset:20480
	s_waitcnt lgkmcnt(4)
	v_mfma_f32_16x16x32_bf16 v[116:119], v[238:241], v[218:221], v[116:119]
	v_mfma_f32_16x16x32_bf16 v[104:107], v[238:241], v[222:225], v[104:107]
	v_mfma_f32_16x16x32_bf16 v[88:91], v[238:241], v[226:229], v[88:91]
	v_mfma_f32_16x16x32_bf16 v[72:75], v[238:241], v[230:233], v[72:75]
	s_waitcnt vmcnt(12)
	ds_write_b128 v150, v[4:7] offset:24576
	ds_write_b128 v150, v[52:55] offset:28672
	s_waitcnt lgkmcnt(5)
	v_mfma_f32_16x16x32_bf16 v[112:115], v[242:245], v[218:221], v[112:115]
	v_mfma_f32_16x16x32_bf16 v[96:99], v[242:245], v[222:225], v[96:99]
	v_mfma_f32_16x16x32_bf16 v[84:87], v[242:245], v[226:229], v[84:87]
	v_mfma_f32_16x16x32_bf16 v[68:71], v[242:245], v[230:233], v[68:71]
	s_waitcnt vmcnt(10)
	ds_write_b128 v150, v[8:11]
	ds_write_b128 v150, v[16:19] offset:4096
	s_waitcnt lgkmcnt(6)
	v_mfma_f32_16x16x32_bf16 v[108:111], v[156:159], v[218:221], v[108:111]
	v_mfma_f32_16x16x32_bf16 v[92:95], v[156:159], v[222:225], v[92:95]
	v_mfma_f32_16x16x32_bf16 v[76:79], v[156:159], v[226:229], v[76:79]
	v_mfma_f32_16x16x32_bf16 v[64:67], v[156:159], v[230:233], v[64:67]
	s_waitcnt vmcnt(8)
	ds_write_b128 v150, v[32:35] offset:8192
	ds_write_b128 v150, v[48:51] offset:12288
	s_setprio 0
	s_waitcnt lgkmcnt(0)
	s_barrier
	s_cmpk_lt_u32 s4, 0xf00
	s_cbranch_scc1 .LBB0_2289
; #define GLOAD(ra, rb, koff)                                                        \
;   {                                                                                \
;     _Pragma("unroll") for (int j = 0; j < 4; j++) ra[j] = *(const u32x4*)(pa + j * sa32 + (koff));   \
;     _Pragma("unroll") for (int j = 0; j < NB_; j++) rb[j] = *(const u32x4*)(pbv[j] + (koff));         \
;   }
; template <int NT, bool PRE> ...
;     ...
;   if (!PRE) {
;     GLOAD(ra0, rb0, 0);
;     GLOAD(ra1, rb1, 64);
;   }
;   __syncthreads();
;   for (int k0 = 0; k0 < K; k0 += 128) {
;     LSTORE(ra0, rb0, 0);
;     __syncthreads();
;     GLOAD(ra0, rb0, min(k0 + 128, K - 128));
;     __builtin_amdgcn_sched_barrier(0);
;     COMPUTE(0);
;     LSTORE(ra1, rb1, 1);
;     __syncthreads();
;     GLOAD(ra1, rb1, min(k0 + 192, K - 64));
;     __builtin_amdgcn_sched_barrier(0);
;     COMPUTE(1);
	ds_read_b128 v[156:159], v152
	ds_read_b128 v[202:205], v153 offset:16384
	ds_read_b128 v[206:209], v153 offset:18432
	ds_read_b128 v[210:213], v153 offset:20480
	ds_read_b128 v[214:217], v153 offset:22528
	ds_read_b128 v[160:163], v152 offset:2048
	ds_read_b128 v[164:167], v152 offset:4096
	ds_read_b128 v[198:201], v152 offset:6144
	ds_read_b128 v[218:221], v154
	ds_read_b128 v[222:225], v154 offset:2048
	ds_read_b128 v[226:229], v154 offset:4096
	ds_read_b128 v[230:233], v154 offset:6144
	ds_read_b128 v[234:237], v155 offset:16384
	ds_read_b128 v[238:241], v155 offset:18432
	ds_read_b128 v[242:245], v155 offset:20480
	s_addk_i32 s4, 0x80
	s_setprio 1
	s_waitcnt lgkmcnt(13)
	v_mfma_f32_16x16x32_bf16 v[124:127], v[202:205], v[156:159], v[124:127]
	s_waitcnt lgkmcnt(12)
	v_mfma_f32_16x16x32_bf16 v[116:119], v[206:209], v[156:159], v[116:119]
	s_waitcnt lgkmcnt(11)
	v_mfma_f32_16x16x32_bf16 v[112:115], v[210:213], v[156:159], v[112:115]
	s_waitcnt lgkmcnt(10)
	v_mfma_f32_16x16x32_bf16 v[108:111], v[214:217], v[156:159], v[108:111]
	ds_read_b128 v[156:159], v155 offset:22528
	s_waitcnt lgkmcnt(10)
	v_mfma_f32_16x16x32_bf16 v[120:123], v[202:205], v[160:163], v[120:123]
	v_mfma_f32_16x16x32_bf16 v[104:107], v[206:209], v[160:163], v[104:107]
	v_mfma_f32_16x16x32_bf16 v[96:99], v[210:213], v[160:163], v[96:99]
	v_mfma_f32_16x16x32_bf16 v[92:95], v[214:217], v[160:163], v[92:95]
	s_waitcnt lgkmcnt(9)
	v_mfma_f32_16x16x32_bf16 v[100:103], v[202:205], v[164:167], v[100:103]
	v_mfma_f32_16x16x32_bf16 v[88:91], v[206:209], v[164:167], v[88:91]
	v_mfma_f32_16x16x32_bf16 v[84:87], v[210:213], v[164:167], v[84:87]
	v_mfma_f32_16x16x32_bf16 v[76:79], v[214:217], v[164:167], v[76:79]
	s_waitcnt lgkmcnt(8)
	v_mfma_f32_16x16x32_bf16 v[80:83], v[202:205], v[198:201], v[80:83]
	v_mfma_f32_16x16x32_bf16 v[72:75], v[206:209], v[198:201], v[72:75]
	v_mfma_f32_16x16x32_bf16 v[68:71], v[210:213], v[198:201], v[68:71]
	v_mfma_f32_16x16x32_bf16 v[64:67], v[214:217], v[198:201], v[64:67]
	s_waitcnt lgkmcnt(3)
	v_mfma_f32_16x16x32_bf16 v[124:127], v[234:237], v[218:221], v[124:127]
	v_mfma_f32_16x16x32_bf16 v[120:123], v[234:237], v[222:225], v[120:123]
	v_mfma_f32_16x16x32_bf16 v[100:103], v[234:237], v[226:229], v[100:103]
	v_mfma_f32_16x16x32_bf16 v[80:83], v[234:237], v[230:233], v[80:83]
	s_waitcnt vmcnt(6)
	ds_write_b128 v150, v[28:31] offset:49152
	ds_write_b128 v150, v[36:39] offset:53248
	s_waitcnt lgkmcnt(4)
	v_mfma_f32_16x16x32_bf16 v[116:119], v[238:241], v[218:221], v[116:119]
	v_mfma_f32_16x16x32_bf16 v[104:107], v[238:241], v[222:225], v[104:107]
	v_mfma_f32_16x16x32_bf16 v[88:91], v[238:241], v[226:229], v[88:91]
	v_mfma_f32_16x16x32_bf16 v[72:75], v[238:241], v[230:233], v[72:75]
	s_waitcnt vmcnt(3)
	ds_write_b128 v150, v[44:47] offset:57344
	ds_write_b128 v150, v[12:15] offset:32768
	s_waitcnt lgkmcnt(5)
	v_mfma_f32_16x16x32_bf16 v[112:115], v[242:245], v[218:221], v[112:115]
	v_mfma_f32_16x16x32_bf16 v[96:99], v[242:245], v[222:225], v[96:99]
	v_mfma_f32_16x16x32_bf16 v[84:87], v[242:245], v[226:229], v[84:87]
	v_mfma_f32_16x16x32_bf16 v[68:71], v[242:245], v[230:233], v[68:71]
	s_waitcnt vmcnt(1)
	ds_write_b128 v150, v[24:27] offset:36864
	ds_write_b128 v150, v[40:43] offset:40960
	s_waitcnt lgkmcnt(6)
	v_mfma_f32_16x16x32_bf16 v[108:111], v[156:159], v[218:221], v[108:111]
	v_mfma_f32_16x16x32_bf16 v[92:95], v[156:159], v[222:225], v[92:95]
	v_mfma_f32_16x16x32_bf16 v[76:79], v[156:159], v[226:229], v[76:79]
	v_mfma_f32_16x16x32_bf16 v[64:67], v[156:159], v[230:233], v[64:67]
	s_waitcnt vmcnt(0)
	ds_write_b128 v150, v[56:59] offset:45056
	ds_write_b128 v150, v[60:63] offset:61440
	s_setprio 0
	s_waitcnt lgkmcnt(0)
	s_barrier
; template <int EPI>
; __device__ __forceinline__ void phase_gemm(const Params& P, const u16* A, int lda, const u16* Bt, int K, int N, u16* sA, u16* sB) {
;     ...
;     for (; t < Tfull; t += G) {
;       const int m0 = (t % 132) * 128, n0 = (t / 132) * 128;
;       f32x4 acc[4][4];
;       zero_acc<4>(acc);
;       gemm_core_r<4, true>(pa, (size_t)32 * lda, pbv, K, acc, sA, sB, tq, ra0, rb0, ra1, rb1);
;       if (t + G < Tfull) {
;         PG_PTRS(t + G);
;         gemm_preload<4>(pa, (size_t)32 * lda, pbv, ra0, rb0, ra1, rb1);
	ds_read_b128 v[156:159], v152 offset:32768
	ds_read_b128 v[202:205], v153 offset:49152
	ds_read_b128 v[206:209], v153 offset:51200
	ds_read_b128 v[210:213], v153 offset:53248
	ds_read_b128 v[214:217], v153 offset:55296
	ds_read_b128 v[160:163], v152 offset:34816
	ds_read_b128 v[164:167], v152 offset:36864
	ds_read_b128 v[198:201], v152 offset:38912
	ds_read_b128 v[218:221], v154 offset:32768
	ds_read_b128 v[222:225], v154 offset:34816
	ds_read_b128 v[226:229], v154 offset:36864
	ds_read_b128 v[230:233], v154 offset:38912
	ds_read_b128 v[234:237], v155 offset:49152
	ds_read_b128 v[238:241], v155 offset:51200
	ds_read_b128 v[242:245], v155 offset:53248
	s_setprio 1
	s_waitcnt lgkmcnt(13)
	v_mfma_f32_16x16x32_bf16 v[124:127], v[202:205], v[156:159], v[124:127]
	s_waitcnt lgkmcnt(12)
	v_mfma_f32_16x16x32_bf16 v[116:119], v[206:209], v[156:159], v[116:119]
	s_waitcnt lgkmcnt(11)
	v_mfma_f32_16x16x32_bf16 v[112:115], v[210:213], v[156:159], v[112:115]
	s_waitcnt lgkmcnt(10)
	v_mfma_f32_16x16x32_bf16 v[108:111], v[214:217], v[156:159], v[108:111]
	ds_read_b128 v[156:159], v155 offset:55296
	s_waitcnt lgkmcnt(10)
	v_mfma_f32_16x16x32_bf16 v[120:123], v[202:205], v[160:163], v[120:123]
	v_mfma_f32_16x16x32_bf16 v[104:107], v[206:209], v[160:163], v[104:107]
	v_mfma_f32_16x16x32_bf16 v[96:99], v[210:213], v[160:163], v[96:99]
	v_mfma_f32_16x16x32_bf16 v[92:95], v[214:217], v[160:163], v[92:95]
	s_waitcnt lgkmcnt(9)
	v_mfma_f32_16x16x32_bf16 v[100:103], v[202:205], v[164:167], v[100:103]
	v_mfma_f32_16x16x32_bf16 v[88:91], v[206:209], v[164:167], v[88:91]
	v_mfma_f32_16x16x32_bf16 v[84:87], v[210:213], v[164:167], v[84:87]
	v_mfma_f32_16x16x32_bf16 v[76:79], v[214:217], v[164:167], v[76:79]
	s_waitcnt lgkmcnt(8)
	v_mfma_f32_16x16x32_bf16 v[80:83], v[202:205], v[198:201], v[80:83]
	v_mfma_f32_16x16x32_bf16 v[72:75], v[206:209], v[198:201], v[72:75]
	v_mfma_f32_16x16x32_bf16 v[68:71], v[210:213], v[198:201], v[68:71]
	v_mfma_f32_16x16x32_bf16 v[64:67], v[214:217], v[198:201], v[64:67]
	s_waitcnt lgkmcnt(3)
	v_mfma_f32_16x16x32_bf16 v[124:127], v[234:237], v[218:221], v[124:127]
	v_mfma_f32_16x16x32_bf16 v[120:123], v[234:237], v[222:225], v[120:123]
	v_mfma_f32_16x16x32_bf16 v[100:103], v[234:237], v[226:229], v[100:103]
	v_mfma_f32_16x16x32_bf16 v[80:83], v[234:237], v[230:233], v[80:83]
	s_waitcnt lgkmcnt(2)
	v_mfma_f32_16x16x32_bf16 v[116:119], v[238:241], v[218:221], v[116:119]
	v_mfma_f32_16x16x32_bf16 v[104:107], v[238:241], v[222:225], v[104:107]
	v_mfma_f32_16x16x32_bf16 v[88:91], v[238:241], v[226:229], v[88:91]
	v_mfma_f32_16x16x32_bf16 v[72:75], v[238:241], v[230:233], v[72:75]
	s_waitcnt lgkmcnt(1)
	v_mfma_f32_16x16x32_bf16 v[112:115], v[242:245], v[218:221], v[112:115]
	v_mfma_f32_16x16x32_bf16 v[96:99], v[242:245], v[222:225], v[96:99]
	v_mfma_f32_16x16x32_bf16 v[84:87], v[242:245], v[226:229], v[84:87]
	v_mfma_f32_16x16x32_bf16 v[68:71], v[242:245], v[230:233], v[68:71]
	s_waitcnt lgkmcnt(0)
	v_mfma_f32_16x16x32_bf16 v[108:111], v[156:159], v[218:221], v[108:111]
	v_mfma_f32_16x16x32_bf16 v[92:95], v[156:159], v[222:225], v[92:95]
	v_mfma_f32_16x16x32_bf16 v[76:79], v[156:159], v[226:229], v[76:79]
	v_mfma_f32_16x16x32_bf16 v[64:67], v[156:159], v[230:233], v[64:67]
	s_setprio 0
	s_waitcnt lgkmcnt(0)
	s_add_i32 s7, s6, s90
	s_cmp_ge_i32 s7, s18
	s_cselect_b64 s[4:5], -1, 0
	s_and_b64 vcc, exec, s[4:5]
	s_cbranch_vccnz .LBB0_2287
	s_cmp_lg_u32 s90, 0x200
	s_cbranch_scc1 .Lrm_w2p_orig
	s_and_b32 s54, s7, 7
	s_lshl_b32 s54, s54, 6
	s_bfe_u32 s8, s7, 0x60003
	s_or_b32 s54, s54, s8
	s_andn2_b32 s8, s7, 0x1ff
	s_or_b32 s54, s54, s8
	s_cmp_lt_u32 s54, 0
	s_cbranch_scc0 .Lrm_w2p_b
	s_lshr_b32 s8, s54, 3
	s_mul_hi_u32 s8, s8, 0x3e0f83e1
	s_lshr_b32 s8, s8, 5
	s_mul_i32 s9, s8, 1056
	s_sub_i32 s54, s54, s9
	s_lshl_b32 s8, s8, 3
	s_and_b32 s9, s54, 7
	s_add_i32 s8, s8, s9
	s_lshr_b32 s9, s54, 3
	s_branch .Lrm_w2p_done
